# GEMM K-loops: LDS-DMA addresses via SGPR base + 32-bit VGPR offset (saddr form), removing per-DMA 64-bit VALU adds in load segments
# speedup vs baseline: 1.0120x; 1.0063x over previous
.LBB0_170:
	ds_read_b128 v[148:151], v165
	ds_read_b128 v[152:155], v165 offset:1024
	ds_read_b128 v[156:159], v165 offset:2048
	ds_read_b128 v[160:163], v165 offset:3072
	ds_read_b128 v[170:173], v166
	ds_read_b128 v[174:177], v166 offset:1024
	ds_read_b128 v[178:181], v166 offset:2048
	ds_read_b128 v[182:185], v166 offset:3072
	s_add_u32 s28, s52, 0xfffc0080
	s_addc_u32 s29, s53, -1
	s_cmp_eq_u32 s73, 12
	s_cselect_b32 s31, s15, s29
	s_cselect_b32 s30, s69, s28
	s_cselect_b32 s29, s13, s72
	s_cselect_b32 s28, s70, s71
	s_add_i32 m0, s21, 0xc000
	ds_read_b128 v[186:189], v167
	ds_read_b128 v[190:193], v167 offset:1024
	ds_read_b128 v[194:197], v167 offset:2048
	ds_read_b128 v[198:201], v167 offset:3072
	ds_read_b128 v[202:205], v167 offset:4096
	ds_read_b128 v[206:209], v167 offset:5120
	ds_read_b128 v[210:213], v167 offset:6144
	ds_read_b128 v[214:217], v167 offset:7168
	global_load_lds_dwordx4 v140, s[52:53]
	s_add_i32 m0, s21, 0xe000
	s_nop 0
	global_load_lds_dwordx4 v142, s[52:53]
	s_waitcnt vmcnt(8)
	s_waitcnt lgkmcnt(0)
	s_barrier
	s_setprio 1
	s_waitcnt lgkmcnt(0)
	v_mfma_f32_16x16x32_bf16 v[126:129], v[148:151], v[186:189], v[126:129]
	v_mfma_f32_16x16x32_bf16 v[118:121], v[156:159], v[186:189], v[118:121]
	v_mfma_f32_16x16x32_bf16 v[110:113], v[148:151], v[194:197], v[110:113]
	v_mfma_f32_16x16x32_bf16 v[102:105], v[156:159], v[194:197], v[102:105]
	v_mfma_f32_16x16x32_bf16 v[94:97], v[148:151], v[202:205], v[94:97]
	v_mfma_f32_16x16x32_bf16 v[86:89], v[156:159], v[202:205], v[86:89]
	v_mfma_f32_16x16x32_bf16 v[78:81], v[148:151], v[210:213], v[78:81]
	v_mfma_f32_16x16x32_bf16 v[70:73], v[156:159], v[210:213], v[70:73]
	v_mfma_f32_16x16x32_bf16 v[126:129], v[152:155], v[190:193], v[126:129]
	v_mfma_f32_16x16x32_bf16 v[118:121], v[160:163], v[190:193], v[118:121]
	v_mfma_f32_16x16x32_bf16 v[110:113], v[152:155], v[198:201], v[110:113]
	v_mfma_f32_16x16x32_bf16 v[102:105], v[160:163], v[198:201], v[102:105]
	v_mfma_f32_16x16x32_bf16 v[94:97], v[152:155], v[206:209], v[94:97]
	v_mfma_f32_16x16x32_bf16 v[86:89], v[160:163], v[206:209], v[86:89]
	v_mfma_f32_16x16x32_bf16 v[78:81], v[152:155], v[214:217], v[78:81]
	v_mfma_f32_16x16x32_bf16 v[70:73], v[160:163], v[214:217], v[70:73]
	s_setprio 0
	s_setprio 1
	v_mfma_f32_16x16x32_bf16 v[122:125], v[170:173], v[186:189], v[122:125]
	v_mfma_f32_16x16x32_bf16 v[114:117], v[178:181], v[186:189], v[114:117]
	v_mfma_f32_16x16x32_bf16 v[106:109], v[170:173], v[194:197], v[106:109]
	v_mfma_f32_16x16x32_bf16 v[98:101], v[178:181], v[194:197], v[98:101]
	v_mfma_f32_16x16x32_bf16 v[90:93], v[170:173], v[202:205], v[90:93]
	v_mfma_f32_16x16x32_bf16 v[82:85], v[178:181], v[202:205], v[82:85]
	v_mfma_f32_16x16x32_bf16 v[74:77], v[170:173], v[210:213], v[74:77]
	v_mfma_f32_16x16x32_bf16 v[66:69], v[178:181], v[210:213], v[66:69]
	v_mfma_f32_16x16x32_bf16 v[122:125], v[174:177], v[190:193], v[122:125]
	v_mfma_f32_16x16x32_bf16 v[114:117], v[182:185], v[190:193], v[114:117]
	v_mfma_f32_16x16x32_bf16 v[106:109], v[174:177], v[198:201], v[106:109]
	v_mfma_f32_16x16x32_bf16 v[98:101], v[182:185], v[198:201], v[98:101]
	v_mfma_f32_16x16x32_bf16 v[90:93], v[174:177], v[206:209], v[90:93]
	v_mfma_f32_16x16x32_bf16 v[82:85], v[182:185], v[206:209], v[82:85]
	v_mfma_f32_16x16x32_bf16 v[74:77], v[174:177], v[214:217], v[74:77]
	v_mfma_f32_16x16x32_bf16 v[66:69], v[182:185], v[214:217], v[66:69]
	s_setprio 0
	s_barrier
	s_add_i32 s74, s59, s24
	s_mov_b32 m0, s74
	ds_read_b128 v[186:189], v167 offset:16384
	ds_read_b128 v[190:193], v167 offset:17408
	ds_read_b128 v[194:197], v167 offset:18432
	ds_read_b128 v[198:201], v167 offset:19456
	ds_read_b128 v[202:205], v167 offset:20480
	ds_read_b128 v[206:209], v167 offset:21504
	ds_read_b128 v[210:213], v167 offset:22528
	ds_read_b128 v[214:217], v167 offset:23552
	global_load_lds_dwordx4 v134, s[28:29]
	s_add_i32 m0, s74, 0x2000
	s_add_u32 s74, s28, 0x40000
	s_addc_u32 s75, s29, 0
	s_add_i32 s76, s66, s24
	global_load_lds_dwordx4 v130, s[28:29]
	s_mov_b32 m0, s76
	s_nop 0
	global_load_lds_dwordx4 v134, s[74:75]
	s_add_i32 m0, s76, 0x2000
	s_nop 0
	global_load_lds_dwordx4 v130, s[74:75]
	s_mov_b32 m0, s21
	s_nop 0
	global_load_lds_dwordx4 v136, s[30:31]
	s_mov_b32 m0, s34
	s_nop 0
	global_load_lds_dwordx4 v132, s[30:31]
	s_waitcnt vmcnt(8)
	s_waitcnt lgkmcnt(0)
	s_barrier
	s_setprio 1
	s_waitcnt lgkmcnt(0)
	v_mfma_f32_16x16x32_bf16 v[62:65], v[148:151], v[186:189], v[62:65]
	v_mfma_f32_16x16x32_bf16 v[54:57], v[156:159], v[186:189], v[54:57]
	v_mfma_f32_16x16x32_bf16 v[46:49], v[148:151], v[194:197], v[46:49]
	v_mfma_f32_16x16x32_bf16 v[38:41], v[156:159], v[194:197], v[38:41]
	v_mfma_f32_16x16x32_bf16 v[30:33], v[148:151], v[202:205], v[30:33]
	v_mfma_f32_16x16x32_bf16 v[22:25], v[156:159], v[202:205], v[22:25]
	v_mfma_f32_16x16x32_bf16 v[14:17], v[148:151], v[210:213], v[14:17]
	v_mfma_f32_16x16x32_bf16 v[6:9], v[156:159], v[210:213], v[6:9]
	v_mfma_f32_16x16x32_bf16 v[62:65], v[152:155], v[190:193], v[62:65]
	v_mfma_f32_16x16x32_bf16 v[54:57], v[160:163], v[190:193], v[54:57]
	v_mfma_f32_16x16x32_bf16 v[46:49], v[152:155], v[198:201], v[46:49]
	v_mfma_f32_16x16x32_bf16 v[38:41], v[160:163], v[198:201], v[38:41]
	v_mfma_f32_16x16x32_bf16 v[30:33], v[152:155], v[206:209], v[30:33]
	v_mfma_f32_16x16x32_bf16 v[22:25], v[160:163], v[206:209], v[22:25]
	v_mfma_f32_16x16x32_bf16 v[14:17], v[152:155], v[214:217], v[14:17]
	v_mfma_f32_16x16x32_bf16 v[6:9], v[160:163], v[214:217], v[6:9]
	s_setprio 0
	s_setprio 1
	v_mfma_f32_16x16x32_bf16 v[58:61], v[170:173], v[186:189], v[58:61]
	v_mfma_f32_16x16x32_bf16 v[50:53], v[178:181], v[186:189], v[50:53]
	v_mfma_f32_16x16x32_bf16 v[42:45], v[170:173], v[194:197], v[42:45]
	v_mfma_f32_16x16x32_bf16 v[34:37], v[178:181], v[194:197], v[34:37]
	v_mfma_f32_16x16x32_bf16 v[26:29], v[170:173], v[202:205], v[26:29]
	v_mfma_f32_16x16x32_bf16 v[18:21], v[178:181], v[202:205], v[18:21]
	v_mfma_f32_16x16x32_bf16 v[10:13], v[170:173], v[210:213], v[10:13]
	v_mfma_f32_16x16x32_bf16 v[2:5], v[178:181], v[210:213], v[2:5]
	v_mfma_f32_16x16x32_bf16 v[58:61], v[174:177], v[190:193], v[58:61]
	v_mfma_f32_16x16x32_bf16 v[50:53], v[182:185], v[190:193], v[50:53]
	v_mfma_f32_16x16x32_bf16 v[42:45], v[174:177], v[198:201], v[42:45]
	v_mfma_f32_16x16x32_bf16 v[34:37], v[182:185], v[198:201], v[34:37]
	v_mfma_f32_16x16x32_bf16 v[26:29], v[174:177], v[206:209], v[26:29]
	v_mfma_f32_16x16x32_bf16 v[18:21], v[182:185], v[206:209], v[18:21]
	v_mfma_f32_16x16x32_bf16 v[10:13], v[174:177], v[214:217], v[10:13]
	v_mfma_f32_16x16x32_bf16 v[2:5], v[182:185], v[214:217], v[2:5]
	s_setprio 0
	s_barrier
	s_add_i32 s74, 0, 0x18000
	s_add_i32 s75, 0, 0x1c000
	v_add_u32_e32 v160, s74, v139
	v_add_u32_e32 v169, s75, v139
	ds_read_b128 v[148:151], v160
	ds_read_b128 v[152:155], v160 offset:1024
	ds_read_b128 v[156:159], v160 offset:2048
	ds_read_b128 v[160:163], v160 offset:3072
	ds_read_b128 v[170:173], v169
	ds_read_b128 v[174:177], v169 offset:1024
	ds_read_b128 v[178:181], v169 offset:2048
	ds_read_b128 v[182:185], v169 offset:3072
	s_add_u32 s98, s30, 0x40000
	s_addc_u32 s99, s31, 0
	s_mov_b32 m0, s35
	ds_read_b128 v[186:189], v167 offset:32768
	ds_read_b128 v[190:193], v167 offset:33792
	ds_read_b128 v[194:197], v167 offset:34816
	ds_read_b128 v[198:201], v167 offset:35840
	ds_read_b128 v[202:205], v167 offset:36864
	ds_read_b128 v[206:209], v167 offset:37888
	ds_read_b128 v[210:213], v167 offset:38912
	ds_read_b128 v[214:217], v167 offset:39936
	global_load_lds_dwordx4 v136, s[98:99]
	s_mov_b32 m0, s54
	s_nop 0
	global_load_lds_dwordx4 v132, s[98:99]
	s_waitcnt vmcnt(8)
	s_waitcnt lgkmcnt(0)
	s_barrier
	s_setprio 1
	s_waitcnt lgkmcnt(0)
	v_mfma_f32_16x16x32_bf16 v[126:129], v[148:151], v[186:189], v[126:129]
	v_mfma_f32_16x16x32_bf16 v[118:121], v[156:159], v[186:189], v[118:121]
	v_mfma_f32_16x16x32_bf16 v[110:113], v[148:151], v[194:197], v[110:113]
	v_mfma_f32_16x16x32_bf16 v[102:105], v[156:159], v[194:197], v[102:105]
	v_mfma_f32_16x16x32_bf16 v[94:97], v[148:151], v[202:205], v[94:97]
	v_mfma_f32_16x16x32_bf16 v[86:89], v[156:159], v[202:205], v[86:89]
	v_mfma_f32_16x16x32_bf16 v[78:81], v[148:151], v[210:213], v[78:81]
	v_mfma_f32_16x16x32_bf16 v[70:73], v[156:159], v[210:213], v[70:73]
	v_mfma_f32_16x16x32_bf16 v[126:129], v[152:155], v[190:193], v[126:129]
	v_mfma_f32_16x16x32_bf16 v[118:121], v[160:163], v[190:193], v[118:121]
	v_mfma_f32_16x16x32_bf16 v[110:113], v[152:155], v[198:201], v[110:113]
	v_mfma_f32_16x16x32_bf16 v[102:105], v[160:163], v[198:201], v[102:105]
	v_mfma_f32_16x16x32_bf16 v[94:97], v[152:155], v[206:209], v[94:97]
	v_mfma_f32_16x16x32_bf16 v[86:89], v[160:163], v[206:209], v[86:89]
	v_mfma_f32_16x16x32_bf16 v[78:81], v[152:155], v[214:217], v[78:81]
	v_mfma_f32_16x16x32_bf16 v[70:73], v[160:163], v[214:217], v[70:73]
	s_setprio 0
	s_setprio 1
	v_mfma_f32_16x16x32_bf16 v[122:125], v[170:173], v[186:189], v[122:125]
	v_mfma_f32_16x16x32_bf16 v[114:117], v[178:181], v[186:189], v[114:117]
	v_mfma_f32_16x16x32_bf16 v[106:109], v[170:173], v[194:197], v[106:109]
	v_mfma_f32_16x16x32_bf16 v[98:101], v[178:181], v[194:197], v[98:101]
	v_mfma_f32_16x16x32_bf16 v[90:93], v[170:173], v[202:205], v[90:93]
	v_mfma_f32_16x16x32_bf16 v[82:85], v[178:181], v[202:205], v[82:85]
	v_mfma_f32_16x16x32_bf16 v[74:77], v[170:173], v[210:213], v[74:77]
	v_mfma_f32_16x16x32_bf16 v[66:69], v[178:181], v[210:213], v[66:69]
	v_mfma_f32_16x16x32_bf16 v[122:125], v[174:177], v[190:193], v[122:125]
	v_mfma_f32_16x16x32_bf16 v[114:117], v[182:185], v[190:193], v[114:117]
	v_mfma_f32_16x16x32_bf16 v[106:109], v[174:177], v[198:201], v[106:109]
	v_mfma_f32_16x16x32_bf16 v[98:101], v[182:185], v[198:201], v[98:101]
	v_mfma_f32_16x16x32_bf16 v[90:93], v[174:177], v[206:209], v[90:93]
	v_mfma_f32_16x16x32_bf16 v[82:85], v[182:185], v[206:209], v[82:85]
	v_mfma_f32_16x16x32_bf16 v[74:77], v[174:177], v[214:217], v[74:77]
	v_mfma_f32_16x16x32_bf16 v[66:69], v[182:185], v[214:217], v[66:69]
	s_setprio 0
	s_barrier
	s_add_i32 s98, s74, s24
	s_add_i32 m0, s98, 0xffffff80
	ds_read_b128 v[186:189], v167 offset:49152
	ds_read_b128 v[190:193], v167 offset:50176
	ds_read_b128 v[194:197], v167 offset:51200
	ds_read_b128 v[198:201], v167 offset:52224
	ds_read_b128 v[202:205], v167 offset:53248
	ds_read_b128 v[206:209], v167 offset:54272
	ds_read_b128 v[210:213], v167 offset:55296
	ds_read_b128 v[214:217], v167 offset:56320
	global_load_lds_dwordx4 v134, s[28:29] offset:128
	s_add_i32 m0, s98, 0x1f80
	s_add_i32 s98, s75, s24
	global_load_lds_dwordx4 v130, s[28:29] offset:128
	s_add_u32 s28, s28, 0x40080
	s_addc_u32 s29, s29, 0
	s_mov_b32 m0, s98
	s_nop 0
	global_load_lds_dwordx4 v134, s[28:29]
	s_add_i32 m0, s98, 0x2000
	s_nop 0
	global_load_lds_dwordx4 v130, s[28:29]
	s_add_i32 m0, s56, 0xffffff80
	s_nop 0
	global_load_lds_dwordx4 v136, s[30:31] offset:128
	s_add_i32 m0, s57, 0xffffff80
	s_nop 0
	global_load_lds_dwordx4 v132, s[30:31] offset:128
	s_waitcnt vmcnt(8)
	s_waitcnt lgkmcnt(0)
	s_barrier
	s_setprio 1
	s_waitcnt lgkmcnt(0)
	v_mfma_f32_16x16x32_bf16 v[62:65], v[148:151], v[186:189], v[62:65]
	v_mfma_f32_16x16x32_bf16 v[54:57], v[156:159], v[186:189], v[54:57]
	v_mfma_f32_16x16x32_bf16 v[46:49], v[148:151], v[194:197], v[46:49]
	v_mfma_f32_16x16x32_bf16 v[38:41], v[156:159], v[194:197], v[38:41]
	v_mfma_f32_16x16x32_bf16 v[30:33], v[148:151], v[202:205], v[30:33]
	v_mfma_f32_16x16x32_bf16 v[22:25], v[156:159], v[202:205], v[22:25]
	v_mfma_f32_16x16x32_bf16 v[14:17], v[148:151], v[210:213], v[14:17]
	v_mfma_f32_16x16x32_bf16 v[6:9], v[156:159], v[210:213], v[6:9]
	v_mfma_f32_16x16x32_bf16 v[62:65], v[152:155], v[190:193], v[62:65]
	v_mfma_f32_16x16x32_bf16 v[54:57], v[160:163], v[190:193], v[54:57]
	v_mfma_f32_16x16x32_bf16 v[46:49], v[152:155], v[198:201], v[46:49]
	v_mfma_f32_16x16x32_bf16 v[38:41], v[160:163], v[198:201], v[38:41]
	v_mfma_f32_16x16x32_bf16 v[30:33], v[152:155], v[206:209], v[30:33]
	v_mfma_f32_16x16x32_bf16 v[22:25], v[160:163], v[206:209], v[22:25]
	v_mfma_f32_16x16x32_bf16 v[14:17], v[152:155], v[214:217], v[14:17]
	v_mfma_f32_16x16x32_bf16 v[6:9], v[160:163], v[214:217], v[6:9]
	s_setprio 0
	s_setprio 1
	v_mfma_f32_16x16x32_bf16 v[58:61], v[170:173], v[186:189], v[58:61]
	v_mfma_f32_16x16x32_bf16 v[50:53], v[178:181], v[186:189], v[50:53]
	v_mfma_f32_16x16x32_bf16 v[42:45], v[170:173], v[194:197], v[42:45]
	v_mfma_f32_16x16x32_bf16 v[34:37], v[178:181], v[194:197], v[34:37]
	v_mfma_f32_16x16x32_bf16 v[26:29], v[170:173], v[202:205], v[26:29]
	v_mfma_f32_16x16x32_bf16 v[18:21], v[178:181], v[202:205], v[18:21]
	v_mfma_f32_16x16x32_bf16 v[10:13], v[170:173], v[210:213], v[10:13]
	v_mfma_f32_16x16x32_bf16 v[2:5], v[178:181], v[210:213], v[2:5]
	v_mfma_f32_16x16x32_bf16 v[58:61], v[174:177], v[190:193], v[58:61]
	v_mfma_f32_16x16x32_bf16 v[50:53], v[182:185], v[190:193], v[50:53]
	v_mfma_f32_16x16x32_bf16 v[42:45], v[174:177], v[198:201], v[42:45]
	v_mfma_f32_16x16x32_bf16 v[34:37], v[182:185], v[198:201], v[34:37]
	v_mfma_f32_16x16x32_bf16 v[26:29], v[174:177], v[206:209], v[26:29]
	v_mfma_f32_16x16x32_bf16 v[18:21], v[182:185], v[206:209], v[18:21]
	v_mfma_f32_16x16x32_bf16 v[10:13], v[174:177], v[214:217], v[10:13]
	v_mfma_f32_16x16x32_bf16 v[2:5], v[182:185], v[214:217], v[2:5]
	s_setprio 0
	s_barrier
	s_add_i32 s73, s73, 2
	s_add_u32 s52, s52, 0x100
	s_addc_u32 s53, s53, 0
	s_add_u32 s71, s71, 0x100
	s_addc_u32 s72, s72, 0
	s_cmp_gt_u32 s73, 13
	s_cbranch_scc0 .LBB0_170
	s_and_b64 vcc, exec, s[10:11]
	s_cbranch_vccz .LBB0_173
	s_barrier

.LBB0_730:
	v_add_u32_e32 v155, s58, v153
	ds_read_b128 v[156:159], v155
	ds_read_b128 v[160:163], v155 offset:1024
	ds_read_b128 v[164:167], v155 offset:2048
	ds_read_b128 v[168:171], v155 offset:3072
	v_add_u32_e32 v155, s59, v153
	s_add_u32 s20, s10, s18
	ds_read_b128 v[172:175], v155
	ds_read_b128 v[176:179], v155 offset:1024
	ds_read_b128 v[180:183], v155 offset:2048
	ds_read_b128 v[184:187], v155 offset:3072
	s_addc_u32 s21, s11, s19
	s_add_u32 s20, s20, 0x100
	s_addc_u32 s21, s21, 0
	s_add_u32 s64, s15, s18
	s_addc_u32 s65, s62, s19
	s_cmpk_eq_i32 s18, 0x1500
	s_cselect_b32 s29, s17, s21
	s_cselect_b32 s28, s16, s20
	s_cselect_b32 s21, s1, s65
	s_cselect_b32 s20, s0, s64
	v_lshl_add_u64 v[220:221], v[148:149], 0, s[18:19]
	s_add_i32 m0, s51, 0xc000
	ds_read_b128 v[188:191], v154
	ds_read_b128 v[192:195], v154 offset:1024
	ds_read_b128 v[196:199], v154 offset:2048
	ds_read_b128 v[200:203], v154 offset:3072
	ds_read_b128 v[204:207], v154 offset:4096
	ds_read_b128 v[208:211], v154 offset:5120
	ds_read_b128 v[212:215], v154 offset:6144
	ds_read_b128 v[216:219], v154 offset:7168
	global_load_lds_dwordx4 v[220:221], off
	v_lshl_add_u64 v[220:221], v[150:151], 0, s[18:19]
	s_add_i32 m0, s51, 0xe000
	s_nop 0
	global_load_lds_dwordx4 v[220:221], off
	s_waitcnt vmcnt(8)
	s_waitcnt lgkmcnt(0)
	s_barrier
	s_setprio 1
	s_waitcnt lgkmcnt(0)
	v_mfma_f32_16x16x32_bf16 v[126:129], v[156:159], v[188:191], v[126:129]
	v_mfma_f32_16x16x32_bf16 v[122:125], v[164:167], v[188:191], v[122:125]
	v_mfma_f32_16x16x32_bf16 v[110:113], v[156:159], v[196:199], v[110:113]
	v_mfma_f32_16x16x32_bf16 v[106:109], v[164:167], v[196:199], v[106:109]
	v_mfma_f32_16x16x32_bf16 v[94:97], v[156:159], v[204:207], v[94:97]
	v_mfma_f32_16x16x32_bf16 v[90:93], v[164:167], v[204:207], v[90:93]
	v_mfma_f32_16x16x32_bf16 v[78:81], v[156:159], v[212:215], v[78:81]
	v_mfma_f32_16x16x32_bf16 v[74:77], v[164:167], v[212:215], v[74:77]
	v_mfma_f32_16x16x32_bf16 v[126:129], v[160:163], v[192:195], v[126:129]
	v_mfma_f32_16x16x32_bf16 v[122:125], v[168:171], v[192:195], v[122:125]
	v_mfma_f32_16x16x32_bf16 v[110:113], v[160:163], v[200:203], v[110:113]
	v_mfma_f32_16x16x32_bf16 v[106:109], v[168:171], v[200:203], v[106:109]
	v_mfma_f32_16x16x32_bf16 v[94:97], v[160:163], v[208:211], v[94:97]
	v_mfma_f32_16x16x32_bf16 v[90:93], v[168:171], v[208:211], v[90:93]
	v_mfma_f32_16x16x32_bf16 v[78:81], v[160:163], v[216:219], v[78:81]
	v_mfma_f32_16x16x32_bf16 v[74:77], v[168:171], v[216:219], v[74:77]
	s_setprio 0
	s_setprio 1
	v_mfma_f32_16x16x32_bf16 v[118:121], v[172:175], v[188:191], v[118:121]
	v_mfma_f32_16x16x32_bf16 v[114:117], v[180:183], v[188:191], v[114:117]
	v_mfma_f32_16x16x32_bf16 v[102:105], v[172:175], v[196:199], v[102:105]
	v_mfma_f32_16x16x32_bf16 v[98:101], v[180:183], v[196:199], v[98:101]
	v_mfma_f32_16x16x32_bf16 v[86:89], v[172:175], v[204:207], v[86:89]
	v_mfma_f32_16x16x32_bf16 v[82:85], v[180:183], v[204:207], v[82:85]
	v_mfma_f32_16x16x32_bf16 v[70:73], v[172:175], v[212:215], v[70:73]
	v_mfma_f32_16x16x32_bf16 v[66:69], v[180:183], v[212:215], v[66:69]
	v_mfma_f32_16x16x32_bf16 v[118:121], v[176:179], v[192:195], v[118:121]
	v_mfma_f32_16x16x32_bf16 v[114:117], v[184:187], v[192:195], v[114:117]
	v_mfma_f32_16x16x32_bf16 v[102:105], v[176:179], v[200:203], v[102:105]
	v_mfma_f32_16x16x32_bf16 v[98:101], v[184:187], v[200:203], v[98:101]
	v_mfma_f32_16x16x32_bf16 v[86:89], v[176:179], v[208:211], v[86:89]
	v_mfma_f32_16x16x32_bf16 v[82:85], v[184:187], v[208:211], v[82:85]
	v_mfma_f32_16x16x32_bf16 v[70:73], v[176:179], v[216:219], v[70:73]
	v_mfma_f32_16x16x32_bf16 v[66:69], v[184:187], v[216:219], v[66:69]
	s_setprio 0
	s_barrier
	s_add_i32 s64, s58, s35
	s_mov_b32 m0, s64
	ds_read_b128 v[188:191], v154 offset:16384
	ds_read_b128 v[192:195], v154 offset:17408
	ds_read_b128 v[196:199], v154 offset:18432
	ds_read_b128 v[200:203], v154 offset:19456
	ds_read_b128 v[204:207], v154 offset:20480
	ds_read_b128 v[208:211], v154 offset:21504
	ds_read_b128 v[212:215], v154 offset:22528
	ds_read_b128 v[216:219], v154 offset:23552
	global_load_lds_dwordx4 v132, s[20:21]
	s_add_i32 m0, s64, 0x2000
	s_add_u32 s64, s20, 0xb0000
	s_addc_u32 s65, s21, 0
	s_add_i32 s66, s59, s35
	global_load_lds_dwordx4 v136, s[20:21]
	s_mov_b32 m0, s66
	s_nop 0
	global_load_lds_dwordx4 v132, s[64:65]
	s_add_i32 m0, s66, 0x2000
	s_nop 0
	global_load_lds_dwordx4 v136, s[64:65]
	s_mov_b32 m0, s51
	s_nop 0
	global_load_lds_dwordx4 v130, s[28:29]
	s_mov_b32 m0, s52
	s_nop 0
	global_load_lds_dwordx4 v134, s[28:29]
	s_waitcnt vmcnt(8)
	s_waitcnt lgkmcnt(0)
	s_barrier
	s_setprio 1
	s_waitcnt lgkmcnt(0)
	v_mfma_f32_16x16x32_bf16 v[62:65], v[156:159], v[188:191], v[62:65]
	v_mfma_f32_16x16x32_bf16 v[58:61], v[164:167], v[188:191], v[58:61]
	v_mfma_f32_16x16x32_bf16 v[46:49], v[156:159], v[196:199], v[46:49]
	v_mfma_f32_16x16x32_bf16 v[42:45], v[164:167], v[196:199], v[42:45]
	v_mfma_f32_16x16x32_bf16 v[30:33], v[156:159], v[204:207], v[30:33]
	v_mfma_f32_16x16x32_bf16 v[26:29], v[164:167], v[204:207], v[26:29]
	v_mfma_f32_16x16x32_bf16 v[14:17], v[156:159], v[212:215], v[14:17]
	v_mfma_f32_16x16x32_bf16 v[10:13], v[164:167], v[212:215], v[10:13]
	v_mfma_f32_16x16x32_bf16 v[62:65], v[160:163], v[192:195], v[62:65]
	v_mfma_f32_16x16x32_bf16 v[58:61], v[168:171], v[192:195], v[58:61]
	v_mfma_f32_16x16x32_bf16 v[46:49], v[160:163], v[200:203], v[46:49]
	v_mfma_f32_16x16x32_bf16 v[42:45], v[168:171], v[200:203], v[42:45]
	v_mfma_f32_16x16x32_bf16 v[30:33], v[160:163], v[208:211], v[30:33]
	v_mfma_f32_16x16x32_bf16 v[26:29], v[168:171], v[208:211], v[26:29]
	v_mfma_f32_16x16x32_bf16 v[14:17], v[160:163], v[216:219], v[14:17]
	v_mfma_f32_16x16x32_bf16 v[10:13], v[168:171], v[216:219], v[10:13]
	s_setprio 0
	s_setprio 1
	v_mfma_f32_16x16x32_bf16 v[54:57], v[172:175], v[188:191], v[54:57]
	v_mfma_f32_16x16x32_bf16 v[50:53], v[180:183], v[188:191], v[50:53]
	v_mfma_f32_16x16x32_bf16 v[38:41], v[172:175], v[196:199], v[38:41]
	v_mfma_f32_16x16x32_bf16 v[34:37], v[180:183], v[196:199], v[34:37]
	v_mfma_f32_16x16x32_bf16 v[22:25], v[172:175], v[204:207], v[22:25]
	v_mfma_f32_16x16x32_bf16 v[18:21], v[180:183], v[204:207], v[18:21]
	v_mfma_f32_16x16x32_bf16 v[6:9], v[172:175], v[212:215], v[6:9]
	v_mfma_f32_16x16x32_bf16 v[2:5], v[180:183], v[212:215], v[2:5]
	v_mfma_f32_16x16x32_bf16 v[54:57], v[176:179], v[192:195], v[54:57]
	v_mfma_f32_16x16x32_bf16 v[50:53], v[184:187], v[192:195], v[50:53]
	v_mfma_f32_16x16x32_bf16 v[38:41], v[176:179], v[200:203], v[38:41]
	v_mfma_f32_16x16x32_bf16 v[34:37], v[184:187], v[200:203], v[34:37]
	v_mfma_f32_16x16x32_bf16 v[22:25], v[176:179], v[208:211], v[22:25]
	v_mfma_f32_16x16x32_bf16 v[18:21], v[184:187], v[208:211], v[18:21]
	v_mfma_f32_16x16x32_bf16 v[6:9], v[176:179], v[216:219], v[6:9]
	v_mfma_f32_16x16x32_bf16 v[2:5], v[184:187], v[216:219], v[2:5]
	s_setprio 0
	s_barrier
	s_add_i32 s64, 0, 0x18000
	v_add_u32_e32 v155, s64, v153
	s_add_i32 s65, 0, 0x1c000
	ds_read_b128 v[156:159], v155
	ds_read_b128 v[160:163], v155 offset:1024
	ds_read_b128 v[164:167], v155 offset:2048
	ds_read_b128 v[168:171], v155 offset:3072
	v_add_u32_e32 v155, s65, v153
	ds_read_b128 v[172:175], v155
	ds_read_b128 v[176:179], v155 offset:1024
	ds_read_b128 v[180:183], v155 offset:2048
	ds_read_b128 v[184:187], v155 offset:3072
	s_add_u32 s98, s28, 0xb0000
	s_addc_u32 s99, s29, 0
	s_mov_b32 m0, s53
	ds_read_b128 v[188:191], v154 offset:32768
	ds_read_b128 v[192:195], v154 offset:33792
	ds_read_b128 v[196:199], v154 offset:34816
	ds_read_b128 v[200:203], v154 offset:35840
	ds_read_b128 v[204:207], v154 offset:36864
	ds_read_b128 v[208:211], v154 offset:37888
	ds_read_b128 v[212:215], v154 offset:38912
	ds_read_b128 v[216:219], v154 offset:39936
	global_load_lds_dwordx4 v130, s[98:99]
	s_mov_b32 m0, s54
	s_nop 0
	global_load_lds_dwordx4 v134, s[98:99]
	s_waitcnt vmcnt(8)
	s_waitcnt lgkmcnt(0)
	s_barrier
	s_setprio 1
	s_waitcnt lgkmcnt(0)
	v_mfma_f32_16x16x32_bf16 v[126:129], v[156:159], v[188:191], v[126:129]
	v_mfma_f32_16x16x32_bf16 v[122:125], v[164:167], v[188:191], v[122:125]
	v_mfma_f32_16x16x32_bf16 v[110:113], v[156:159], v[196:199], v[110:113]
	v_mfma_f32_16x16x32_bf16 v[106:109], v[164:167], v[196:199], v[106:109]
	v_mfma_f32_16x16x32_bf16 v[94:97], v[156:159], v[204:207], v[94:97]
	v_mfma_f32_16x16x32_bf16 v[90:93], v[164:167], v[204:207], v[90:93]
	v_mfma_f32_16x16x32_bf16 v[78:81], v[156:159], v[212:215], v[78:81]
	v_mfma_f32_16x16x32_bf16 v[74:77], v[164:167], v[212:215], v[74:77]
	v_mfma_f32_16x16x32_bf16 v[126:129], v[160:163], v[192:195], v[126:129]
	v_mfma_f32_16x16x32_bf16 v[122:125], v[168:171], v[192:195], v[122:125]
	v_mfma_f32_16x16x32_bf16 v[110:113], v[160:163], v[200:203], v[110:113]
	v_mfma_f32_16x16x32_bf16 v[106:109], v[168:171], v[200:203], v[106:109]
	v_mfma_f32_16x16x32_bf16 v[94:97], v[160:163], v[208:211], v[94:97]
	v_mfma_f32_16x16x32_bf16 v[90:93], v[168:171], v[208:211], v[90:93]
	v_mfma_f32_16x16x32_bf16 v[78:81], v[160:163], v[216:219], v[78:81]
	v_mfma_f32_16x16x32_bf16 v[74:77], v[168:171], v[216:219], v[74:77]
	s_setprio 0
	s_setprio 1
	v_mfma_f32_16x16x32_bf16 v[118:121], v[172:175], v[188:191], v[118:121]
	v_mfma_f32_16x16x32_bf16 v[114:117], v[180:183], v[188:191], v[114:117]
	v_mfma_f32_16x16x32_bf16 v[102:105], v[172:175], v[196:199], v[102:105]
	v_mfma_f32_16x16x32_bf16 v[98:101], v[180:183], v[196:199], v[98:101]
	v_mfma_f32_16x16x32_bf16 v[86:89], v[172:175], v[204:207], v[86:89]
	v_mfma_f32_16x16x32_bf16 v[82:85], v[180:183], v[204:207], v[82:85]
	v_mfma_f32_16x16x32_bf16 v[70:73], v[172:175], v[212:215], v[70:73]
	v_mfma_f32_16x16x32_bf16 v[66:69], v[180:183], v[212:215], v[66:69]
	v_mfma_f32_16x16x32_bf16 v[118:121], v[176:179], v[192:195], v[118:121]
	v_mfma_f32_16x16x32_bf16 v[114:117], v[184:187], v[192:195], v[114:117]
	v_mfma_f32_16x16x32_bf16 v[102:105], v[176:179], v[200:203], v[102:105]
	v_mfma_f32_16x16x32_bf16 v[98:101], v[184:187], v[200:203], v[98:101]
	v_mfma_f32_16x16x32_bf16 v[86:89], v[176:179], v[208:211], v[86:89]
	v_mfma_f32_16x16x32_bf16 v[82:85], v[184:187], v[208:211], v[82:85]
	v_mfma_f32_16x16x32_bf16 v[70:73], v[176:179], v[216:219], v[70:73]
	v_mfma_f32_16x16x32_bf16 v[66:69], v[184:187], v[216:219], v[66:69]
	s_setprio 0
	s_barrier
	s_add_i32 s98, s64, s35
	s_add_i32 m0, s98, 0xffffff80
	ds_read_b128 v[188:191], v154 offset:49152
	ds_read_b128 v[192:195], v154 offset:50176
	ds_read_b128 v[196:199], v154 offset:51200
	ds_read_b128 v[200:203], v154 offset:52224
	ds_read_b128 v[204:207], v154 offset:53248
	ds_read_b128 v[208:211], v154 offset:54272
	ds_read_b128 v[212:215], v154 offset:55296
	ds_read_b128 v[216:219], v154 offset:56320
	global_load_lds_dwordx4 v132, s[20:21] offset:128
	s_add_i32 m0, s98, 0x1f80
	s_add_i32 s98, s65, s35
	global_load_lds_dwordx4 v136, s[20:21] offset:128
	s_add_u32 s20, s20, 0xb0080
	s_addc_u32 s21, s21, 0
	s_mov_b32 m0, s98
	s_nop 0
	global_load_lds_dwordx4 v132, s[20:21]
	s_add_i32 m0, s98, 0x2000
	s_nop 0
	global_load_lds_dwordx4 v136, s[20:21]
	s_add_i32 m0, s56, 0xffffff80
	s_nop 0
	global_load_lds_dwordx4 v130, s[28:29] offset:128
	s_add_i32 m0, s57, 0xffffff80
	s_nop 0
	global_load_lds_dwordx4 v134, s[28:29] offset:128
	s_waitcnt vmcnt(8)
	s_waitcnt lgkmcnt(0)
	s_barrier
	s_setprio 1
	s_waitcnt lgkmcnt(0)
	v_mfma_f32_16x16x32_bf16 v[62:65], v[156:159], v[188:191], v[62:65]
	v_mfma_f32_16x16x32_bf16 v[58:61], v[164:167], v[188:191], v[58:61]
	v_mfma_f32_16x16x32_bf16 v[46:49], v[156:159], v[196:199], v[46:49]
	v_mfma_f32_16x16x32_bf16 v[42:45], v[164:167], v[196:199], v[42:45]
	v_mfma_f32_16x16x32_bf16 v[30:33], v[156:159], v[204:207], v[30:33]
	v_mfma_f32_16x16x32_bf16 v[26:29], v[164:167], v[204:207], v[26:29]
	v_mfma_f32_16x16x32_bf16 v[14:17], v[156:159], v[212:215], v[14:17]
	v_mfma_f32_16x16x32_bf16 v[10:13], v[164:167], v[212:215], v[10:13]
	v_mfma_f32_16x16x32_bf16 v[62:65], v[160:163], v[192:195], v[62:65]
	v_mfma_f32_16x16x32_bf16 v[58:61], v[168:171], v[192:195], v[58:61]
	v_mfma_f32_16x16x32_bf16 v[46:49], v[160:163], v[200:203], v[46:49]
	v_mfma_f32_16x16x32_bf16 v[42:45], v[168:171], v[200:203], v[42:45]
	v_mfma_f32_16x16x32_bf16 v[30:33], v[160:163], v[208:211], v[30:33]
	v_mfma_f32_16x16x32_bf16 v[26:29], v[168:171], v[208:211], v[26:29]
	v_mfma_f32_16x16x32_bf16 v[14:17], v[160:163], v[216:219], v[14:17]
	v_mfma_f32_16x16x32_bf16 v[10:13], v[168:171], v[216:219], v[10:13]
	s_setprio 0
	s_setprio 1
	v_mfma_f32_16x16x32_bf16 v[54:57], v[172:175], v[188:191], v[54:57]
	v_mfma_f32_16x16x32_bf16 v[50:53], v[180:183], v[188:191], v[50:53]
	v_mfma_f32_16x16x32_bf16 v[38:41], v[172:175], v[196:199], v[38:41]
	v_mfma_f32_16x16x32_bf16 v[34:37], v[180:183], v[196:199], v[34:37]
	v_mfma_f32_16x16x32_bf16 v[22:25], v[172:175], v[204:207], v[22:25]
	v_mfma_f32_16x16x32_bf16 v[18:21], v[180:183], v[204:207], v[18:21]
	v_mfma_f32_16x16x32_bf16 v[6:9], v[172:175], v[212:215], v[6:9]
	v_mfma_f32_16x16x32_bf16 v[2:5], v[180:183], v[212:215], v[2:5]
	v_mfma_f32_16x16x32_bf16 v[54:57], v[176:179], v[192:195], v[54:57]
	v_mfma_f32_16x16x32_bf16 v[50:53], v[184:187], v[192:195], v[50:53]
	v_mfma_f32_16x16x32_bf16 v[38:41], v[176:179], v[200:203], v[38:41]
	v_mfma_f32_16x16x32_bf16 v[34:37], v[184:187], v[200:203], v[34:37]
	v_mfma_f32_16x16x32_bf16 v[22:25], v[176:179], v[208:211], v[22:25]
	v_mfma_f32_16x16x32_bf16 v[18:21], v[184:187], v[208:211], v[18:21]
	v_mfma_f32_16x16x32_bf16 v[6:9], v[176:179], v[216:219], v[6:9]
	v_mfma_f32_16x16x32_bf16 v[2:5], v[184:187], v[216:219], v[2:5]
	s_setprio 0
	s_barrier
	s_add_i32 s63, s63, 2
	s_add_u32 s18, s18, 0x100
	s_addc_u32 s19, s19, 0
	s_cmp_gt_u32 s63, 41
	s_cbranch_scc0 .LBB0_730
	s_add_u32 s18, s15, 0xffffff00
	s_addc_u32 s19, s62, -1
	s_and_b64 vcc, exec, s[4:5]
	s_cbranch_vccnz .LBB0_733
	v_mov_b32_e32 v2, 0
	s_mov_b32 s8, s60
	s_mov_b32 s50, s61
	s_mov_b64 s[10:11], s[16:17]
	s_mov_b32 s55, s14
	v_mov_b32_e32 v3, v2
	v_mov_b32_e32 v4, v2
	v_mov_b32_e32 v5, v2
	v_mov_b32_e32 v6, v2
	v_mov_b32_e32 v7, v2
	v_mov_b32_e32 v8, v2
	v_mov_b32_e32 v9, v2
	v_mov_b32_e32 v18, v2
	v_mov_b32_e32 v19, v2
	v_mov_b32_e32 v20, v2
	v_mov_b32_e32 v21, v2
	v_mov_b32_e32 v22, v2
	v_mov_b32_e32 v23, v2
	v_mov_b32_e32 v24, v2
	v_mov_b32_e32 v25, v2
	v_mov_b32_e32 v34, v2
	v_mov_b32_e32 v35, v2
	v_mov_b32_e32 v36, v2
	v_mov_b32_e32 v37, v2
	v_mov_b32_e32 v38, v2
	v_mov_b32_e32 v39, v2
	v_mov_b32_e32 v40, v2
	v_mov_b32_e32 v41, v2
	v_mov_b32_e32 v50, v2
	v_mov_b32_e32 v51, v2
	v_mov_b32_e32 v52, v2
	v_mov_b32_e32 v53, v2
	v_mov_b32_e32 v54, v2
	v_mov_b32_e32 v55, v2
	v_mov_b32_e32 v56, v2
	v_mov_b32_e32 v57, v2
	v_mov_b32_e32 v10, v2
	v_mov_b32_e32 v11, v2
	v_mov_b32_e32 v12, v2
	v_mov_b32_e32 v13, v2
	v_mov_b32_e32 v14, v2
	v_mov_b32_e32 v15, v2
	v_mov_b32_e32 v16, v2
	v_mov_b32_e32 v17, v2
	v_mov_b32_e32 v26, v2
	v_mov_b32_e32 v27, v2
	v_mov_b32_e32 v28, v2
	v_mov_b32_e32 v29, v2
	v_mov_b32_e32 v30, v2
	v_mov_b32_e32 v31, v2
	v_mov_b32_e32 v32, v2
	v_mov_b32_e32 v33, v2
	v_mov_b32_e32 v42, v2
	v_mov_b32_e32 v43, v2
	v_mov_b32_e32 v44, v2
	v_mov_b32_e32 v45, v2
	v_mov_b32_e32 v46, v2
	v_mov_b32_e32 v47, v2
	v_mov_b32_e32 v48, v2
	v_mov_b32_e32 v49, v2
	v_mov_b32_e32 v58, v2
	v_mov_b32_e32 v59, v2
	v_mov_b32_e32 v60, v2
	v_mov_b32_e32 v61, v2
	v_mov_b32_e32 v62, v2
	v_mov_b32_e32 v63, v2
	v_mov_b32_e32 v64, v2
	v_mov_b32_e32 v65, v2
	v_mov_b32_e32 v66, v2
	v_mov_b32_e32 v67, v2
	v_mov_b32_e32 v68, v2
	v_mov_b32_e32 v69, v2
	v_mov_b32_e32 v70, v2
	v_mov_b32_e32 v71, v2
	v_mov_b32_e32 v72, v2
	v_mov_b32_e32 v73, v2
	v_mov_b32_e32 v82, v2
	v_mov_b32_e32 v83, v2
	v_mov_b32_e32 v84, v2
	v_mov_b32_e32 v85, v2
	v_mov_b32_e32 v86, v2
	v_mov_b32_e32 v87, v2
	v_mov_b32_e32 v88, v2
	v_mov_b32_e32 v89, v2
	v_mov_b32_e32 v98, v2
	v_mov_b32_e32 v99, v2
	v_mov_b32_e32 v100, v2
	v_mov_b32_e32 v101, v2
	v_mov_b32_e32 v102, v2
	v_mov_b32_e32 v103, v2
	v_mov_b32_e32 v104, v2
	v_mov_b32_e32 v105, v2
	v_mov_b32_e32 v114, v2
	v_mov_b32_e32 v115, v2
	v_mov_b32_e32 v116, v2
	v_mov_b32_e32 v117, v2
	v_mov_b32_e32 v118, v2
	v_mov_b32_e32 v119, v2
	v_mov_b32_e32 v120, v2
	v_mov_b32_e32 v121, v2
	v_mov_b32_e32 v74, v2
	v_mov_b32_e32 v75, v2
	v_mov_b32_e32 v76, v2
	v_mov_b32_e32 v77, v2
	v_mov_b32_e32 v78, v2
	v_mov_b32_e32 v79, v2
	v_mov_b32_e32 v80, v2
	v_mov_b32_e32 v81, v2
	v_mov_b32_e32 v90, v2
	v_mov_b32_e32 v91, v2
	v_mov_b32_e32 v92, v2
	v_mov_b32_e32 v93, v2
	v_mov_b32_e32 v94, v2
	v_mov_b32_e32 v95, v2
	v_mov_b32_e32 v96, v2
	v_mov_b32_e32 v97, v2
	v_mov_b32_e32 v106, v2
	v_mov_b32_e32 v107, v2
	v_mov_b32_e32 v108, v2
	v_mov_b32_e32 v109, v2
	v_mov_b32_e32 v110, v2
	v_mov_b32_e32 v111, v2
	v_mov_b32_e32 v112, v2
	v_mov_b32_e32 v113, v2
	v_mov_b32_e32 v122, v2
	v_mov_b32_e32 v123, v2
	v_mov_b32_e32 v124, v2
	v_mov_b32_e32 v125, v2
	v_mov_b32_e32 v126, v2
	v_mov_b32_e32 v127, v2
	v_mov_b32_e32 v128, v2
	v_mov_b32_e32 v129, v2
	s_branch .LBB0_734

.LBB0_862:
	ds_read_b128 v[154:157], v141
	ds_read_b128 v[158:161], v141 offset:1024
	ds_read_b128 v[162:165], v141 offset:2048
	ds_read_b128 v[166:169], v141 offset:3072
	ds_read_b128 v[170:173], v182
	ds_read_b128 v[174:177], v182 offset:1024
	ds_read_b128 v[178:181], v182 offset:2048
	ds_read_b128 v[186:189], v182 offset:3072
	s_add_u32 s28, s12, 0xfffc0080
	s_addc_u32 s29, s13, -1
	s_cmp_eq_u32 s34, 12
	s_cselect_b32 s31, s9, s29
	s_cselect_b32 s30, s11, s28
	s_cselect_b32 s29, s14, s24
	s_cselect_b32 s28, s22, s23
	s_add_i32 m0, s87, 0xc000
	ds_read_b128 v[190:193], v183
	ds_read_b128 v[194:197], v183 offset:1024
	ds_read_b128 v[198:201], v183 offset:2048
	ds_read_b128 v[202:205], v183 offset:3072
	ds_read_b128 v[206:209], v183 offset:4096
	ds_read_b128 v[210:213], v183 offset:5120
	ds_read_b128 v[214:217], v183 offset:6144
	ds_read_b128 v[218:221], v183 offset:7168
	global_load_lds_dwordx4 v146, s[12:13]
	s_add_i32 m0, s87, 0xe000
	s_nop 0
	global_load_lds_dwordx4 v148, s[12:13]
	s_waitcnt vmcnt(8)
	s_waitcnt lgkmcnt(0)
	s_barrier
	s_setprio 1
	s_waitcnt lgkmcnt(0)
	v_mfma_f32_16x16x32_bf16 v[126:129], v[154:157], v[190:193], v[126:129]
	v_mfma_f32_16x16x32_bf16 v[122:125], v[162:165], v[190:193], v[122:125]
	v_mfma_f32_16x16x32_bf16 v[118:121], v[154:157], v[198:201], v[118:121]
	v_mfma_f32_16x16x32_bf16 v[114:117], v[162:165], v[198:201], v[114:117]
	v_mfma_f32_16x16x32_bf16 v[110:113], v[154:157], v[206:209], v[110:113]
	v_mfma_f32_16x16x32_bf16 v[106:109], v[162:165], v[206:209], v[106:109]
	v_mfma_f32_16x16x32_bf16 v[102:105], v[154:157], v[214:217], v[102:105]
	v_mfma_f32_16x16x32_bf16 v[98:101], v[162:165], v[214:217], v[98:101]
	v_mfma_f32_16x16x32_bf16 v[126:129], v[158:161], v[194:197], v[126:129]
	v_mfma_f32_16x16x32_bf16 v[122:125], v[166:169], v[194:197], v[122:125]
	v_mfma_f32_16x16x32_bf16 v[118:121], v[158:161], v[202:205], v[118:121]
	v_mfma_f32_16x16x32_bf16 v[114:117], v[166:169], v[202:205], v[114:117]
	v_mfma_f32_16x16x32_bf16 v[110:113], v[158:161], v[210:213], v[110:113]
	v_mfma_f32_16x16x32_bf16 v[106:109], v[166:169], v[210:213], v[106:109]
	v_mfma_f32_16x16x32_bf16 v[102:105], v[158:161], v[218:221], v[102:105]
	v_mfma_f32_16x16x32_bf16 v[98:101], v[166:169], v[218:221], v[98:101]
	s_setprio 0
	s_setprio 1
	v_mfma_f32_16x16x32_bf16 v[62:65], v[170:173], v[190:193], v[62:65]
	v_mfma_f32_16x16x32_bf16 v[58:61], v[178:181], v[190:193], v[58:61]
	v_mfma_f32_16x16x32_bf16 v[54:57], v[170:173], v[198:201], v[54:57]
	v_mfma_f32_16x16x32_bf16 v[50:53], v[178:181], v[198:201], v[50:53]
	v_mfma_f32_16x16x32_bf16 v[46:49], v[170:173], v[206:209], v[46:49]
	v_mfma_f32_16x16x32_bf16 v[42:45], v[178:181], v[206:209], v[42:45]
	v_mfma_f32_16x16x32_bf16 v[38:41], v[170:173], v[214:217], v[38:41]
	v_mfma_f32_16x16x32_bf16 v[34:37], v[178:181], v[214:217], v[34:37]
	v_mfma_f32_16x16x32_bf16 v[62:65], v[174:177], v[194:197], v[62:65]
	v_mfma_f32_16x16x32_bf16 v[58:61], v[186:189], v[194:197], v[58:61]
	v_mfma_f32_16x16x32_bf16 v[54:57], v[174:177], v[202:205], v[54:57]
	v_mfma_f32_16x16x32_bf16 v[50:53], v[186:189], v[202:205], v[50:53]
	v_mfma_f32_16x16x32_bf16 v[46:49], v[174:177], v[210:213], v[46:49]
	v_mfma_f32_16x16x32_bf16 v[42:45], v[186:189], v[210:213], v[42:45]
	v_mfma_f32_16x16x32_bf16 v[38:41], v[174:177], v[218:221], v[38:41]
	v_mfma_f32_16x16x32_bf16 v[34:37], v[186:189], v[218:221], v[34:37]
	s_setprio 0
	s_barrier
	s_add_i32 s35, s97, s77
	s_mov_b32 m0, s35
	ds_read_b128 v[190:193], v183 offset:16384
	ds_read_b128 v[194:197], v183 offset:17408
	ds_read_b128 v[198:201], v183 offset:18432
	ds_read_b128 v[202:205], v183 offset:19456
	ds_read_b128 v[206:209], v183 offset:20480
	ds_read_b128 v[210:213], v183 offset:21504
	ds_read_b128 v[214:217], v183 offset:22528
	ds_read_b128 v[218:221], v183 offset:23552
	global_load_lds_dwordx4 v132, s[28:29]
	s_add_i32 m0, s35, 0x2000
	s_add_u32 s68, s28, 0x40000
	s_addc_u32 s69, s29, 0
	s_add_i32 s35, s74, s77
	global_load_lds_dwordx4 v136, s[28:29]
	s_mov_b32 m0, s35
	s_nop 0
	global_load_lds_dwordx4 v132, s[68:69]
	s_add_i32 m0, s35, 0x2000
	s_nop 0
	global_load_lds_dwordx4 v136, s[68:69]
	s_mov_b32 m0, s87
	s_nop 0
	global_load_lds_dwordx4 v130, s[30:31]
	s_mov_b32 m0, s88
	s_nop 0
	global_load_lds_dwordx4 v134, s[30:31]
	s_waitcnt vmcnt(8)
	s_waitcnt lgkmcnt(0)
	s_barrier
	s_setprio 1
	s_waitcnt lgkmcnt(0)
	v_mfma_f32_16x16x32_bf16 v[94:97], v[154:157], v[190:193], v[94:97]
	v_mfma_f32_16x16x32_bf16 v[90:93], v[162:165], v[190:193], v[90:93]
	v_mfma_f32_16x16x32_bf16 v[86:89], v[154:157], v[198:201], v[86:89]
	v_mfma_f32_16x16x32_bf16 v[82:85], v[162:165], v[198:201], v[82:85]
	v_mfma_f32_16x16x32_bf16 v[78:81], v[154:157], v[206:209], v[78:81]
	v_mfma_f32_16x16x32_bf16 v[74:77], v[162:165], v[206:209], v[74:77]
	v_mfma_f32_16x16x32_bf16 v[70:73], v[154:157], v[214:217], v[70:73]
	v_mfma_f32_16x16x32_bf16 v[66:69], v[162:165], v[214:217], v[66:69]
	v_mfma_f32_16x16x32_bf16 v[94:97], v[158:161], v[194:197], v[94:97]
	v_mfma_f32_16x16x32_bf16 v[90:93], v[166:169], v[194:197], v[90:93]
	v_mfma_f32_16x16x32_bf16 v[86:89], v[158:161], v[202:205], v[86:89]
	v_mfma_f32_16x16x32_bf16 v[82:85], v[166:169], v[202:205], v[82:85]
	v_mfma_f32_16x16x32_bf16 v[78:81], v[158:161], v[210:213], v[78:81]
	v_mfma_f32_16x16x32_bf16 v[74:77], v[166:169], v[210:213], v[74:77]
	v_mfma_f32_16x16x32_bf16 v[70:73], v[158:161], v[218:221], v[70:73]
	v_mfma_f32_16x16x32_bf16 v[66:69], v[166:169], v[218:221], v[66:69]
	s_setprio 0
	s_setprio 1
	v_mfma_f32_16x16x32_bf16 v[30:33], v[170:173], v[190:193], v[30:33]
	v_mfma_f32_16x16x32_bf16 v[26:29], v[178:181], v[190:193], v[26:29]
	v_mfma_f32_16x16x32_bf16 v[22:25], v[170:173], v[198:201], v[22:25]
	v_mfma_f32_16x16x32_bf16 v[18:21], v[178:181], v[198:201], v[18:21]
	v_mfma_f32_16x16x32_bf16 v[14:17], v[170:173], v[206:209], v[14:17]
	v_mfma_f32_16x16x32_bf16 v[10:13], v[178:181], v[206:209], v[10:13]
	v_mfma_f32_16x16x32_bf16 v[6:9], v[170:173], v[214:217], v[6:9]
	v_mfma_f32_16x16x32_bf16 v[2:5], v[178:181], v[214:217], v[2:5]
	v_mfma_f32_16x16x32_bf16 v[30:33], v[174:177], v[194:197], v[30:33]
	v_mfma_f32_16x16x32_bf16 v[26:29], v[186:189], v[194:197], v[26:29]
	v_mfma_f32_16x16x32_bf16 v[22:25], v[174:177], v[202:205], v[22:25]
	v_mfma_f32_16x16x32_bf16 v[18:21], v[186:189], v[202:205], v[18:21]
	v_mfma_f32_16x16x32_bf16 v[14:17], v[174:177], v[210:213], v[14:17]
	v_mfma_f32_16x16x32_bf16 v[10:13], v[186:189], v[210:213], v[10:13]
	v_mfma_f32_16x16x32_bf16 v[6:9], v[174:177], v[218:221], v[6:9]
	v_mfma_f32_16x16x32_bf16 v[2:5], v[186:189], v[218:221], v[2:5]
	s_setprio 0
	s_barrier
	s_add_i32 s35, 0, 0x18000
	s_add_i32 s63, 0, 0x1c000
	v_add_u32_e32 v166, s35, v139
	v_add_u32_e32 v185, s63, v139
	ds_read_b128 v[154:157], v166
	ds_read_b128 v[158:161], v166 offset:1024
	ds_read_b128 v[162:165], v166 offset:2048
	ds_read_b128 v[166:169], v166 offset:3072
	ds_read_b128 v[170:173], v185
	ds_read_b128 v[174:177], v185 offset:1024
	ds_read_b128 v[178:181], v185 offset:2048
	ds_read_b128 v[186:189], v185 offset:3072
	s_add_u32 s98, s30, 0x40000
	s_addc_u32 s99, s31, 0
	s_mov_b32 m0, s89
	ds_read_b128 v[190:193], v183 offset:32768
	ds_read_b128 v[194:197], v183 offset:33792
	ds_read_b128 v[198:201], v183 offset:34816
	ds_read_b128 v[202:205], v183 offset:35840
	ds_read_b128 v[206:209], v183 offset:36864
	ds_read_b128 v[210:213], v183 offset:37888
	ds_read_b128 v[214:217], v183 offset:38912
	ds_read_b128 v[218:221], v183 offset:39936
	global_load_lds_dwordx4 v130, s[98:99]
	s_mov_b32 m0, s90
	s_nop 0
	global_load_lds_dwordx4 v134, s[98:99]
	s_waitcnt vmcnt(8)
	s_waitcnt lgkmcnt(0)
	s_barrier
	s_setprio 1
	s_waitcnt lgkmcnt(0)
	v_mfma_f32_16x16x32_bf16 v[126:129], v[154:157], v[190:193], v[126:129]
	v_mfma_f32_16x16x32_bf16 v[122:125], v[162:165], v[190:193], v[122:125]
	v_mfma_f32_16x16x32_bf16 v[118:121], v[154:157], v[198:201], v[118:121]
	v_mfma_f32_16x16x32_bf16 v[114:117], v[162:165], v[198:201], v[114:117]
	v_mfma_f32_16x16x32_bf16 v[110:113], v[154:157], v[206:209], v[110:113]
	v_mfma_f32_16x16x32_bf16 v[106:109], v[162:165], v[206:209], v[106:109]
	v_mfma_f32_16x16x32_bf16 v[102:105], v[154:157], v[214:217], v[102:105]
	v_mfma_f32_16x16x32_bf16 v[98:101], v[162:165], v[214:217], v[98:101]
	v_mfma_f32_16x16x32_bf16 v[126:129], v[158:161], v[194:197], v[126:129]
	v_mfma_f32_16x16x32_bf16 v[122:125], v[166:169], v[194:197], v[122:125]
	v_mfma_f32_16x16x32_bf16 v[118:121], v[158:161], v[202:205], v[118:121]
	v_mfma_f32_16x16x32_bf16 v[114:117], v[166:169], v[202:205], v[114:117]
	v_mfma_f32_16x16x32_bf16 v[110:113], v[158:161], v[210:213], v[110:113]
	v_mfma_f32_16x16x32_bf16 v[106:109], v[166:169], v[210:213], v[106:109]
	v_mfma_f32_16x16x32_bf16 v[102:105], v[158:161], v[218:221], v[102:105]
	v_mfma_f32_16x16x32_bf16 v[98:101], v[166:169], v[218:221], v[98:101]
	s_setprio 0
	s_setprio 1
	v_mfma_f32_16x16x32_bf16 v[62:65], v[170:173], v[190:193], v[62:65]
	v_mfma_f32_16x16x32_bf16 v[58:61], v[178:181], v[190:193], v[58:61]
	v_mfma_f32_16x16x32_bf16 v[54:57], v[170:173], v[198:201], v[54:57]
	v_mfma_f32_16x16x32_bf16 v[50:53], v[178:181], v[198:201], v[50:53]
	v_mfma_f32_16x16x32_bf16 v[46:49], v[170:173], v[206:209], v[46:49]
	v_mfma_f32_16x16x32_bf16 v[42:45], v[178:181], v[206:209], v[42:45]
	v_mfma_f32_16x16x32_bf16 v[38:41], v[170:173], v[214:217], v[38:41]
	v_mfma_f32_16x16x32_bf16 v[34:37], v[178:181], v[214:217], v[34:37]
	v_mfma_f32_16x16x32_bf16 v[62:65], v[174:177], v[194:197], v[62:65]
	v_mfma_f32_16x16x32_bf16 v[58:61], v[186:189], v[194:197], v[58:61]
	v_mfma_f32_16x16x32_bf16 v[54:57], v[174:177], v[202:205], v[54:57]
	v_mfma_f32_16x16x32_bf16 v[50:53], v[186:189], v[202:205], v[50:53]
	v_mfma_f32_16x16x32_bf16 v[46:49], v[174:177], v[210:213], v[46:49]
	v_mfma_f32_16x16x32_bf16 v[42:45], v[186:189], v[210:213], v[42:45]
	v_mfma_f32_16x16x32_bf16 v[38:41], v[174:177], v[218:221], v[38:41]
	v_mfma_f32_16x16x32_bf16 v[34:37], v[186:189], v[218:221], v[34:37]
	s_setprio 0
	s_barrier
	s_add_i32 s98, s35, s77
	s_add_i32 m0, s98, 0xffffff80
	ds_read_b128 v[190:193], v183 offset:49152
	ds_read_b128 v[194:197], v183 offset:50176
	ds_read_b128 v[198:201], v183 offset:51200
	ds_read_b128 v[202:205], v183 offset:52224
	ds_read_b128 v[206:209], v183 offset:53248
	ds_read_b128 v[210:213], v183 offset:54272
	ds_read_b128 v[214:217], v183 offset:55296
	ds_read_b128 v[218:221], v183 offset:56320
	global_load_lds_dwordx4 v132, s[28:29] offset:128
	s_add_i32 m0, s98, 0x1f80
	s_add_i32 s98, s63, s77
	global_load_lds_dwordx4 v136, s[28:29] offset:128
	s_add_u32 s28, s28, 0x40080
	s_addc_u32 s29, s29, 0
	s_mov_b32 m0, s98
	s_nop 0
	global_load_lds_dwordx4 v132, s[28:29]
	s_add_i32 m0, s98, 0x2000
	s_nop 0
	global_load_lds_dwordx4 v136, s[28:29]
	s_add_i32 m0, s92, 0xffffff80
	s_nop 0
	global_load_lds_dwordx4 v130, s[30:31] offset:128
	s_add_i32 m0, s93, 0xffffff80
	s_nop 0
	global_load_lds_dwordx4 v134, s[30:31] offset:128
	s_waitcnt vmcnt(8)
	s_waitcnt lgkmcnt(0)
	s_barrier
	s_setprio 1
	s_waitcnt lgkmcnt(0)
	v_mfma_f32_16x16x32_bf16 v[94:97], v[154:157], v[190:193], v[94:97]
	v_mfma_f32_16x16x32_bf16 v[90:93], v[162:165], v[190:193], v[90:93]
	v_mfma_f32_16x16x32_bf16 v[86:89], v[154:157], v[198:201], v[86:89]
	v_mfma_f32_16x16x32_bf16 v[82:85], v[162:165], v[198:201], v[82:85]
	v_mfma_f32_16x16x32_bf16 v[78:81], v[154:157], v[206:209], v[78:81]
	v_mfma_f32_16x16x32_bf16 v[74:77], v[162:165], v[206:209], v[74:77]
	v_mfma_f32_16x16x32_bf16 v[70:73], v[154:157], v[214:217], v[70:73]
	v_mfma_f32_16x16x32_bf16 v[66:69], v[162:165], v[214:217], v[66:69]
	v_mfma_f32_16x16x32_bf16 v[94:97], v[158:161], v[194:197], v[94:97]
	v_mfma_f32_16x16x32_bf16 v[90:93], v[166:169], v[194:197], v[90:93]
	v_mfma_f32_16x16x32_bf16 v[86:89], v[158:161], v[202:205], v[86:89]
	v_mfma_f32_16x16x32_bf16 v[82:85], v[166:169], v[202:205], v[82:85]
	v_mfma_f32_16x16x32_bf16 v[78:81], v[158:161], v[210:213], v[78:81]
	v_mfma_f32_16x16x32_bf16 v[74:77], v[166:169], v[210:213], v[74:77]
	v_mfma_f32_16x16x32_bf16 v[70:73], v[158:161], v[218:221], v[70:73]
	v_mfma_f32_16x16x32_bf16 v[66:69], v[166:169], v[218:221], v[66:69]
	s_setprio 0
	s_setprio 1
	v_mfma_f32_16x16x32_bf16 v[30:33], v[170:173], v[190:193], v[30:33]
	v_mfma_f32_16x16x32_bf16 v[26:29], v[178:181], v[190:193], v[26:29]
	v_mfma_f32_16x16x32_bf16 v[22:25], v[170:173], v[198:201], v[22:25]
	v_mfma_f32_16x16x32_bf16 v[18:21], v[178:181], v[198:201], v[18:21]
	v_mfma_f32_16x16x32_bf16 v[14:17], v[170:173], v[206:209], v[14:17]
	v_mfma_f32_16x16x32_bf16 v[10:13], v[178:181], v[206:209], v[10:13]
	v_mfma_f32_16x16x32_bf16 v[6:9], v[170:173], v[214:217], v[6:9]
	v_mfma_f32_16x16x32_bf16 v[2:5], v[178:181], v[214:217], v[2:5]
	v_mfma_f32_16x16x32_bf16 v[30:33], v[174:177], v[194:197], v[30:33]
	v_mfma_f32_16x16x32_bf16 v[26:29], v[186:189], v[194:197], v[26:29]
	v_mfma_f32_16x16x32_bf16 v[22:25], v[174:177], v[202:205], v[22:25]
	v_mfma_f32_16x16x32_bf16 v[18:21], v[186:189], v[202:205], v[18:21]
	v_mfma_f32_16x16x32_bf16 v[14:17], v[174:177], v[210:213], v[14:17]
	v_mfma_f32_16x16x32_bf16 v[10:13], v[186:189], v[210:213], v[10:13]
	v_mfma_f32_16x16x32_bf16 v[6:9], v[174:177], v[218:221], v[6:9]
	v_mfma_f32_16x16x32_bf16 v[2:5], v[186:189], v[218:221], v[2:5]
	s_setprio 0
	s_barrier
	s_add_i32 s34, s34, 2
	s_add_u32 s12, s12, 0x100
	s_addc_u32 s13, s13, 0
	s_add_u32 s23, s23, 0x100
	s_addc_u32 s24, s24, 0
	s_cmp_gt_u32 s34, 13
	s_cbranch_scc0 .LBB0_862
	s_and_b64 vcc, exec, s[54:55]
	s_cbranch_vccz .LBB0_865
	s_barrier

.LBB0_1654:
	ds_read_b128 v[152:155], v131
	ds_read_b128 v[156:159], v131 offset:1024
	ds_read_b128 v[160:163], v131 offset:2048
	ds_read_b128 v[180:183], v131 offset:3072
	ds_read_b128 v[184:187], v176
	ds_read_b128 v[188:191], v176 offset:1024
	ds_read_b128 v[192:195], v176 offset:2048
	ds_read_b128 v[196:199], v176 offset:3072
	s_add_u32 s28, s36, 0xfffc0080
	s_addc_u32 s29, s37, -1
	s_cmp_eq_u32 s51, 12
	s_cselect_b32 s31, s15, s29
	s_cselect_b32 s30, s47, s28
	s_cselect_b32 s29, s13, s50
	s_cselect_b32 s28, s48, s49
	s_add_i32 m0, s33, 0xc000
	ds_read_b128 v[200:203], v177
	ds_read_b128 v[204:207], v177 offset:1024
	ds_read_b128 v[208:211], v177 offset:2048
	ds_read_b128 v[212:215], v177 offset:3072
	ds_read_b128 v[216:219], v177 offset:4096
	ds_read_b128 v[220:223], v177 offset:5120
	ds_read_b128 v[224:227], v177 offset:6144
	ds_read_b128 v[228:231], v177 offset:7168
	global_load_lds_dwordx4 v144, s[36:37]
	s_add_i32 m0, s33, 0xe000
	s_nop 0
	global_load_lds_dwordx4 v146, s[36:37]
	s_waitcnt vmcnt(8)
	s_waitcnt lgkmcnt(0)
	s_barrier
	s_setprio 1
	s_waitcnt lgkmcnt(0)
	v_mfma_f32_16x16x32_bf16 v[126:129], v[152:155], v[200:203], v[126:129]
	v_mfma_f32_16x16x32_bf16 v[122:125], v[160:163], v[200:203], v[122:125]
	v_mfma_f32_16x16x32_bf16 v[110:113], v[152:155], v[208:211], v[110:113]
	v_mfma_f32_16x16x32_bf16 v[106:109], v[160:163], v[208:211], v[106:109]
	v_mfma_f32_16x16x32_bf16 v[94:97], v[152:155], v[216:219], v[94:97]
	v_mfma_f32_16x16x32_bf16 v[90:93], v[160:163], v[216:219], v[90:93]
	v_mfma_f32_16x16x32_bf16 v[78:81], v[152:155], v[224:227], v[78:81]
	v_mfma_f32_16x16x32_bf16 v[74:77], v[160:163], v[224:227], v[74:77]
	v_mfma_f32_16x16x32_bf16 v[126:129], v[156:159], v[204:207], v[126:129]
	v_mfma_f32_16x16x32_bf16 v[122:125], v[180:183], v[204:207], v[122:125]
	v_mfma_f32_16x16x32_bf16 v[110:113], v[156:159], v[212:215], v[110:113]
	v_mfma_f32_16x16x32_bf16 v[106:109], v[180:183], v[212:215], v[106:109]
	v_mfma_f32_16x16x32_bf16 v[94:97], v[156:159], v[220:223], v[94:97]
	v_mfma_f32_16x16x32_bf16 v[90:93], v[180:183], v[220:223], v[90:93]
	v_mfma_f32_16x16x32_bf16 v[78:81], v[156:159], v[228:231], v[78:81]
	v_mfma_f32_16x16x32_bf16 v[74:77], v[180:183], v[228:231], v[74:77]
	s_setprio 0
	s_setprio 1
	v_mfma_f32_16x16x32_bf16 v[118:121], v[184:187], v[200:203], v[118:121]
	v_mfma_f32_16x16x32_bf16 v[114:117], v[192:195], v[200:203], v[114:117]
	v_mfma_f32_16x16x32_bf16 v[102:105], v[184:187], v[208:211], v[102:105]
	v_mfma_f32_16x16x32_bf16 v[98:101], v[192:195], v[208:211], v[98:101]
	v_mfma_f32_16x16x32_bf16 v[86:89], v[184:187], v[216:219], v[86:89]
	v_mfma_f32_16x16x32_bf16 v[82:85], v[192:195], v[216:219], v[82:85]
	v_mfma_f32_16x16x32_bf16 v[70:73], v[184:187], v[224:227], v[70:73]
	v_mfma_f32_16x16x32_bf16 v[66:69], v[192:195], v[224:227], v[66:69]
	v_mfma_f32_16x16x32_bf16 v[118:121], v[188:191], v[204:207], v[118:121]
	v_mfma_f32_16x16x32_bf16 v[114:117], v[196:199], v[204:207], v[114:117]
	v_mfma_f32_16x16x32_bf16 v[102:105], v[188:191], v[212:215], v[102:105]
	v_mfma_f32_16x16x32_bf16 v[98:101], v[196:199], v[212:215], v[98:101]
	v_mfma_f32_16x16x32_bf16 v[86:89], v[188:191], v[220:223], v[86:89]
	v_mfma_f32_16x16x32_bf16 v[82:85], v[196:199], v[220:223], v[82:85]
	v_mfma_f32_16x16x32_bf16 v[70:73], v[188:191], v[228:231], v[70:73]
	v_mfma_f32_16x16x32_bf16 v[66:69], v[196:199], v[228:231], v[66:69]
	s_setprio 0
	s_barrier
	s_add_i32 s52, s45, s25
	s_mov_b32 m0, s52
	ds_read_b128 v[200:203], v177 offset:16384
	ds_read_b128 v[204:207], v177 offset:17408
	ds_read_b128 v[208:211], v177 offset:18432
	ds_read_b128 v[212:215], v177 offset:19456
	ds_read_b128 v[216:219], v177 offset:20480
	ds_read_b128 v[220:223], v177 offset:21504
	ds_read_b128 v[224:227], v177 offset:22528
	ds_read_b128 v[228:231], v177 offset:23552
	global_load_lds_dwordx4 v134, s[28:29]
	s_add_i32 m0, s52, 0x2000
	s_add_u32 s52, s28, 0x40000
	s_addc_u32 s53, s29, 0
	s_add_i32 s54, s46, s25
	global_load_lds_dwordx4 v140, s[28:29]
	s_mov_b32 m0, s54
	s_nop 0
	global_load_lds_dwordx4 v134, s[52:53]
	s_add_i32 m0, s54, 0x2000
	s_nop 0
	global_load_lds_dwordx4 v140, s[52:53]
	s_mov_b32 m0, s33
	s_nop 0
	global_load_lds_dwordx4 v132, s[30:31]
	s_mov_b32 m0, s34
	s_nop 0
	global_load_lds_dwordx4 v136, s[30:31]
	s_waitcnt vmcnt(8)
	s_waitcnt lgkmcnt(0)
	s_barrier
	s_setprio 1
	s_waitcnt lgkmcnt(0)
	v_mfma_f32_16x16x32_bf16 v[62:65], v[152:155], v[200:203], v[62:65]
	v_mfma_f32_16x16x32_bf16 v[58:61], v[160:163], v[200:203], v[58:61]
	v_mfma_f32_16x16x32_bf16 v[46:49], v[152:155], v[208:211], v[46:49]
	v_mfma_f32_16x16x32_bf16 v[42:45], v[160:163], v[208:211], v[42:45]
	v_mfma_f32_16x16x32_bf16 v[30:33], v[152:155], v[216:219], v[30:33]
	v_mfma_f32_16x16x32_bf16 v[26:29], v[160:163], v[216:219], v[26:29]
	v_mfma_f32_16x16x32_bf16 v[14:17], v[152:155], v[224:227], v[14:17]
	v_mfma_f32_16x16x32_bf16 v[10:13], v[160:163], v[224:227], v[10:13]
	v_mfma_f32_16x16x32_bf16 v[62:65], v[156:159], v[204:207], v[62:65]
	v_mfma_f32_16x16x32_bf16 v[58:61], v[180:183], v[204:207], v[58:61]
	v_mfma_f32_16x16x32_bf16 v[46:49], v[156:159], v[212:215], v[46:49]
	v_mfma_f32_16x16x32_bf16 v[42:45], v[180:183], v[212:215], v[42:45]
	v_mfma_f32_16x16x32_bf16 v[30:33], v[156:159], v[220:223], v[30:33]
	v_mfma_f32_16x16x32_bf16 v[26:29], v[180:183], v[220:223], v[26:29]
	v_mfma_f32_16x16x32_bf16 v[14:17], v[156:159], v[228:231], v[14:17]
	v_mfma_f32_16x16x32_bf16 v[10:13], v[180:183], v[228:231], v[10:13]
	s_setprio 0
	s_setprio 1
	v_mfma_f32_16x16x32_bf16 v[54:57], v[184:187], v[200:203], v[54:57]
	v_mfma_f32_16x16x32_bf16 v[50:53], v[192:195], v[200:203], v[50:53]
	v_mfma_f32_16x16x32_bf16 v[38:41], v[184:187], v[208:211], v[38:41]
	v_mfma_f32_16x16x32_bf16 v[34:37], v[192:195], v[208:211], v[34:37]
	v_mfma_f32_16x16x32_bf16 v[22:25], v[184:187], v[216:219], v[22:25]
	v_mfma_f32_16x16x32_bf16 v[18:21], v[192:195], v[216:219], v[18:21]
	v_mfma_f32_16x16x32_bf16 v[6:9], v[184:187], v[224:227], v[6:9]
	v_mfma_f32_16x16x32_bf16 v[2:5], v[192:195], v[224:227], v[2:5]
	v_mfma_f32_16x16x32_bf16 v[54:57], v[188:191], v[204:207], v[54:57]
	v_mfma_f32_16x16x32_bf16 v[50:53], v[196:199], v[204:207], v[50:53]
	v_mfma_f32_16x16x32_bf16 v[38:41], v[188:191], v[212:215], v[38:41]
	v_mfma_f32_16x16x32_bf16 v[34:37], v[196:199], v[212:215], v[34:37]
	v_mfma_f32_16x16x32_bf16 v[22:25], v[188:191], v[220:223], v[22:25]
	v_mfma_f32_16x16x32_bf16 v[18:21], v[196:199], v[220:223], v[18:21]
	v_mfma_f32_16x16x32_bf16 v[6:9], v[188:191], v[228:231], v[6:9]
	v_mfma_f32_16x16x32_bf16 v[2:5], v[196:199], v[228:231], v[2:5]
	s_setprio 0
	s_barrier
	s_add_i32 s52, 0, 0x18000
	v_add_u32_e32 v179, s52, v175
	s_add_i32 s53, 0, 0x1c000
	ds_read_b128 v[152:155], v179
	ds_read_b128 v[156:159], v179 offset:1024
	ds_read_b128 v[160:163], v179 offset:2048
	ds_read_b128 v[180:183], v179 offset:3072
	v_add_u32_e32 v179, s53, v175
	ds_read_b128 v[184:187], v179
	ds_read_b128 v[188:191], v179 offset:1024
	ds_read_b128 v[192:195], v179 offset:2048
	ds_read_b128 v[196:199], v179 offset:3072
	s_add_u32 s98, s30, 0x40000
	s_addc_u32 s99, s31, 0
	s_mov_b32 m0, s35
	ds_read_b128 v[200:203], v177 offset:32768
	ds_read_b128 v[204:207], v177 offset:33792
	ds_read_b128 v[208:211], v177 offset:34816
	ds_read_b128 v[212:215], v177 offset:35840
	ds_read_b128 v[216:219], v177 offset:36864
	ds_read_b128 v[220:223], v177 offset:37888
	ds_read_b128 v[224:227], v177 offset:38912
	ds_read_b128 v[228:231], v177 offset:39936
	global_load_lds_dwordx4 v132, s[98:99]
	s_mov_b32 m0, s38
	s_nop 0
	global_load_lds_dwordx4 v136, s[98:99]
	s_waitcnt vmcnt(8)
	s_waitcnt lgkmcnt(0)
	s_barrier
	s_setprio 1
	s_waitcnt lgkmcnt(0)
	v_mfma_f32_16x16x32_bf16 v[126:129], v[152:155], v[200:203], v[126:129]
	v_mfma_f32_16x16x32_bf16 v[122:125], v[160:163], v[200:203], v[122:125]
	v_mfma_f32_16x16x32_bf16 v[110:113], v[152:155], v[208:211], v[110:113]
	v_mfma_f32_16x16x32_bf16 v[106:109], v[160:163], v[208:211], v[106:109]
	v_mfma_f32_16x16x32_bf16 v[94:97], v[152:155], v[216:219], v[94:97]
	v_mfma_f32_16x16x32_bf16 v[90:93], v[160:163], v[216:219], v[90:93]
	v_mfma_f32_16x16x32_bf16 v[78:81], v[152:155], v[224:227], v[78:81]
	v_mfma_f32_16x16x32_bf16 v[74:77], v[160:163], v[224:227], v[74:77]
	v_mfma_f32_16x16x32_bf16 v[126:129], v[156:159], v[204:207], v[126:129]
	v_mfma_f32_16x16x32_bf16 v[122:125], v[180:183], v[204:207], v[122:125]
	v_mfma_f32_16x16x32_bf16 v[110:113], v[156:159], v[212:215], v[110:113]
	v_mfma_f32_16x16x32_bf16 v[106:109], v[180:183], v[212:215], v[106:109]
	v_mfma_f32_16x16x32_bf16 v[94:97], v[156:159], v[220:223], v[94:97]
	v_mfma_f32_16x16x32_bf16 v[90:93], v[180:183], v[220:223], v[90:93]
	v_mfma_f32_16x16x32_bf16 v[78:81], v[156:159], v[228:231], v[78:81]
	v_mfma_f32_16x16x32_bf16 v[74:77], v[180:183], v[228:231], v[74:77]
	s_setprio 0
	s_setprio 1
	v_mfma_f32_16x16x32_bf16 v[118:121], v[184:187], v[200:203], v[118:121]
	v_mfma_f32_16x16x32_bf16 v[114:117], v[192:195], v[200:203], v[114:117]
	v_mfma_f32_16x16x32_bf16 v[102:105], v[184:187], v[208:211], v[102:105]
	v_mfma_f32_16x16x32_bf16 v[98:101], v[192:195], v[208:211], v[98:101]
	v_mfma_f32_16x16x32_bf16 v[86:89], v[184:187], v[216:219], v[86:89]
	v_mfma_f32_16x16x32_bf16 v[82:85], v[192:195], v[216:219], v[82:85]
	v_mfma_f32_16x16x32_bf16 v[70:73], v[184:187], v[224:227], v[70:73]
	v_mfma_f32_16x16x32_bf16 v[66:69], v[192:195], v[224:227], v[66:69]
	v_mfma_f32_16x16x32_bf16 v[118:121], v[188:191], v[204:207], v[118:121]
	v_mfma_f32_16x16x32_bf16 v[114:117], v[196:199], v[204:207], v[114:117]
	v_mfma_f32_16x16x32_bf16 v[102:105], v[188:191], v[212:215], v[102:105]
	v_mfma_f32_16x16x32_bf16 v[98:101], v[196:199], v[212:215], v[98:101]
	v_mfma_f32_16x16x32_bf16 v[86:89], v[188:191], v[220:223], v[86:89]
	v_mfma_f32_16x16x32_bf16 v[82:85], v[196:199], v[220:223], v[82:85]
	v_mfma_f32_16x16x32_bf16 v[70:73], v[188:191], v[228:231], v[70:73]
	v_mfma_f32_16x16x32_bf16 v[66:69], v[196:199], v[228:231], v[66:69]
	s_setprio 0
	s_barrier
	s_add_i32 s98, s52, s25
	s_add_i32 m0, s98, 0xffffff80
	ds_read_b128 v[200:203], v177 offset:49152
	ds_read_b128 v[204:207], v177 offset:50176
	ds_read_b128 v[208:211], v177 offset:51200
	ds_read_b128 v[212:215], v177 offset:52224
	ds_read_b128 v[216:219], v177 offset:53248
	ds_read_b128 v[220:223], v177 offset:54272
	ds_read_b128 v[224:227], v177 offset:55296
	ds_read_b128 v[228:231], v177 offset:56320
	global_load_lds_dwordx4 v134, s[28:29] offset:128
	s_add_i32 m0, s98, 0x1f80
	s_add_i32 s98, s53, s25
	global_load_lds_dwordx4 v140, s[28:29] offset:128
	s_add_u32 s28, s28, 0x40080
	s_addc_u32 s29, s29, 0
	s_mov_b32 m0, s98
	s_nop 0
	global_load_lds_dwordx4 v134, s[28:29]
	s_add_i32 m0, s98, 0x2000
	s_nop 0
	global_load_lds_dwordx4 v140, s[28:29]
	s_add_i32 m0, s42, 0xffffff80
	s_nop 0
	global_load_lds_dwordx4 v132, s[30:31] offset:128
	s_add_i32 m0, s43, 0xffffff80
	s_nop 0
	global_load_lds_dwordx4 v136, s[30:31] offset:128
	s_waitcnt vmcnt(8)
	s_waitcnt lgkmcnt(0)
	s_barrier
	s_setprio 1
	s_waitcnt lgkmcnt(0)
	v_mfma_f32_16x16x32_bf16 v[62:65], v[152:155], v[200:203], v[62:65]
	v_mfma_f32_16x16x32_bf16 v[58:61], v[160:163], v[200:203], v[58:61]
	v_mfma_f32_16x16x32_bf16 v[46:49], v[152:155], v[208:211], v[46:49]
	v_mfma_f32_16x16x32_bf16 v[42:45], v[160:163], v[208:211], v[42:45]
	v_mfma_f32_16x16x32_bf16 v[30:33], v[152:155], v[216:219], v[30:33]
	v_mfma_f32_16x16x32_bf16 v[26:29], v[160:163], v[216:219], v[26:29]
	v_mfma_f32_16x16x32_bf16 v[14:17], v[152:155], v[224:227], v[14:17]
	v_mfma_f32_16x16x32_bf16 v[10:13], v[160:163], v[224:227], v[10:13]
	v_mfma_f32_16x16x32_bf16 v[62:65], v[156:159], v[204:207], v[62:65]
	v_mfma_f32_16x16x32_bf16 v[58:61], v[180:183], v[204:207], v[58:61]
	v_mfma_f32_16x16x32_bf16 v[46:49], v[156:159], v[212:215], v[46:49]
	v_mfma_f32_16x16x32_bf16 v[42:45], v[180:183], v[212:215], v[42:45]
	v_mfma_f32_16x16x32_bf16 v[30:33], v[156:159], v[220:223], v[30:33]
	v_mfma_f32_16x16x32_bf16 v[26:29], v[180:183], v[220:223], v[26:29]
	v_mfma_f32_16x16x32_bf16 v[14:17], v[156:159], v[228:231], v[14:17]
	v_mfma_f32_16x16x32_bf16 v[10:13], v[180:183], v[228:231], v[10:13]
	s_setprio 0
	s_setprio 1
	v_mfma_f32_16x16x32_bf16 v[54:57], v[184:187], v[200:203], v[54:57]
	v_mfma_f32_16x16x32_bf16 v[50:53], v[192:195], v[200:203], v[50:53]
	v_mfma_f32_16x16x32_bf16 v[38:41], v[184:187], v[208:211], v[38:41]
	v_mfma_f32_16x16x32_bf16 v[34:37], v[192:195], v[208:211], v[34:37]
	v_mfma_f32_16x16x32_bf16 v[22:25], v[184:187], v[216:219], v[22:25]
	v_mfma_f32_16x16x32_bf16 v[18:21], v[192:195], v[216:219], v[18:21]
	v_mfma_f32_16x16x32_bf16 v[6:9], v[184:187], v[224:227], v[6:9]
	v_mfma_f32_16x16x32_bf16 v[2:5], v[192:195], v[224:227], v[2:5]
	v_mfma_f32_16x16x32_bf16 v[54:57], v[188:191], v[204:207], v[54:57]
	v_mfma_f32_16x16x32_bf16 v[50:53], v[196:199], v[204:207], v[50:53]
	v_mfma_f32_16x16x32_bf16 v[38:41], v[188:191], v[212:215], v[38:41]
	v_mfma_f32_16x16x32_bf16 v[34:37], v[196:199], v[212:215], v[34:37]
	v_mfma_f32_16x16x32_bf16 v[22:25], v[188:191], v[220:223], v[22:25]
	v_mfma_f32_16x16x32_bf16 v[18:21], v[196:199], v[220:223], v[18:21]
	v_mfma_f32_16x16x32_bf16 v[6:9], v[188:191], v[228:231], v[6:9]
	v_mfma_f32_16x16x32_bf16 v[2:5], v[196:199], v[228:231], v[2:5]
	s_setprio 0
	s_barrier
	s_add_i32 s51, s51, 2
	s_add_u32 s36, s36, 0x100
	s_addc_u32 s37, s37, 0
	s_add_u32 s49, s49, 0x100
	s_addc_u32 s50, s50, 0
	s_cmp_gt_u32 s51, 13
	s_cbranch_scc0 .LBB0_1654
	s_and_b64 vcc, exec, s[10:11]
	s_cbranch_vccz .LBB0_1657
	s_barrier

.LBB0_1786:
	v_add_u32_e32 v155, s48, v153
	ds_read_b128 v[156:159], v155
	ds_read_b128 v[160:163], v155 offset:1024
	ds_read_b128 v[164:167], v155 offset:2048
	ds_read_b128 v[168:171], v155 offset:3072
	v_add_u32_e32 v155, s49, v153
	s_add_u32 s28, s10, s38
	ds_read_b128 v[172:175], v155
	ds_read_b128 v[176:179], v155 offset:1024
	ds_read_b128 v[180:183], v155 offset:2048
	ds_read_b128 v[184:187], v155 offset:3072
	s_addc_u32 s29, s11, s39
	s_add_u32 s28, s28, 0x100
	s_addc_u32 s29, s29, 0
	s_add_u32 s54, s21, s38
	s_addc_u32 s55, s50, s39
	s_cmpk_eq_i32 s38, 0x700
	s_cselect_b32 s31, s17, s29
	s_cselect_b32 s30, s51, s28
	s_cselect_b32 s29, s15, s55
	s_cselect_b32 s28, s52, s54
	v_lshl_add_u64 v[220:221], v[148:149], 0, s[38:39]
	s_add_i32 m0, s1, 0xc000
	ds_read_b128 v[188:191], v154
	ds_read_b128 v[192:195], v154 offset:1024
	ds_read_b128 v[196:199], v154 offset:2048
	ds_read_b128 v[200:203], v154 offset:3072
	ds_read_b128 v[204:207], v154 offset:4096
	ds_read_b128 v[208:211], v154 offset:5120
	ds_read_b128 v[212:215], v154 offset:6144
	ds_read_b128 v[216:219], v154 offset:7168
	global_load_lds_dwordx4 v[220:221], off
	v_lshl_add_u64 v[220:221], v[150:151], 0, s[38:39]
	s_add_i32 m0, s1, 0xe000
	s_nop 0
	global_load_lds_dwordx4 v[220:221], off
	s_waitcnt vmcnt(8)
	s_waitcnt lgkmcnt(0)
	s_barrier
	s_setprio 1
	s_waitcnt lgkmcnt(0)
	v_mfma_f32_16x16x32_bf16 v[126:129], v[156:159], v[188:191], v[126:129]
	v_mfma_f32_16x16x32_bf16 v[122:125], v[164:167], v[188:191], v[122:125]
	v_mfma_f32_16x16x32_bf16 v[110:113], v[156:159], v[196:199], v[110:113]
	v_mfma_f32_16x16x32_bf16 v[106:109], v[164:167], v[196:199], v[106:109]
	v_mfma_f32_16x16x32_bf16 v[94:97], v[156:159], v[204:207], v[94:97]
	v_mfma_f32_16x16x32_bf16 v[90:93], v[164:167], v[204:207], v[90:93]
	v_mfma_f32_16x16x32_bf16 v[78:81], v[156:159], v[212:215], v[78:81]
	v_mfma_f32_16x16x32_bf16 v[74:77], v[164:167], v[212:215], v[74:77]
	v_mfma_f32_16x16x32_bf16 v[126:129], v[160:163], v[192:195], v[126:129]
	v_mfma_f32_16x16x32_bf16 v[122:125], v[168:171], v[192:195], v[122:125]
	v_mfma_f32_16x16x32_bf16 v[110:113], v[160:163], v[200:203], v[110:113]
	v_mfma_f32_16x16x32_bf16 v[106:109], v[168:171], v[200:203], v[106:109]
	v_mfma_f32_16x16x32_bf16 v[94:97], v[160:163], v[208:211], v[94:97]
	v_mfma_f32_16x16x32_bf16 v[90:93], v[168:171], v[208:211], v[90:93]
	v_mfma_f32_16x16x32_bf16 v[78:81], v[160:163], v[216:219], v[78:81]
	v_mfma_f32_16x16x32_bf16 v[74:77], v[168:171], v[216:219], v[74:77]
	s_setprio 0
	s_setprio 1
	v_mfma_f32_16x16x32_bf16 v[118:121], v[172:175], v[188:191], v[118:121]
	v_mfma_f32_16x16x32_bf16 v[114:117], v[180:183], v[188:191], v[114:117]
	v_mfma_f32_16x16x32_bf16 v[102:105], v[172:175], v[196:199], v[102:105]
	v_mfma_f32_16x16x32_bf16 v[98:101], v[180:183], v[196:199], v[98:101]
	v_mfma_f32_16x16x32_bf16 v[86:89], v[172:175], v[204:207], v[86:89]
	v_mfma_f32_16x16x32_bf16 v[82:85], v[180:183], v[204:207], v[82:85]
	v_mfma_f32_16x16x32_bf16 v[70:73], v[172:175], v[212:215], v[70:73]
	v_mfma_f32_16x16x32_bf16 v[66:69], v[180:183], v[212:215], v[66:69]
	v_mfma_f32_16x16x32_bf16 v[118:121], v[176:179], v[192:195], v[118:121]
	v_mfma_f32_16x16x32_bf16 v[114:117], v[184:187], v[192:195], v[114:117]
	v_mfma_f32_16x16x32_bf16 v[102:105], v[176:179], v[200:203], v[102:105]
	v_mfma_f32_16x16x32_bf16 v[98:101], v[184:187], v[200:203], v[98:101]
	v_mfma_f32_16x16x32_bf16 v[86:89], v[176:179], v[208:211], v[86:89]
	v_mfma_f32_16x16x32_bf16 v[82:85], v[184:187], v[208:211], v[82:85]
	v_mfma_f32_16x16x32_bf16 v[70:73], v[176:179], v[216:219], v[70:73]
	v_mfma_f32_16x16x32_bf16 v[66:69], v[184:187], v[216:219], v[66:69]
	s_setprio 0
	s_barrier
	s_add_i32 s54, s48, s41
	s_mov_b32 m0, s54
	ds_read_b128 v[188:191], v154 offset:16384
	ds_read_b128 v[192:195], v154 offset:17408
	ds_read_b128 v[196:199], v154 offset:18432
	ds_read_b128 v[200:203], v154 offset:19456
	ds_read_b128 v[204:207], v154 offset:20480
	ds_read_b128 v[208:211], v154 offset:21504
	ds_read_b128 v[212:215], v154 offset:22528
	ds_read_b128 v[216:219], v154 offset:23552
	global_load_lds_dwordx4 v132, s[28:29]
	s_add_i32 m0, s54, 0x2000
	s_add_u32 s54, s28, 0x40000
	s_addc_u32 s55, s29, 0
	s_add_i32 s56, s49, s41
	global_load_lds_dwordx4 v136, s[28:29]
	s_mov_b32 m0, s56
	s_nop 0
	global_load_lds_dwordx4 v132, s[54:55]
	s_add_i32 m0, s56, 0x2000
	s_nop 0
	global_load_lds_dwordx4 v136, s[54:55]
	s_mov_b32 m0, s1
	s_nop 0
	global_load_lds_dwordx4 v130, s[30:31]
	s_mov_b32 m0, s42
	s_nop 0
	global_load_lds_dwordx4 v134, s[30:31]
	s_waitcnt vmcnt(8)
	s_waitcnt lgkmcnt(0)
	s_barrier
	s_setprio 1
	s_waitcnt lgkmcnt(0)
	v_mfma_f32_16x16x32_bf16 v[62:65], v[156:159], v[188:191], v[62:65]
	v_mfma_f32_16x16x32_bf16 v[58:61], v[164:167], v[188:191], v[58:61]
	v_mfma_f32_16x16x32_bf16 v[46:49], v[156:159], v[196:199], v[46:49]
	v_mfma_f32_16x16x32_bf16 v[42:45], v[164:167], v[196:199], v[42:45]
	v_mfma_f32_16x16x32_bf16 v[30:33], v[156:159], v[204:207], v[30:33]
	v_mfma_f32_16x16x32_bf16 v[26:29], v[164:167], v[204:207], v[26:29]
	v_mfma_f32_16x16x32_bf16 v[14:17], v[156:159], v[212:215], v[14:17]
	v_mfma_f32_16x16x32_bf16 v[10:13], v[164:167], v[212:215], v[10:13]
	v_mfma_f32_16x16x32_bf16 v[62:65], v[160:163], v[192:195], v[62:65]
	v_mfma_f32_16x16x32_bf16 v[58:61], v[168:171], v[192:195], v[58:61]
	v_mfma_f32_16x16x32_bf16 v[46:49], v[160:163], v[200:203], v[46:49]
	v_mfma_f32_16x16x32_bf16 v[42:45], v[168:171], v[200:203], v[42:45]
	v_mfma_f32_16x16x32_bf16 v[30:33], v[160:163], v[208:211], v[30:33]
	v_mfma_f32_16x16x32_bf16 v[26:29], v[168:171], v[208:211], v[26:29]
	v_mfma_f32_16x16x32_bf16 v[14:17], v[160:163], v[216:219], v[14:17]
	v_mfma_f32_16x16x32_bf16 v[10:13], v[168:171], v[216:219], v[10:13]
	s_setprio 0
	s_setprio 1
	v_mfma_f32_16x16x32_bf16 v[54:57], v[172:175], v[188:191], v[54:57]
	v_mfma_f32_16x16x32_bf16 v[50:53], v[180:183], v[188:191], v[50:53]
	v_mfma_f32_16x16x32_bf16 v[38:41], v[172:175], v[196:199], v[38:41]
	v_mfma_f32_16x16x32_bf16 v[34:37], v[180:183], v[196:199], v[34:37]
	v_mfma_f32_16x16x32_bf16 v[22:25], v[172:175], v[204:207], v[22:25]
	v_mfma_f32_16x16x32_bf16 v[18:21], v[180:183], v[204:207], v[18:21]
	v_mfma_f32_16x16x32_bf16 v[6:9], v[172:175], v[212:215], v[6:9]
	v_mfma_f32_16x16x32_bf16 v[2:5], v[180:183], v[212:215], v[2:5]
	v_mfma_f32_16x16x32_bf16 v[54:57], v[176:179], v[192:195], v[54:57]
	v_mfma_f32_16x16x32_bf16 v[50:53], v[184:187], v[192:195], v[50:53]
	v_mfma_f32_16x16x32_bf16 v[38:41], v[176:179], v[200:203], v[38:41]
	v_mfma_f32_16x16x32_bf16 v[34:37], v[184:187], v[200:203], v[34:37]
	v_mfma_f32_16x16x32_bf16 v[22:25], v[176:179], v[208:211], v[22:25]
	v_mfma_f32_16x16x32_bf16 v[18:21], v[184:187], v[208:211], v[18:21]
	v_mfma_f32_16x16x32_bf16 v[6:9], v[176:179], v[216:219], v[6:9]
	v_mfma_f32_16x16x32_bf16 v[2:5], v[184:187], v[216:219], v[2:5]
	s_setprio 0
	s_barrier
	s_add_i32 s54, 0, 0x18000
	v_add_u32_e32 v155, s54, v153
	s_add_i32 s55, 0, 0x1c000
	ds_read_b128 v[156:159], v155
	ds_read_b128 v[160:163], v155 offset:1024
	ds_read_b128 v[164:167], v155 offset:2048
	ds_read_b128 v[168:171], v155 offset:3072
	v_add_u32_e32 v155, s55, v153
	ds_read_b128 v[172:175], v155
	ds_read_b128 v[176:179], v155 offset:1024
	ds_read_b128 v[180:183], v155 offset:2048
	ds_read_b128 v[184:187], v155 offset:3072
	s_add_u32 s98, s30, 0x40000
	s_addc_u32 s99, s31, 0
	s_mov_b32 m0, s43
	ds_read_b128 v[188:191], v154 offset:32768
	ds_read_b128 v[192:195], v154 offset:33792
	ds_read_b128 v[196:199], v154 offset:34816
	ds_read_b128 v[200:203], v154 offset:35840
	ds_read_b128 v[204:207], v154 offset:36864
	ds_read_b128 v[208:211], v154 offset:37888
	ds_read_b128 v[212:215], v154 offset:38912
	ds_read_b128 v[216:219], v154 offset:39936
	global_load_lds_dwordx4 v130, s[98:99]
	s_mov_b32 m0, s44
	s_nop 0
	global_load_lds_dwordx4 v134, s[98:99]
	s_waitcnt vmcnt(8)
	s_waitcnt lgkmcnt(0)
	s_barrier
	s_setprio 1
	s_waitcnt lgkmcnt(0)
	v_mfma_f32_16x16x32_bf16 v[126:129], v[156:159], v[188:191], v[126:129]
	v_mfma_f32_16x16x32_bf16 v[122:125], v[164:167], v[188:191], v[122:125]
	v_mfma_f32_16x16x32_bf16 v[110:113], v[156:159], v[196:199], v[110:113]
	v_mfma_f32_16x16x32_bf16 v[106:109], v[164:167], v[196:199], v[106:109]
	v_mfma_f32_16x16x32_bf16 v[94:97], v[156:159], v[204:207], v[94:97]
	v_mfma_f32_16x16x32_bf16 v[90:93], v[164:167], v[204:207], v[90:93]
	v_mfma_f32_16x16x32_bf16 v[78:81], v[156:159], v[212:215], v[78:81]
	v_mfma_f32_16x16x32_bf16 v[74:77], v[164:167], v[212:215], v[74:77]
	v_mfma_f32_16x16x32_bf16 v[126:129], v[160:163], v[192:195], v[126:129]
	v_mfma_f32_16x16x32_bf16 v[122:125], v[168:171], v[192:195], v[122:125]
	v_mfma_f32_16x16x32_bf16 v[110:113], v[160:163], v[200:203], v[110:113]
	v_mfma_f32_16x16x32_bf16 v[106:109], v[168:171], v[200:203], v[106:109]
	v_mfma_f32_16x16x32_bf16 v[94:97], v[160:163], v[208:211], v[94:97]
	v_mfma_f32_16x16x32_bf16 v[90:93], v[168:171], v[208:211], v[90:93]
	v_mfma_f32_16x16x32_bf16 v[78:81], v[160:163], v[216:219], v[78:81]
	v_mfma_f32_16x16x32_bf16 v[74:77], v[168:171], v[216:219], v[74:77]
	s_setprio 0
	s_setprio 1
	v_mfma_f32_16x16x32_bf16 v[118:121], v[172:175], v[188:191], v[118:121]
	v_mfma_f32_16x16x32_bf16 v[114:117], v[180:183], v[188:191], v[114:117]
	v_mfma_f32_16x16x32_bf16 v[102:105], v[172:175], v[196:199], v[102:105]
	v_mfma_f32_16x16x32_bf16 v[98:101], v[180:183], v[196:199], v[98:101]
	v_mfma_f32_16x16x32_bf16 v[86:89], v[172:175], v[204:207], v[86:89]
	v_mfma_f32_16x16x32_bf16 v[82:85], v[180:183], v[204:207], v[82:85]
	v_mfma_f32_16x16x32_bf16 v[70:73], v[172:175], v[212:215], v[70:73]
	v_mfma_f32_16x16x32_bf16 v[66:69], v[180:183], v[212:215], v[66:69]
	v_mfma_f32_16x16x32_bf16 v[118:121], v[176:179], v[192:195], v[118:121]
	v_mfma_f32_16x16x32_bf16 v[114:117], v[184:187], v[192:195], v[114:117]
	v_mfma_f32_16x16x32_bf16 v[102:105], v[176:179], v[200:203], v[102:105]
	v_mfma_f32_16x16x32_bf16 v[98:101], v[184:187], v[200:203], v[98:101]
	v_mfma_f32_16x16x32_bf16 v[86:89], v[176:179], v[208:211], v[86:89]
	v_mfma_f32_16x16x32_bf16 v[82:85], v[184:187], v[208:211], v[82:85]
	v_mfma_f32_16x16x32_bf16 v[70:73], v[176:179], v[216:219], v[70:73]
	v_mfma_f32_16x16x32_bf16 v[66:69], v[184:187], v[216:219], v[66:69]
	s_setprio 0
	s_barrier
	s_add_i32 s98, s54, s41
	s_add_i32 m0, s98, 0xffffff80
	ds_read_b128 v[188:191], v154 offset:49152
	ds_read_b128 v[192:195], v154 offset:50176
	ds_read_b128 v[196:199], v154 offset:51200
	ds_read_b128 v[200:203], v154 offset:52224
	ds_read_b128 v[204:207], v154 offset:53248
	ds_read_b128 v[208:211], v154 offset:54272
	ds_read_b128 v[212:215], v154 offset:55296
	ds_read_b128 v[216:219], v154 offset:56320
	global_load_lds_dwordx4 v132, s[28:29] offset:128
	s_add_i32 m0, s98, 0x1f80
	s_add_i32 s98, s55, s41
	global_load_lds_dwordx4 v136, s[28:29] offset:128
	s_add_u32 s28, s28, 0x40080
	s_addc_u32 s29, s29, 0
	s_mov_b32 m0, s98
	s_nop 0
	global_load_lds_dwordx4 v132, s[28:29]
	s_add_i32 m0, s98, 0x2000
	s_nop 0
	global_load_lds_dwordx4 v136, s[28:29]
	s_add_i32 m0, s46, 0xffffff80
	s_nop 0
	global_load_lds_dwordx4 v130, s[30:31] offset:128
	s_add_i32 m0, s47, 0xffffff80
	s_nop 0
	global_load_lds_dwordx4 v134, s[30:31] offset:128
	s_waitcnt vmcnt(8)
	s_waitcnt lgkmcnt(0)
	s_barrier
	s_setprio 1
	s_waitcnt lgkmcnt(0)
	v_mfma_f32_16x16x32_bf16 v[62:65], v[156:159], v[188:191], v[62:65]
	v_mfma_f32_16x16x32_bf16 v[58:61], v[164:167], v[188:191], v[58:61]
	v_mfma_f32_16x16x32_bf16 v[46:49], v[156:159], v[196:199], v[46:49]
	v_mfma_f32_16x16x32_bf16 v[42:45], v[164:167], v[196:199], v[42:45]
	v_mfma_f32_16x16x32_bf16 v[30:33], v[156:159], v[204:207], v[30:33]
	v_mfma_f32_16x16x32_bf16 v[26:29], v[164:167], v[204:207], v[26:29]
	v_mfma_f32_16x16x32_bf16 v[14:17], v[156:159], v[212:215], v[14:17]
	v_mfma_f32_16x16x32_bf16 v[10:13], v[164:167], v[212:215], v[10:13]
	v_mfma_f32_16x16x32_bf16 v[62:65], v[160:163], v[192:195], v[62:65]
	v_mfma_f32_16x16x32_bf16 v[58:61], v[168:171], v[192:195], v[58:61]
	v_mfma_f32_16x16x32_bf16 v[46:49], v[160:163], v[200:203], v[46:49]
	v_mfma_f32_16x16x32_bf16 v[42:45], v[168:171], v[200:203], v[42:45]
	v_mfma_f32_16x16x32_bf16 v[30:33], v[160:163], v[208:211], v[30:33]
	v_mfma_f32_16x16x32_bf16 v[26:29], v[168:171], v[208:211], v[26:29]
	v_mfma_f32_16x16x32_bf16 v[14:17], v[160:163], v[216:219], v[14:17]
	v_mfma_f32_16x16x32_bf16 v[10:13], v[168:171], v[216:219], v[10:13]
	s_setprio 0
	s_setprio 1
	v_mfma_f32_16x16x32_bf16 v[54:57], v[172:175], v[188:191], v[54:57]
	v_mfma_f32_16x16x32_bf16 v[50:53], v[180:183], v[188:191], v[50:53]
	v_mfma_f32_16x16x32_bf16 v[38:41], v[172:175], v[196:199], v[38:41]
	v_mfma_f32_16x16x32_bf16 v[34:37], v[180:183], v[196:199], v[34:37]
	v_mfma_f32_16x16x32_bf16 v[22:25], v[172:175], v[204:207], v[22:25]
	v_mfma_f32_16x16x32_bf16 v[18:21], v[180:183], v[204:207], v[18:21]
	v_mfma_f32_16x16x32_bf16 v[6:9], v[172:175], v[212:215], v[6:9]
	v_mfma_f32_16x16x32_bf16 v[2:5], v[180:183], v[212:215], v[2:5]
	v_mfma_f32_16x16x32_bf16 v[54:57], v[176:179], v[192:195], v[54:57]
	v_mfma_f32_16x16x32_bf16 v[50:53], v[184:187], v[192:195], v[50:53]
	v_mfma_f32_16x16x32_bf16 v[38:41], v[176:179], v[200:203], v[38:41]
	v_mfma_f32_16x16x32_bf16 v[34:37], v[184:187], v[200:203], v[34:37]
	v_mfma_f32_16x16x32_bf16 v[22:25], v[176:179], v[208:211], v[22:25]
	v_mfma_f32_16x16x32_bf16 v[18:21], v[184:187], v[208:211], v[18:21]
	v_mfma_f32_16x16x32_bf16 v[6:9], v[176:179], v[216:219], v[6:9]
	v_mfma_f32_16x16x32_bf16 v[2:5], v[184:187], v[216:219], v[2:5]
	s_setprio 0
	s_barrier
	s_add_i32 s53, s53, 2
	s_add_u32 s38, s38, 0x100
	s_addc_u32 s39, s39, 0
	s_cmp_gt_u32 s53, 13
	s_cbranch_scc0 .LBB0_1786
	s_add_u32 s28, s21, 0xffffff00
	s_addc_u32 s29, s50, -1
	s_andn2_b64 vcc, exec, s[4:5]
	s_cbranch_vccnz .LBB0_1789
	v_mov_b32_e32 v2, 0
	s_mov_b32 s6, s14
	s_mov_b32 s0, s16
	s_mov_b64 s[10:11], s[36:37]
	s_mov_b32 s45, s20
	v_mov_b32_e32 v3, v2
	v_mov_b32_e32 v4, v2
	v_mov_b32_e32 v5, v2
	v_mov_b32_e32 v6, v2
	v_mov_b32_e32 v7, v2
	v_mov_b32_e32 v8, v2
	v_mov_b32_e32 v9, v2
	v_mov_b32_e32 v18, v2
	v_mov_b32_e32 v19, v2
	v_mov_b32_e32 v20, v2
	v_mov_b32_e32 v21, v2
	v_mov_b32_e32 v22, v2
	v_mov_b32_e32 v23, v2
	v_mov_b32_e32 v24, v2
	v_mov_b32_e32 v25, v2
	v_mov_b32_e32 v34, v2
	v_mov_b32_e32 v35, v2
	v_mov_b32_e32 v36, v2
	v_mov_b32_e32 v37, v2
	v_mov_b32_e32 v38, v2
	v_mov_b32_e32 v39, v2
	v_mov_b32_e32 v40, v2
	v_mov_b32_e32 v41, v2
	v_mov_b32_e32 v50, v2
	v_mov_b32_e32 v51, v2
	v_mov_b32_e32 v52, v2
	v_mov_b32_e32 v53, v2
	v_mov_b32_e32 v54, v2
	v_mov_b32_e32 v55, v2
	v_mov_b32_e32 v56, v2
	v_mov_b32_e32 v57, v2
	v_mov_b32_e32 v10, v2
	v_mov_b32_e32 v11, v2
	v_mov_b32_e32 v12, v2
	v_mov_b32_e32 v13, v2
	v_mov_b32_e32 v14, v2
	v_mov_b32_e32 v15, v2
	v_mov_b32_e32 v16, v2
	v_mov_b32_e32 v17, v2
	v_mov_b32_e32 v26, v2
	v_mov_b32_e32 v27, v2
	v_mov_b32_e32 v28, v2
	v_mov_b32_e32 v29, v2
	v_mov_b32_e32 v30, v2
	v_mov_b32_e32 v31, v2
	v_mov_b32_e32 v32, v2
	v_mov_b32_e32 v33, v2
	v_mov_b32_e32 v42, v2
	v_mov_b32_e32 v43, v2
	v_mov_b32_e32 v44, v2
	v_mov_b32_e32 v45, v2
	v_mov_b32_e32 v46, v2
	v_mov_b32_e32 v47, v2
	v_mov_b32_e32 v48, v2
	v_mov_b32_e32 v49, v2
	v_mov_b32_e32 v58, v2
	v_mov_b32_e32 v59, v2
	v_mov_b32_e32 v60, v2
	v_mov_b32_e32 v61, v2
	v_mov_b32_e32 v62, v2
	v_mov_b32_e32 v63, v2
	v_mov_b32_e32 v64, v2
	v_mov_b32_e32 v65, v2
	v_mov_b32_e32 v66, v2
	v_mov_b32_e32 v67, v2
	v_mov_b32_e32 v68, v2
	v_mov_b32_e32 v69, v2
	v_mov_b32_e32 v70, v2
	v_mov_b32_e32 v71, v2
	v_mov_b32_e32 v72, v2
	v_mov_b32_e32 v73, v2
	v_mov_b32_e32 v82, v2
	v_mov_b32_e32 v83, v2
	v_mov_b32_e32 v84, v2
	v_mov_b32_e32 v85, v2
	v_mov_b32_e32 v86, v2
	v_mov_b32_e32 v87, v2
	v_mov_b32_e32 v88, v2
	v_mov_b32_e32 v89, v2
	v_mov_b32_e32 v98, v2
	v_mov_b32_e32 v99, v2
	v_mov_b32_e32 v100, v2
	v_mov_b32_e32 v101, v2
	v_mov_b32_e32 v102, v2
	v_mov_b32_e32 v103, v2
	v_mov_b32_e32 v104, v2
	v_mov_b32_e32 v105, v2
	v_mov_b32_e32 v114, v2
	v_mov_b32_e32 v115, v2
	v_mov_b32_e32 v116, v2
	v_mov_b32_e32 v117, v2
	v_mov_b32_e32 v118, v2
	v_mov_b32_e32 v119, v2
	v_mov_b32_e32 v120, v2
	v_mov_b32_e32 v121, v2
	v_mov_b32_e32 v74, v2
	v_mov_b32_e32 v75, v2
	v_mov_b32_e32 v76, v2
	v_mov_b32_e32 v77, v2
	v_mov_b32_e32 v78, v2
	v_mov_b32_e32 v79, v2
	v_mov_b32_e32 v80, v2
	v_mov_b32_e32 v81, v2
	v_mov_b32_e32 v90, v2
	v_mov_b32_e32 v91, v2
	v_mov_b32_e32 v92, v2
	v_mov_b32_e32 v93, v2
	v_mov_b32_e32 v94, v2
	v_mov_b32_e32 v95, v2
	v_mov_b32_e32 v96, v2
	v_mov_b32_e32 v97, v2
	v_mov_b32_e32 v106, v2
	v_mov_b32_e32 v107, v2
	v_mov_b32_e32 v108, v2
	v_mov_b32_e32 v109, v2
	v_mov_b32_e32 v110, v2
	v_mov_b32_e32 v111, v2
	v_mov_b32_e32 v112, v2
	v_mov_b32_e32 v113, v2
	v_mov_b32_e32 v122, v2
	v_mov_b32_e32 v123, v2
	v_mov_b32_e32 v124, v2
	v_mov_b32_e32 v125, v2
	v_mov_b32_e32 v126, v2
	v_mov_b32_e32 v127, v2
	v_mov_b32_e32 v128, v2
	v_mov_b32_e32 v129, v2
	s_andn2_b64 vcc, exec, s[2:3]
	s_cbranch_vccnz .LBB0_1790
	s_branch .LBB0_1791

.LBB0_1905:
	ds_read_b128 v[148:151], v165
	ds_read_b128 v[152:155], v165 offset:1024
	ds_read_b128 v[156:159], v165 offset:2048
	ds_read_b128 v[160:163], v165 offset:3072
	ds_read_b128 v[170:173], v166
	ds_read_b128 v[174:177], v166 offset:1024
	ds_read_b128 v[178:181], v166 offset:2048
	ds_read_b128 v[182:185], v166 offset:3072
	s_add_u32 s28, s58, 0xfffc0080
	s_addc_u32 s29, s59, -1
	s_cmp_eq_u32 s74, 12
	s_cselect_b32 s31, s51, s29
	s_cselect_b32 s30, s60, s28
	s_cselect_b32 s29, s49, s73
	s_cselect_b32 s28, s61, s72
	s_add_i32 m0, s33, 0xc000
	ds_read_b128 v[186:189], v167
	ds_read_b128 v[190:193], v167 offset:1024
	ds_read_b128 v[194:197], v167 offset:2048
	ds_read_b128 v[198:201], v167 offset:3072
	ds_read_b128 v[202:205], v167 offset:4096
	ds_read_b128 v[206:209], v167 offset:5120
	ds_read_b128 v[210:213], v167 offset:6144
	ds_read_b128 v[214:217], v167 offset:7168
	global_load_lds_dwordx4 v140, s[58:59]
	s_add_i32 m0, s33, 0xe000
	s_nop 0
	global_load_lds_dwordx4 v142, s[58:59]
	s_waitcnt vmcnt(8)
	s_waitcnt lgkmcnt(0)
	s_barrier
	s_setprio 1
	s_waitcnt lgkmcnt(0)
	v_mfma_f32_16x16x32_bf16 v[126:129], v[148:151], v[186:189], v[126:129]
	v_mfma_f32_16x16x32_bf16 v[118:121], v[156:159], v[186:189], v[118:121]
	v_mfma_f32_16x16x32_bf16 v[110:113], v[148:151], v[194:197], v[110:113]
	v_mfma_f32_16x16x32_bf16 v[102:105], v[156:159], v[194:197], v[102:105]
	v_mfma_f32_16x16x32_bf16 v[94:97], v[148:151], v[202:205], v[94:97]
	v_mfma_f32_16x16x32_bf16 v[86:89], v[156:159], v[202:205], v[86:89]
	v_mfma_f32_16x16x32_bf16 v[78:81], v[148:151], v[210:213], v[78:81]
	v_mfma_f32_16x16x32_bf16 v[70:73], v[156:159], v[210:213], v[70:73]
	v_mfma_f32_16x16x32_bf16 v[126:129], v[152:155], v[190:193], v[126:129]
	v_mfma_f32_16x16x32_bf16 v[118:121], v[160:163], v[190:193], v[118:121]
	v_mfma_f32_16x16x32_bf16 v[110:113], v[152:155], v[198:201], v[110:113]
	v_mfma_f32_16x16x32_bf16 v[102:105], v[160:163], v[198:201], v[102:105]
	v_mfma_f32_16x16x32_bf16 v[94:97], v[152:155], v[206:209], v[94:97]
	v_mfma_f32_16x16x32_bf16 v[86:89], v[160:163], v[206:209], v[86:89]
	v_mfma_f32_16x16x32_bf16 v[78:81], v[152:155], v[214:217], v[78:81]
	v_mfma_f32_16x16x32_bf16 v[70:73], v[160:163], v[214:217], v[70:73]
	s_setprio 0
	s_setprio 1
	v_mfma_f32_16x16x32_bf16 v[122:125], v[170:173], v[186:189], v[122:125]
	v_mfma_f32_16x16x32_bf16 v[114:117], v[178:181], v[186:189], v[114:117]
	v_mfma_f32_16x16x32_bf16 v[106:109], v[170:173], v[194:197], v[106:109]
	v_mfma_f32_16x16x32_bf16 v[98:101], v[178:181], v[194:197], v[98:101]
	v_mfma_f32_16x16x32_bf16 v[90:93], v[170:173], v[202:205], v[90:93]
	v_mfma_f32_16x16x32_bf16 v[82:85], v[178:181], v[202:205], v[82:85]
	v_mfma_f32_16x16x32_bf16 v[74:77], v[170:173], v[210:213], v[74:77]
	v_mfma_f32_16x16x32_bf16 v[66:69], v[178:181], v[210:213], v[66:69]
	v_mfma_f32_16x16x32_bf16 v[122:125], v[174:177], v[190:193], v[122:125]
	v_mfma_f32_16x16x32_bf16 v[114:117], v[182:185], v[190:193], v[114:117]
	v_mfma_f32_16x16x32_bf16 v[106:109], v[174:177], v[198:201], v[106:109]
	v_mfma_f32_16x16x32_bf16 v[98:101], v[182:185], v[198:201], v[98:101]
	v_mfma_f32_16x16x32_bf16 v[90:93], v[174:177], v[206:209], v[90:93]
	v_mfma_f32_16x16x32_bf16 v[82:85], v[182:185], v[206:209], v[82:85]
	v_mfma_f32_16x16x32_bf16 v[74:77], v[174:177], v[214:217], v[74:77]
	v_mfma_f32_16x16x32_bf16 v[66:69], v[182:185], v[214:217], v[66:69]
	s_setprio 0
	s_barrier
	s_add_i32 s75, s67, s23
	s_mov_b32 m0, s75
	ds_read_b128 v[186:189], v167 offset:16384
	ds_read_b128 v[190:193], v167 offset:17408
	ds_read_b128 v[194:197], v167 offset:18432
	ds_read_b128 v[198:201], v167 offset:19456
	ds_read_b128 v[202:205], v167 offset:20480
	ds_read_b128 v[206:209], v167 offset:21504
	ds_read_b128 v[210:213], v167 offset:22528
	ds_read_b128 v[214:217], v167 offset:23552
	global_load_lds_dwordx4 v132, s[28:29]
	s_add_i32 m0, s75, 0x2000
	s_add_u32 s76, s28, 0x40000
	s_addc_u32 s77, s29, 0
	s_add_i32 s75, s68, s23
	global_load_lds_dwordx4 v136, s[28:29]
	s_mov_b32 m0, s75
	s_nop 0
	global_load_lds_dwordx4 v132, s[76:77]
	s_add_i32 m0, s75, 0x2000
	s_nop 0
	global_load_lds_dwordx4 v136, s[76:77]
	s_mov_b32 m0, s33
	s_nop 0
	global_load_lds_dwordx4 v130, s[30:31]
	s_mov_b32 m0, s34
	s_nop 0
	global_load_lds_dwordx4 v134, s[30:31]
	s_waitcnt vmcnt(8)
	s_waitcnt lgkmcnt(0)
	s_barrier
	s_setprio 1
	s_waitcnt lgkmcnt(0)
	v_mfma_f32_16x16x32_bf16 v[62:65], v[148:151], v[186:189], v[62:65]
	v_mfma_f32_16x16x32_bf16 v[54:57], v[156:159], v[186:189], v[54:57]
	v_mfma_f32_16x16x32_bf16 v[46:49], v[148:151], v[194:197], v[46:49]
	v_mfma_f32_16x16x32_bf16 v[38:41], v[156:159], v[194:197], v[38:41]
	v_mfma_f32_16x16x32_bf16 v[30:33], v[148:151], v[202:205], v[30:33]
	v_mfma_f32_16x16x32_bf16 v[22:25], v[156:159], v[202:205], v[22:25]
	v_mfma_f32_16x16x32_bf16 v[14:17], v[148:151], v[210:213], v[14:17]
	v_mfma_f32_16x16x32_bf16 v[6:9], v[156:159], v[210:213], v[6:9]
	v_mfma_f32_16x16x32_bf16 v[62:65], v[152:155], v[190:193], v[62:65]
	v_mfma_f32_16x16x32_bf16 v[54:57], v[160:163], v[190:193], v[54:57]
	v_mfma_f32_16x16x32_bf16 v[46:49], v[152:155], v[198:201], v[46:49]
	v_mfma_f32_16x16x32_bf16 v[38:41], v[160:163], v[198:201], v[38:41]
	v_mfma_f32_16x16x32_bf16 v[30:33], v[152:155], v[206:209], v[30:33]
	v_mfma_f32_16x16x32_bf16 v[22:25], v[160:163], v[206:209], v[22:25]
	v_mfma_f32_16x16x32_bf16 v[14:17], v[152:155], v[214:217], v[14:17]
	v_mfma_f32_16x16x32_bf16 v[6:9], v[160:163], v[214:217], v[6:9]
	s_setprio 0
	s_setprio 1
	v_mfma_f32_16x16x32_bf16 v[58:61], v[170:173], v[186:189], v[58:61]
	v_mfma_f32_16x16x32_bf16 v[50:53], v[178:181], v[186:189], v[50:53]
	v_mfma_f32_16x16x32_bf16 v[42:45], v[170:173], v[194:197], v[42:45]
	v_mfma_f32_16x16x32_bf16 v[34:37], v[178:181], v[194:197], v[34:37]
	v_mfma_f32_16x16x32_bf16 v[26:29], v[170:173], v[202:205], v[26:29]
	v_mfma_f32_16x16x32_bf16 v[18:21], v[178:181], v[202:205], v[18:21]
	v_mfma_f32_16x16x32_bf16 v[10:13], v[170:173], v[210:213], v[10:13]
	v_mfma_f32_16x16x32_bf16 v[2:5], v[178:181], v[210:213], v[2:5]
	v_mfma_f32_16x16x32_bf16 v[58:61], v[174:177], v[190:193], v[58:61]
	v_mfma_f32_16x16x32_bf16 v[50:53], v[182:185], v[190:193], v[50:53]
	v_mfma_f32_16x16x32_bf16 v[42:45], v[174:177], v[198:201], v[42:45]
	v_mfma_f32_16x16x32_bf16 v[34:37], v[182:185], v[198:201], v[34:37]
	v_mfma_f32_16x16x32_bf16 v[26:29], v[174:177], v[206:209], v[26:29]
	v_mfma_f32_16x16x32_bf16 v[18:21], v[182:185], v[206:209], v[18:21]
	v_mfma_f32_16x16x32_bf16 v[10:13], v[174:177], v[214:217], v[10:13]
	v_mfma_f32_16x16x32_bf16 v[2:5], v[182:185], v[214:217], v[2:5]
	s_setprio 0
	s_barrier
	s_add_i32 s75, 0, 0x18000
	s_add_i32 s76, 0, 0x1c000
	v_add_u32_e32 v160, s75, v139
	v_add_u32_e32 v169, s76, v139
	ds_read_b128 v[148:151], v160
	ds_read_b128 v[152:155], v160 offset:1024
	ds_read_b128 v[156:159], v160 offset:2048
	ds_read_b128 v[160:163], v160 offset:3072
	ds_read_b128 v[170:173], v169
	ds_read_b128 v[174:177], v169 offset:1024
	ds_read_b128 v[178:181], v169 offset:2048
	ds_read_b128 v[182:185], v169 offset:3072
	s_add_u32 s98, s30, 0x40000
	s_addc_u32 s99, s31, 0
	s_mov_b32 m0, s35
	ds_read_b128 v[186:189], v167 offset:32768
	ds_read_b128 v[190:193], v167 offset:33792
	ds_read_b128 v[194:197], v167 offset:34816
	ds_read_b128 v[198:201], v167 offset:35840
	ds_read_b128 v[202:205], v167 offset:36864
	ds_read_b128 v[206:209], v167 offset:37888
	ds_read_b128 v[210:213], v167 offset:38912
	ds_read_b128 v[214:217], v167 offset:39936
	global_load_lds_dwordx4 v130, s[98:99]
	s_mov_b32 m0, s57
	s_nop 0
	global_load_lds_dwordx4 v134, s[98:99]
	s_waitcnt vmcnt(8)
	s_waitcnt lgkmcnt(0)
	s_barrier
	s_setprio 1
	s_waitcnt lgkmcnt(0)
	v_mfma_f32_16x16x32_bf16 v[126:129], v[148:151], v[186:189], v[126:129]
	v_mfma_f32_16x16x32_bf16 v[118:121], v[156:159], v[186:189], v[118:121]
	v_mfma_f32_16x16x32_bf16 v[110:113], v[148:151], v[194:197], v[110:113]
	v_mfma_f32_16x16x32_bf16 v[102:105], v[156:159], v[194:197], v[102:105]
	v_mfma_f32_16x16x32_bf16 v[94:97], v[148:151], v[202:205], v[94:97]
	v_mfma_f32_16x16x32_bf16 v[86:89], v[156:159], v[202:205], v[86:89]
	v_mfma_f32_16x16x32_bf16 v[78:81], v[148:151], v[210:213], v[78:81]
	v_mfma_f32_16x16x32_bf16 v[70:73], v[156:159], v[210:213], v[70:73]
	v_mfma_f32_16x16x32_bf16 v[126:129], v[152:155], v[190:193], v[126:129]
	v_mfma_f32_16x16x32_bf16 v[118:121], v[160:163], v[190:193], v[118:121]
	v_mfma_f32_16x16x32_bf16 v[110:113], v[152:155], v[198:201], v[110:113]
	v_mfma_f32_16x16x32_bf16 v[102:105], v[160:163], v[198:201], v[102:105]
	v_mfma_f32_16x16x32_bf16 v[94:97], v[152:155], v[206:209], v[94:97]
	v_mfma_f32_16x16x32_bf16 v[86:89], v[160:163], v[206:209], v[86:89]
	v_mfma_f32_16x16x32_bf16 v[78:81], v[152:155], v[214:217], v[78:81]
	v_mfma_f32_16x16x32_bf16 v[70:73], v[160:163], v[214:217], v[70:73]
	s_setprio 0
	s_setprio 1
	v_mfma_f32_16x16x32_bf16 v[122:125], v[170:173], v[186:189], v[122:125]
	v_mfma_f32_16x16x32_bf16 v[114:117], v[178:181], v[186:189], v[114:117]
	v_mfma_f32_16x16x32_bf16 v[106:109], v[170:173], v[194:197], v[106:109]
	v_mfma_f32_16x16x32_bf16 v[98:101], v[178:181], v[194:197], v[98:101]
	v_mfma_f32_16x16x32_bf16 v[90:93], v[170:173], v[202:205], v[90:93]
	v_mfma_f32_16x16x32_bf16 v[82:85], v[178:181], v[202:205], v[82:85]
	v_mfma_f32_16x16x32_bf16 v[74:77], v[170:173], v[210:213], v[74:77]
	v_mfma_f32_16x16x32_bf16 v[66:69], v[178:181], v[210:213], v[66:69]
	v_mfma_f32_16x16x32_bf16 v[122:125], v[174:177], v[190:193], v[122:125]
	v_mfma_f32_16x16x32_bf16 v[114:117], v[182:185], v[190:193], v[114:117]
	v_mfma_f32_16x16x32_bf16 v[106:109], v[174:177], v[198:201], v[106:109]
	v_mfma_f32_16x16x32_bf16 v[98:101], v[182:185], v[198:201], v[98:101]
	v_mfma_f32_16x16x32_bf16 v[90:93], v[174:177], v[206:209], v[90:93]
	v_mfma_f32_16x16x32_bf16 v[82:85], v[182:185], v[206:209], v[82:85]
	v_mfma_f32_16x16x32_bf16 v[74:77], v[174:177], v[214:217], v[74:77]
	v_mfma_f32_16x16x32_bf16 v[66:69], v[182:185], v[214:217], v[66:69]
	s_setprio 0
	s_barrier
	s_add_i32 s98, s75, s23
	s_add_i32 m0, s98, 0xffffff80
	ds_read_b128 v[186:189], v167 offset:49152
	ds_read_b128 v[190:193], v167 offset:50176
	ds_read_b128 v[194:197], v167 offset:51200
	ds_read_b128 v[198:201], v167 offset:52224
	ds_read_b128 v[202:205], v167 offset:53248
	ds_read_b128 v[206:209], v167 offset:54272
	ds_read_b128 v[210:213], v167 offset:55296
	ds_read_b128 v[214:217], v167 offset:56320
	global_load_lds_dwordx4 v132, s[28:29] offset:128
	s_add_i32 m0, s98, 0x1f80
	s_add_i32 s98, s76, s23
	global_load_lds_dwordx4 v136, s[28:29] offset:128
	s_add_u32 s28, s28, 0x40080
	s_addc_u32 s29, s29, 0
	s_mov_b32 m0, s98
	s_nop 0
	global_load_lds_dwordx4 v132, s[28:29]
	s_add_i32 m0, s98, 0x2000
	s_nop 0
	global_load_lds_dwordx4 v136, s[28:29]
	s_add_i32 m0, s62, 0xffffff80
	s_nop 0
	global_load_lds_dwordx4 v130, s[30:31] offset:128
	s_add_i32 m0, s63, 0xffffff80
	s_nop 0
	global_load_lds_dwordx4 v134, s[30:31] offset:128
	s_waitcnt vmcnt(8)
	s_waitcnt lgkmcnt(0)
	s_barrier
	s_setprio 1
	s_waitcnt lgkmcnt(0)
	v_mfma_f32_16x16x32_bf16 v[62:65], v[148:151], v[186:189], v[62:65]
	v_mfma_f32_16x16x32_bf16 v[54:57], v[156:159], v[186:189], v[54:57]
	v_mfma_f32_16x16x32_bf16 v[46:49], v[148:151], v[194:197], v[46:49]
	v_mfma_f32_16x16x32_bf16 v[38:41], v[156:159], v[194:197], v[38:41]
	v_mfma_f32_16x16x32_bf16 v[30:33], v[148:151], v[202:205], v[30:33]
	v_mfma_f32_16x16x32_bf16 v[22:25], v[156:159], v[202:205], v[22:25]
	v_mfma_f32_16x16x32_bf16 v[14:17], v[148:151], v[210:213], v[14:17]
	v_mfma_f32_16x16x32_bf16 v[6:9], v[156:159], v[210:213], v[6:9]
	v_mfma_f32_16x16x32_bf16 v[62:65], v[152:155], v[190:193], v[62:65]
	v_mfma_f32_16x16x32_bf16 v[54:57], v[160:163], v[190:193], v[54:57]
	v_mfma_f32_16x16x32_bf16 v[46:49], v[152:155], v[198:201], v[46:49]
	v_mfma_f32_16x16x32_bf16 v[38:41], v[160:163], v[198:201], v[38:41]
	v_mfma_f32_16x16x32_bf16 v[30:33], v[152:155], v[206:209], v[30:33]
	v_mfma_f32_16x16x32_bf16 v[22:25], v[160:163], v[206:209], v[22:25]
	v_mfma_f32_16x16x32_bf16 v[14:17], v[152:155], v[214:217], v[14:17]
	v_mfma_f32_16x16x32_bf16 v[6:9], v[160:163], v[214:217], v[6:9]
	s_setprio 0
	s_setprio 1
	v_mfma_f32_16x16x32_bf16 v[58:61], v[170:173], v[186:189], v[58:61]
	v_mfma_f32_16x16x32_bf16 v[50:53], v[178:181], v[186:189], v[50:53]
	v_mfma_f32_16x16x32_bf16 v[42:45], v[170:173], v[194:197], v[42:45]
	v_mfma_f32_16x16x32_bf16 v[34:37], v[178:181], v[194:197], v[34:37]
	v_mfma_f32_16x16x32_bf16 v[26:29], v[170:173], v[202:205], v[26:29]
	v_mfma_f32_16x16x32_bf16 v[18:21], v[178:181], v[202:205], v[18:21]
	v_mfma_f32_16x16x32_bf16 v[10:13], v[170:173], v[210:213], v[10:13]
	v_mfma_f32_16x16x32_bf16 v[2:5], v[178:181], v[210:213], v[2:5]
	v_mfma_f32_16x16x32_bf16 v[58:61], v[174:177], v[190:193], v[58:61]
	v_mfma_f32_16x16x32_bf16 v[50:53], v[182:185], v[190:193], v[50:53]
	v_mfma_f32_16x16x32_bf16 v[42:45], v[174:177], v[198:201], v[42:45]
	v_mfma_f32_16x16x32_bf16 v[34:37], v[182:185], v[198:201], v[34:37]
	v_mfma_f32_16x16x32_bf16 v[26:29], v[174:177], v[206:209], v[26:29]
	v_mfma_f32_16x16x32_bf16 v[18:21], v[182:185], v[206:209], v[18:21]
	v_mfma_f32_16x16x32_bf16 v[10:13], v[174:177], v[214:217], v[10:13]
	v_mfma_f32_16x16x32_bf16 v[2:5], v[182:185], v[214:217], v[2:5]
	s_setprio 0
	s_barrier
	s_add_i32 s74, s74, 2
	s_add_u32 s58, s58, 0x100
	s_addc_u32 s59, s59, 0
	s_add_u32 s72, s72, 0x100
	s_addc_u32 s73, s73, 0
	s_cmp_gt_u32 s74, 13
	s_cbranch_scc0 .LBB0_1905
	s_and_b64 vcc, exec, s[42:43]
	s_cbranch_vccz .LBB0_1908
	s_barrier

.LBB0_2031:
	v_add_u32_e32 v155, s48, v153
	ds_read_b128 v[156:159], v155
	ds_read_b128 v[160:163], v155 offset:1024
	ds_read_b128 v[164:167], v155 offset:2048
	ds_read_b128 v[168:171], v155 offset:3072
	v_add_u32_e32 v155, s49, v153
	s_add_u32 s28, s12, s20
	ds_read_b128 v[172:175], v155
	ds_read_b128 v[176:179], v155 offset:1024
	ds_read_b128 v[180:183], v155 offset:2048
	ds_read_b128 v[184:187], v155 offset:3072
	s_addc_u32 s29, s13, s21
	s_add_u32 s28, s28, 0x100
	s_addc_u32 s29, s29, 0
	s_add_u32 s54, s17, s20
	s_addc_u32 s55, s52, s21
	s_cmpk_eq_i32 s20, 0x1500
	s_cselect_b32 s31, s19, s29
	s_cselect_b32 s30, s18, s28
	s_cselect_b32 s29, s1, s55
	s_cselect_b32 s28, s0, s54
	v_lshl_add_u64 v[220:221], v[148:149], 0, s[20:21]
	s_add_i32 m0, s41, 0xc000
	ds_read_b128 v[188:191], v154
	ds_read_b128 v[192:195], v154 offset:1024
	ds_read_b128 v[196:199], v154 offset:2048
	ds_read_b128 v[200:203], v154 offset:3072
	ds_read_b128 v[204:207], v154 offset:4096
	ds_read_b128 v[208:211], v154 offset:5120
	ds_read_b128 v[212:215], v154 offset:6144
	ds_read_b128 v[216:219], v154 offset:7168
	global_load_lds_dwordx4 v[220:221], off
	v_lshl_add_u64 v[220:221], v[150:151], 0, s[20:21]
	s_add_i32 m0, s41, 0xe000
	s_nop 0
	global_load_lds_dwordx4 v[220:221], off
	s_waitcnt vmcnt(8)
	s_waitcnt lgkmcnt(0)
	s_barrier
	s_setprio 1
	s_waitcnt lgkmcnt(0)
	v_mfma_f32_16x16x32_bf16 v[126:129], v[156:159], v[188:191], v[126:129]
	v_mfma_f32_16x16x32_bf16 v[122:125], v[164:167], v[188:191], v[122:125]
	v_mfma_f32_16x16x32_bf16 v[110:113], v[156:159], v[196:199], v[110:113]
	v_mfma_f32_16x16x32_bf16 v[106:109], v[164:167], v[196:199], v[106:109]
	v_mfma_f32_16x16x32_bf16 v[94:97], v[156:159], v[204:207], v[94:97]
	v_mfma_f32_16x16x32_bf16 v[90:93], v[164:167], v[204:207], v[90:93]
	v_mfma_f32_16x16x32_bf16 v[78:81], v[156:159], v[212:215], v[78:81]
	v_mfma_f32_16x16x32_bf16 v[74:77], v[164:167], v[212:215], v[74:77]
	v_mfma_f32_16x16x32_bf16 v[126:129], v[160:163], v[192:195], v[126:129]
	v_mfma_f32_16x16x32_bf16 v[122:125], v[168:171], v[192:195], v[122:125]
	v_mfma_f32_16x16x32_bf16 v[110:113], v[160:163], v[200:203], v[110:113]
	v_mfma_f32_16x16x32_bf16 v[106:109], v[168:171], v[200:203], v[106:109]
	v_mfma_f32_16x16x32_bf16 v[94:97], v[160:163], v[208:211], v[94:97]
	v_mfma_f32_16x16x32_bf16 v[90:93], v[168:171], v[208:211], v[90:93]
	v_mfma_f32_16x16x32_bf16 v[78:81], v[160:163], v[216:219], v[78:81]
	v_mfma_f32_16x16x32_bf16 v[74:77], v[168:171], v[216:219], v[74:77]
	s_setprio 0
	s_setprio 1
	v_mfma_f32_16x16x32_bf16 v[118:121], v[172:175], v[188:191], v[118:121]
	v_mfma_f32_16x16x32_bf16 v[114:117], v[180:183], v[188:191], v[114:117]
	v_mfma_f32_16x16x32_bf16 v[102:105], v[172:175], v[196:199], v[102:105]
	v_mfma_f32_16x16x32_bf16 v[98:101], v[180:183], v[196:199], v[98:101]
	v_mfma_f32_16x16x32_bf16 v[86:89], v[172:175], v[204:207], v[86:89]
	v_mfma_f32_16x16x32_bf16 v[82:85], v[180:183], v[204:207], v[82:85]
	v_mfma_f32_16x16x32_bf16 v[70:73], v[172:175], v[212:215], v[70:73]
	v_mfma_f32_16x16x32_bf16 v[66:69], v[180:183], v[212:215], v[66:69]
	v_mfma_f32_16x16x32_bf16 v[118:121], v[176:179], v[192:195], v[118:121]
	v_mfma_f32_16x16x32_bf16 v[114:117], v[184:187], v[192:195], v[114:117]
	v_mfma_f32_16x16x32_bf16 v[102:105], v[176:179], v[200:203], v[102:105]
	v_mfma_f32_16x16x32_bf16 v[98:101], v[184:187], v[200:203], v[98:101]
	v_mfma_f32_16x16x32_bf16 v[86:89], v[176:179], v[208:211], v[86:89]
	v_mfma_f32_16x16x32_bf16 v[82:85], v[184:187], v[208:211], v[82:85]
	v_mfma_f32_16x16x32_bf16 v[70:73], v[176:179], v[216:219], v[70:73]
	v_mfma_f32_16x16x32_bf16 v[66:69], v[184:187], v[216:219], v[66:69]
	s_setprio 0
	s_barrier
	s_add_i32 s54, s48, s35
	s_mov_b32 m0, s54
	ds_read_b128 v[188:191], v154 offset:16384
	ds_read_b128 v[192:195], v154 offset:17408
	ds_read_b128 v[196:199], v154 offset:18432
	ds_read_b128 v[200:203], v154 offset:19456
	ds_read_b128 v[204:207], v154 offset:20480
	ds_read_b128 v[208:211], v154 offset:21504
	ds_read_b128 v[212:215], v154 offset:22528
	ds_read_b128 v[216:219], v154 offset:23552
	global_load_lds_dwordx4 v132, s[28:29]
	s_add_i32 m0, s54, 0x2000
	s_add_u32 s54, s28, 0xb0000
	s_addc_u32 s55, s29, 0
	s_add_i32 s56, s49, s35
	global_load_lds_dwordx4 v136, s[28:29]
	s_mov_b32 m0, s56
	s_nop 0
	global_load_lds_dwordx4 v132, s[54:55]
	s_add_i32 m0, s56, 0x2000
	s_nop 0
	global_load_lds_dwordx4 v136, s[54:55]
	s_mov_b32 m0, s41
	s_nop 0
	global_load_lds_dwordx4 v130, s[30:31]
	s_mov_b32 m0, s42
	s_nop 0
	global_load_lds_dwordx4 v134, s[30:31]
	s_waitcnt vmcnt(8)
	s_waitcnt lgkmcnt(0)
	s_barrier
	s_setprio 1
	s_waitcnt lgkmcnt(0)
	v_mfma_f32_16x16x32_bf16 v[62:65], v[156:159], v[188:191], v[62:65]
	v_mfma_f32_16x16x32_bf16 v[58:61], v[164:167], v[188:191], v[58:61]
	v_mfma_f32_16x16x32_bf16 v[46:49], v[156:159], v[196:199], v[46:49]
	v_mfma_f32_16x16x32_bf16 v[42:45], v[164:167], v[196:199], v[42:45]
	v_mfma_f32_16x16x32_bf16 v[30:33], v[156:159], v[204:207], v[30:33]
	v_mfma_f32_16x16x32_bf16 v[26:29], v[164:167], v[204:207], v[26:29]
	v_mfma_f32_16x16x32_bf16 v[14:17], v[156:159], v[212:215], v[14:17]
	v_mfma_f32_16x16x32_bf16 v[10:13], v[164:167], v[212:215], v[10:13]
	v_mfma_f32_16x16x32_bf16 v[62:65], v[160:163], v[192:195], v[62:65]
	v_mfma_f32_16x16x32_bf16 v[58:61], v[168:171], v[192:195], v[58:61]
	v_mfma_f32_16x16x32_bf16 v[46:49], v[160:163], v[200:203], v[46:49]
	v_mfma_f32_16x16x32_bf16 v[42:45], v[168:171], v[200:203], v[42:45]
	v_mfma_f32_16x16x32_bf16 v[30:33], v[160:163], v[208:211], v[30:33]
	v_mfma_f32_16x16x32_bf16 v[26:29], v[168:171], v[208:211], v[26:29]
	v_mfma_f32_16x16x32_bf16 v[14:17], v[160:163], v[216:219], v[14:17]
	v_mfma_f32_16x16x32_bf16 v[10:13], v[168:171], v[216:219], v[10:13]
	s_setprio 0
	s_setprio 1
	v_mfma_f32_16x16x32_bf16 v[54:57], v[172:175], v[188:191], v[54:57]
	v_mfma_f32_16x16x32_bf16 v[50:53], v[180:183], v[188:191], v[50:53]
	v_mfma_f32_16x16x32_bf16 v[38:41], v[172:175], v[196:199], v[38:41]
	v_mfma_f32_16x16x32_bf16 v[34:37], v[180:183], v[196:199], v[34:37]
	v_mfma_f32_16x16x32_bf16 v[22:25], v[172:175], v[204:207], v[22:25]
	v_mfma_f32_16x16x32_bf16 v[18:21], v[180:183], v[204:207], v[18:21]
	v_mfma_f32_16x16x32_bf16 v[6:9], v[172:175], v[212:215], v[6:9]
	v_mfma_f32_16x16x32_bf16 v[2:5], v[180:183], v[212:215], v[2:5]
	v_mfma_f32_16x16x32_bf16 v[54:57], v[176:179], v[192:195], v[54:57]
	v_mfma_f32_16x16x32_bf16 v[50:53], v[184:187], v[192:195], v[50:53]
	v_mfma_f32_16x16x32_bf16 v[38:41], v[176:179], v[200:203], v[38:41]
	v_mfma_f32_16x16x32_bf16 v[34:37], v[184:187], v[200:203], v[34:37]
	v_mfma_f32_16x16x32_bf16 v[22:25], v[176:179], v[208:211], v[22:25]
	v_mfma_f32_16x16x32_bf16 v[18:21], v[184:187], v[208:211], v[18:21]
	v_mfma_f32_16x16x32_bf16 v[6:9], v[176:179], v[216:219], v[6:9]
	v_mfma_f32_16x16x32_bf16 v[2:5], v[184:187], v[216:219], v[2:5]
	s_setprio 0
	s_barrier
	s_add_i32 s54, 0, 0x18000
	v_add_u32_e32 v155, s54, v153
	s_add_i32 s55, 0, 0x1c000
	ds_read_b128 v[156:159], v155
	ds_read_b128 v[160:163], v155 offset:1024
	ds_read_b128 v[164:167], v155 offset:2048
	ds_read_b128 v[168:171], v155 offset:3072
	v_add_u32_e32 v155, s55, v153
	ds_read_b128 v[172:175], v155
	ds_read_b128 v[176:179], v155 offset:1024
	ds_read_b128 v[180:183], v155 offset:2048
	ds_read_b128 v[184:187], v155 offset:3072
	s_add_u32 s98, s30, 0xb0000
	s_addc_u32 s99, s31, 0
	s_mov_b32 m0, s43
	ds_read_b128 v[188:191], v154 offset:32768
	ds_read_b128 v[192:195], v154 offset:33792
	ds_read_b128 v[196:199], v154 offset:34816
	ds_read_b128 v[200:203], v154 offset:35840
	ds_read_b128 v[204:207], v154 offset:36864
	ds_read_b128 v[208:211], v154 offset:37888
	ds_read_b128 v[212:215], v154 offset:38912
	ds_read_b128 v[216:219], v154 offset:39936
	global_load_lds_dwordx4 v130, s[98:99]
	s_mov_b32 m0, s44
	s_nop 0
	global_load_lds_dwordx4 v134, s[98:99]
	s_waitcnt vmcnt(8)
	s_waitcnt lgkmcnt(0)
	s_barrier
	s_setprio 1
	s_waitcnt lgkmcnt(0)
	v_mfma_f32_16x16x32_bf16 v[126:129], v[156:159], v[188:191], v[126:129]
	v_mfma_f32_16x16x32_bf16 v[122:125], v[164:167], v[188:191], v[122:125]
	v_mfma_f32_16x16x32_bf16 v[110:113], v[156:159], v[196:199], v[110:113]
	v_mfma_f32_16x16x32_bf16 v[106:109], v[164:167], v[196:199], v[106:109]
	v_mfma_f32_16x16x32_bf16 v[94:97], v[156:159], v[204:207], v[94:97]
	v_mfma_f32_16x16x32_bf16 v[90:93], v[164:167], v[204:207], v[90:93]
	v_mfma_f32_16x16x32_bf16 v[78:81], v[156:159], v[212:215], v[78:81]
	v_mfma_f32_16x16x32_bf16 v[74:77], v[164:167], v[212:215], v[74:77]
	v_mfma_f32_16x16x32_bf16 v[126:129], v[160:163], v[192:195], v[126:129]
	v_mfma_f32_16x16x32_bf16 v[122:125], v[168:171], v[192:195], v[122:125]
	v_mfma_f32_16x16x32_bf16 v[110:113], v[160:163], v[200:203], v[110:113]
	v_mfma_f32_16x16x32_bf16 v[106:109], v[168:171], v[200:203], v[106:109]
	v_mfma_f32_16x16x32_bf16 v[94:97], v[160:163], v[208:211], v[94:97]
	v_mfma_f32_16x16x32_bf16 v[90:93], v[168:171], v[208:211], v[90:93]
	v_mfma_f32_16x16x32_bf16 v[78:81], v[160:163], v[216:219], v[78:81]
	v_mfma_f32_16x16x32_bf16 v[74:77], v[168:171], v[216:219], v[74:77]
	s_setprio 0
	s_setprio 1
	v_mfma_f32_16x16x32_bf16 v[118:121], v[172:175], v[188:191], v[118:121]
	v_mfma_f32_16x16x32_bf16 v[114:117], v[180:183], v[188:191], v[114:117]
	v_mfma_f32_16x16x32_bf16 v[102:105], v[172:175], v[196:199], v[102:105]
	v_mfma_f32_16x16x32_bf16 v[98:101], v[180:183], v[196:199], v[98:101]
	v_mfma_f32_16x16x32_bf16 v[86:89], v[172:175], v[204:207], v[86:89]
	v_mfma_f32_16x16x32_bf16 v[82:85], v[180:183], v[204:207], v[82:85]
	v_mfma_f32_16x16x32_bf16 v[70:73], v[172:175], v[212:215], v[70:73]
	v_mfma_f32_16x16x32_bf16 v[66:69], v[180:183], v[212:215], v[66:69]
	v_mfma_f32_16x16x32_bf16 v[118:121], v[176:179], v[192:195], v[118:121]
	v_mfma_f32_16x16x32_bf16 v[114:117], v[184:187], v[192:195], v[114:117]
	v_mfma_f32_16x16x32_bf16 v[102:105], v[176:179], v[200:203], v[102:105]
	v_mfma_f32_16x16x32_bf16 v[98:101], v[184:187], v[200:203], v[98:101]
	v_mfma_f32_16x16x32_bf16 v[86:89], v[176:179], v[208:211], v[86:89]
	v_mfma_f32_16x16x32_bf16 v[82:85], v[184:187], v[208:211], v[82:85]
	v_mfma_f32_16x16x32_bf16 v[70:73], v[176:179], v[216:219], v[70:73]
	v_mfma_f32_16x16x32_bf16 v[66:69], v[184:187], v[216:219], v[66:69]
	s_setprio 0
	s_barrier
	s_add_i32 s98, s54, s35
	s_add_i32 m0, s98, 0xffffff80
	ds_read_b128 v[188:191], v154 offset:49152
	ds_read_b128 v[192:195], v154 offset:50176
	ds_read_b128 v[196:199], v154 offset:51200
	ds_read_b128 v[200:203], v154 offset:52224
	ds_read_b128 v[204:207], v154 offset:53248
	ds_read_b128 v[208:211], v154 offset:54272
	ds_read_b128 v[212:215], v154 offset:55296
	ds_read_b128 v[216:219], v154 offset:56320
	global_load_lds_dwordx4 v132, s[28:29] offset:128
	s_add_i32 m0, s98, 0x1f80
	s_add_i32 s98, s55, s35
	global_load_lds_dwordx4 v136, s[28:29] offset:128
	s_add_u32 s28, s28, 0xb0080
	s_addc_u32 s29, s29, 0
	s_mov_b32 m0, s98
	s_nop 0
	global_load_lds_dwordx4 v132, s[28:29]
	s_add_i32 m0, s98, 0x2000
	s_nop 0
	global_load_lds_dwordx4 v136, s[28:29]
	s_add_i32 m0, s46, 0xffffff80
	s_nop 0
	global_load_lds_dwordx4 v130, s[30:31] offset:128
	s_add_i32 m0, s47, 0xffffff80
	s_nop 0
	global_load_lds_dwordx4 v134, s[30:31] offset:128
	s_waitcnt vmcnt(8)
	s_waitcnt lgkmcnt(0)
	s_barrier
	s_setprio 1
	s_waitcnt lgkmcnt(0)
	v_mfma_f32_16x16x32_bf16 v[62:65], v[156:159], v[188:191], v[62:65]
	v_mfma_f32_16x16x32_bf16 v[58:61], v[164:167], v[188:191], v[58:61]
	v_mfma_f32_16x16x32_bf16 v[46:49], v[156:159], v[196:199], v[46:49]
	v_mfma_f32_16x16x32_bf16 v[42:45], v[164:167], v[196:199], v[42:45]
	v_mfma_f32_16x16x32_bf16 v[30:33], v[156:159], v[204:207], v[30:33]
	v_mfma_f32_16x16x32_bf16 v[26:29], v[164:167], v[204:207], v[26:29]
	v_mfma_f32_16x16x32_bf16 v[14:17], v[156:159], v[212:215], v[14:17]
	v_mfma_f32_16x16x32_bf16 v[10:13], v[164:167], v[212:215], v[10:13]
	v_mfma_f32_16x16x32_bf16 v[62:65], v[160:163], v[192:195], v[62:65]
	v_mfma_f32_16x16x32_bf16 v[58:61], v[168:171], v[192:195], v[58:61]
	v_mfma_f32_16x16x32_bf16 v[46:49], v[160:163], v[200:203], v[46:49]
	v_mfma_f32_16x16x32_bf16 v[42:45], v[168:171], v[200:203], v[42:45]
	v_mfma_f32_16x16x32_bf16 v[30:33], v[160:163], v[208:211], v[30:33]
	v_mfma_f32_16x16x32_bf16 v[26:29], v[168:171], v[208:211], v[26:29]
	v_mfma_f32_16x16x32_bf16 v[14:17], v[160:163], v[216:219], v[14:17]
	v_mfma_f32_16x16x32_bf16 v[10:13], v[168:171], v[216:219], v[10:13]
	s_setprio 0
	s_setprio 1
	v_mfma_f32_16x16x32_bf16 v[54:57], v[172:175], v[188:191], v[54:57]
	v_mfma_f32_16x16x32_bf16 v[50:53], v[180:183], v[188:191], v[50:53]
	v_mfma_f32_16x16x32_bf16 v[38:41], v[172:175], v[196:199], v[38:41]
	v_mfma_f32_16x16x32_bf16 v[34:37], v[180:183], v[196:199], v[34:37]
	v_mfma_f32_16x16x32_bf16 v[22:25], v[172:175], v[204:207], v[22:25]
	v_mfma_f32_16x16x32_bf16 v[18:21], v[180:183], v[204:207], v[18:21]
	v_mfma_f32_16x16x32_bf16 v[6:9], v[172:175], v[212:215], v[6:9]
	v_mfma_f32_16x16x32_bf16 v[2:5], v[180:183], v[212:215], v[2:5]
	v_mfma_f32_16x16x32_bf16 v[54:57], v[176:179], v[192:195], v[54:57]
	v_mfma_f32_16x16x32_bf16 v[50:53], v[184:187], v[192:195], v[50:53]
	v_mfma_f32_16x16x32_bf16 v[38:41], v[176:179], v[200:203], v[38:41]
	v_mfma_f32_16x16x32_bf16 v[34:37], v[184:187], v[200:203], v[34:37]
	v_mfma_f32_16x16x32_bf16 v[22:25], v[176:179], v[208:211], v[22:25]
	v_mfma_f32_16x16x32_bf16 v[18:21], v[184:187], v[208:211], v[18:21]
	v_mfma_f32_16x16x32_bf16 v[6:9], v[176:179], v[216:219], v[6:9]
	v_mfma_f32_16x16x32_bf16 v[2:5], v[184:187], v[216:219], v[2:5]
	s_setprio 0
	s_barrier
	s_add_i32 s53, s53, 2
	s_add_u32 s20, s20, 0x100
	s_addc_u32 s21, s21, 0
	s_cmp_gt_u32 s53, 41
	s_cbranch_scc0 .LBB0_2031
	s_add_u32 s20, s17, 0xffffff00
	s_addc_u32 s21, s52, -1
	s_and_b64 vcc, exec, s[4:5]
	s_cbranch_vccnz .LBB0_2034
	v_mov_b32_e32 v2, 0
	s_mov_b32 s10, s50
	s_mov_b32 s23, s51
	s_mov_b64 s[12:13], s[18:19]
	s_mov_b32 s45, s16
	v_mov_b32_e32 v3, v2
	v_mov_b32_e32 v4, v2
	v_mov_b32_e32 v5, v2
	v_mov_b32_e32 v6, v2
	v_mov_b32_e32 v7, v2
	v_mov_b32_e32 v8, v2
	v_mov_b32_e32 v9, v2
	v_mov_b32_e32 v18, v2
	v_mov_b32_e32 v19, v2
	v_mov_b32_e32 v20, v2
	v_mov_b32_e32 v21, v2
	v_mov_b32_e32 v22, v2
	v_mov_b32_e32 v23, v2
	v_mov_b32_e32 v24, v2
	v_mov_b32_e32 v25, v2
	v_mov_b32_e32 v34, v2
	v_mov_b32_e32 v35, v2
	v_mov_b32_e32 v36, v2
	v_mov_b32_e32 v37, v2
	v_mov_b32_e32 v38, v2
	v_mov_b32_e32 v39, v2
	v_mov_b32_e32 v40, v2
	v_mov_b32_e32 v41, v2
	v_mov_b32_e32 v50, v2
	v_mov_b32_e32 v51, v2
	v_mov_b32_e32 v52, v2
	v_mov_b32_e32 v53, v2
	v_mov_b32_e32 v54, v2
	v_mov_b32_e32 v55, v2
	v_mov_b32_e32 v56, v2
	v_mov_b32_e32 v57, v2
	v_mov_b32_e32 v10, v2
	v_mov_b32_e32 v11, v2
	v_mov_b32_e32 v12, v2
	v_mov_b32_e32 v13, v2
	v_mov_b32_e32 v14, v2
	v_mov_b32_e32 v15, v2
	v_mov_b32_e32 v16, v2
	v_mov_b32_e32 v17, v2
	v_mov_b32_e32 v26, v2
	v_mov_b32_e32 v27, v2
	v_mov_b32_e32 v28, v2
	v_mov_b32_e32 v29, v2
	v_mov_b32_e32 v30, v2
	v_mov_b32_e32 v31, v2
	v_mov_b32_e32 v32, v2
	v_mov_b32_e32 v33, v2
	v_mov_b32_e32 v42, v2
	v_mov_b32_e32 v43, v2
	v_mov_b32_e32 v44, v2
	v_mov_b32_e32 v45, v2
	v_mov_b32_e32 v46, v2
	v_mov_b32_e32 v47, v2
	v_mov_b32_e32 v48, v2
	v_mov_b32_e32 v49, v2
	v_mov_b32_e32 v58, v2
	v_mov_b32_e32 v59, v2
	v_mov_b32_e32 v60, v2
	v_mov_b32_e32 v61, v2
	v_mov_b32_e32 v62, v2
	v_mov_b32_e32 v63, v2
	v_mov_b32_e32 v64, v2
	v_mov_b32_e32 v65, v2
	v_mov_b32_e32 v66, v2
	v_mov_b32_e32 v67, v2
	v_mov_b32_e32 v68, v2
	v_mov_b32_e32 v69, v2
	v_mov_b32_e32 v70, v2
	v_mov_b32_e32 v71, v2
	v_mov_b32_e32 v72, v2
	v_mov_b32_e32 v73, v2
	v_mov_b32_e32 v82, v2
	v_mov_b32_e32 v83, v2
	v_mov_b32_e32 v84, v2
	v_mov_b32_e32 v85, v2
	v_mov_b32_e32 v86, v2
	v_mov_b32_e32 v87, v2
	v_mov_b32_e32 v88, v2
	v_mov_b32_e32 v89, v2
	v_mov_b32_e32 v98, v2
	v_mov_b32_e32 v99, v2
	v_mov_b32_e32 v100, v2
	v_mov_b32_e32 v101, v2
	v_mov_b32_e32 v102, v2
	v_mov_b32_e32 v103, v2
	v_mov_b32_e32 v104, v2
	v_mov_b32_e32 v105, v2
	v_mov_b32_e32 v114, v2
	v_mov_b32_e32 v115, v2
	v_mov_b32_e32 v116, v2
	v_mov_b32_e32 v117, v2
	v_mov_b32_e32 v118, v2
	v_mov_b32_e32 v119, v2
	v_mov_b32_e32 v120, v2
	v_mov_b32_e32 v121, v2
	v_mov_b32_e32 v74, v2
	v_mov_b32_e32 v75, v2
	v_mov_b32_e32 v76, v2
	v_mov_b32_e32 v77, v2
	v_mov_b32_e32 v78, v2
	v_mov_b32_e32 v79, v2
	v_mov_b32_e32 v80, v2
	v_mov_b32_e32 v81, v2
	v_mov_b32_e32 v90, v2
	v_mov_b32_e32 v91, v2
	v_mov_b32_e32 v92, v2
	v_mov_b32_e32 v93, v2
	v_mov_b32_e32 v94, v2
	v_mov_b32_e32 v95, v2
	v_mov_b32_e32 v96, v2
	v_mov_b32_e32 v97, v2
	v_mov_b32_e32 v106, v2
	v_mov_b32_e32 v107, v2
	v_mov_b32_e32 v108, v2
	v_mov_b32_e32 v109, v2
	v_mov_b32_e32 v110, v2
	v_mov_b32_e32 v111, v2
	v_mov_b32_e32 v112, v2
	v_mov_b32_e32 v113, v2
	v_mov_b32_e32 v122, v2
	v_mov_b32_e32 v123, v2
	v_mov_b32_e32 v124, v2
	v_mov_b32_e32 v125, v2
	v_mov_b32_e32 v126, v2
	v_mov_b32_e32 v127, v2
	v_mov_b32_e32 v128, v2
	v_mov_b32_e32 v129, v2
	s_andn2_b64 vcc, exec, s[2:3]
	s_cbranch_vccnz .LBB0_2035
	s_branch .LBB0_2036

.LBB0_2133:
	ds_read_b128 v[154:157], v148
	ds_read_b128 v[158:161], v148 offset:1024
	ds_read_b128 v[162:165], v148 offset:2048
	ds_read_b128 v[166:169], v148 offset:3072
	ds_read_b128 v[170:173], v149
	ds_read_b128 v[174:177], v149 offset:1024
	ds_read_b128 v[178:181], v149 offset:2048
	ds_read_b128 v[182:185], v149 offset:3072
	s_add_u32 s28, s20, 0xfa94fc80
	s_addc_u32 s29, s21, -1
	s_cmp_lg_u32 s46, 32
	s_cselect_b32 s28, s28, 0
	s_cselect_b32 s29, s29, 0
	s_add_u32 s30, s4, s28
	s_addc_u32 s31, s5, s29
	s_add_u32 s28, s2, s28
	s_addc_u32 s29, s3, s29
	s_mov_b32 m0, s47
	v_lshl_add_u64 v[218:219], v[144:145], 0, s[20:21]
	ds_read_b128 v[186:189], v150
	ds_read_b128 v[190:193], v150 offset:1024
	ds_read_b128 v[194:197], v150 offset:2048
	ds_read_b128 v[198:201], v150 offset:3072
	ds_read_b128 v[202:205], v150 offset:4096
	ds_read_b128 v[206:209], v150 offset:5120
	ds_read_b128 v[210:213], v150 offset:6144
	ds_read_b128 v[214:217], v150 offset:7168
	global_load_lds_dwordx4 v[218:219], off
	v_lshl_add_u64 v[218:219], v[146:147], 0, s[20:21]
	s_mov_b32 m0, s48
	s_nop 0
	global_load_lds_dwordx4 v[218:219], off
	s_waitcnt vmcnt(8)
	s_waitcnt lgkmcnt(0)
	s_barrier
	s_setprio 1
	s_waitcnt lgkmcnt(0)
	v_mfma_f32_16x16x32_bf16 v[58:61], v[154:157], v[186:189], v[58:61]
	v_mfma_f32_16x16x32_bf16 v[70:73], v[162:165], v[186:189], v[70:73]
	v_mfma_f32_16x16x32_bf16 v[42:45], v[154:157], v[194:197], v[42:45]
	v_mfma_f32_16x16x32_bf16 v[50:53], v[162:165], v[194:197], v[50:53]
	v_mfma_f32_16x16x32_bf16 v[34:37], v[154:157], v[202:205], v[34:37]
	v_mfma_f32_16x16x32_bf16 v[38:41], v[162:165], v[202:205], v[38:41]
	v_mfma_f32_16x16x32_bf16 v[26:29], v[154:157], v[210:213], v[26:29]
	v_mfma_f32_16x16x32_bf16 v[30:33], v[162:165], v[210:213], v[30:33]
	v_mfma_f32_16x16x32_bf16 v[58:61], v[158:161], v[190:193], v[58:61]
	v_mfma_f32_16x16x32_bf16 v[70:73], v[166:169], v[190:193], v[70:73]
	v_mfma_f32_16x16x32_bf16 v[42:45], v[158:161], v[198:201], v[42:45]
	v_mfma_f32_16x16x32_bf16 v[50:53], v[166:169], v[198:201], v[50:53]
	v_mfma_f32_16x16x32_bf16 v[34:37], v[158:161], v[206:209], v[34:37]
	v_mfma_f32_16x16x32_bf16 v[38:41], v[166:169], v[206:209], v[38:41]
	v_mfma_f32_16x16x32_bf16 v[26:29], v[158:161], v[214:217], v[26:29]
	v_mfma_f32_16x16x32_bf16 v[30:33], v[166:169], v[214:217], v[30:33]
	s_setprio 0
	s_setprio 1
	v_mfma_f32_16x16x32_bf16 v[106:109], v[170:173], v[186:189], v[106:109]
	v_mfma_f32_16x16x32_bf16 v[110:113], v[178:181], v[186:189], v[110:113]
	v_mfma_f32_16x16x32_bf16 v[98:101], v[170:173], v[194:197], v[98:101]
	v_mfma_f32_16x16x32_bf16 v[102:105], v[178:181], v[194:197], v[102:105]
	v_mfma_f32_16x16x32_bf16 v[90:93], v[170:173], v[202:205], v[90:93]
	v_mfma_f32_16x16x32_bf16 v[94:97], v[178:181], v[202:205], v[94:97]
	v_mfma_f32_16x16x32_bf16 v[82:85], v[170:173], v[210:213], v[82:85]
	v_mfma_f32_16x16x32_bf16 v[86:89], v[178:181], v[210:213], v[86:89]
	v_mfma_f32_16x16x32_bf16 v[106:109], v[174:177], v[190:193], v[106:109]
	v_mfma_f32_16x16x32_bf16 v[110:113], v[182:185], v[190:193], v[110:113]
	v_mfma_f32_16x16x32_bf16 v[98:101], v[174:177], v[198:201], v[98:101]
	v_mfma_f32_16x16x32_bf16 v[102:105], v[182:185], v[198:201], v[102:105]
	v_mfma_f32_16x16x32_bf16 v[90:93], v[174:177], v[206:209], v[90:93]
	v_mfma_f32_16x16x32_bf16 v[94:97], v[182:185], v[206:209], v[94:97]
	v_mfma_f32_16x16x32_bf16 v[82:85], v[174:177], v[214:217], v[82:85]
	v_mfma_f32_16x16x32_bf16 v[86:89], v[182:185], v[214:217], v[86:89]
	s_setprio 0
	s_barrier
	s_mov_b32 m0, s49
	s_add_u32 s58, s28, 0xb0000
	ds_read_b128 v[186:189], v150 offset:16384
	ds_read_b128 v[190:193], v150 offset:17408
	ds_read_b128 v[194:197], v150 offset:18432
	ds_read_b128 v[198:201], v150 offset:19456
	ds_read_b128 v[202:205], v150 offset:20480
	ds_read_b128 v[206:209], v150 offset:21504
	ds_read_b128 v[210:213], v150 offset:22528
	ds_read_b128 v[214:217], v150 offset:23552
	global_load_lds_dwordx4 v116, s[28:29]
	s_mov_b32 m0, s50
	s_addc_u32 s59, s29, 0
	global_load_lds_dwordx4 v124, s[28:29]
	s_mov_b32 m0, s51
	s_nop 0
	global_load_lds_dwordx4 v116, s[58:59]
	s_mov_b32 m0, s52
	s_nop 0
	global_load_lds_dwordx4 v124, s[58:59]
	s_mov_b32 m0, s25
	s_nop 0
	global_load_lds_dwordx4 v114, s[30:31]
	s_mov_b32 m0, s35
	s_nop 0
	global_load_lds_dwordx4 v122, s[30:31]
	s_waitcnt vmcnt(8)
	s_waitcnt lgkmcnt(0)
	s_barrier
	s_setprio 1
	s_waitcnt lgkmcnt(0)
	v_mfma_f32_16x16x32_bf16 v[18:21], v[154:157], v[186:189], v[18:21]
	v_mfma_f32_16x16x32_bf16 v[22:25], v[162:165], v[186:189], v[22:25]
	v_mfma_f32_16x16x32_bf16 v[10:13], v[154:157], v[194:197], v[10:13]
	v_mfma_f32_16x16x32_bf16 v[14:17], v[162:165], v[194:197], v[14:17]
	v_mfma_f32_16x16x32_bf16 v[2:5], v[154:157], v[202:205], v[2:5]
	v_mfma_f32_16x16x32_bf16 v[6:9], v[162:165], v[202:205], v[6:9]
	v_mfma_f32_16x16x32_bf16 v[62:65], v[154:157], v[210:213], v[62:65]
	v_mfma_f32_16x16x32_bf16 v[74:77], v[162:165], v[210:213], v[74:77]
	v_mfma_f32_16x16x32_bf16 v[18:21], v[158:161], v[190:193], v[18:21]
	v_mfma_f32_16x16x32_bf16 v[22:25], v[166:169], v[190:193], v[22:25]
	v_mfma_f32_16x16x32_bf16 v[10:13], v[158:161], v[198:201], v[10:13]
	v_mfma_f32_16x16x32_bf16 v[14:17], v[166:169], v[198:201], v[14:17]
	v_mfma_f32_16x16x32_bf16 v[2:5], v[158:161], v[206:209], v[2:5]
	v_mfma_f32_16x16x32_bf16 v[6:9], v[166:169], v[206:209], v[6:9]
	v_mfma_f32_16x16x32_bf16 v[62:65], v[158:161], v[214:217], v[62:65]
	v_mfma_f32_16x16x32_bf16 v[74:77], v[166:169], v[214:217], v[74:77]
	s_setprio 0
	s_setprio 1
	v_mfma_f32_16x16x32_bf16 v[66:69], v[170:173], v[186:189], v[66:69]
	v_mfma_f32_16x16x32_bf16 v[78:81], v[178:181], v[186:189], v[78:81]
	v_mfma_f32_16x16x32_bf16 v[46:49], v[170:173], v[194:197], v[46:49]
	v_mfma_f32_16x16x32_bf16 v[54:57], v[178:181], v[194:197], v[54:57]
	v_mfma_f32_16x16x32_bf16 v[118:121], v[170:173], v[202:205], v[118:121]
	v_mfma_f32_16x16x32_bf16 v[126:129], v[178:181], v[202:205], v[126:129]
	v_mfma_f32_16x16x32_bf16 v[130:133], v[170:173], v[210:213], v[130:133]
	v_mfma_f32_16x16x32_bf16 v[134:137], v[178:181], v[210:213], v[134:137]
	v_mfma_f32_16x16x32_bf16 v[66:69], v[174:177], v[190:193], v[66:69]
	v_mfma_f32_16x16x32_bf16 v[78:81], v[182:185], v[190:193], v[78:81]
	v_mfma_f32_16x16x32_bf16 v[46:49], v[174:177], v[198:201], v[46:49]
	v_mfma_f32_16x16x32_bf16 v[54:57], v[182:185], v[198:201], v[54:57]
	v_mfma_f32_16x16x32_bf16 v[118:121], v[174:177], v[206:209], v[118:121]
	v_mfma_f32_16x16x32_bf16 v[126:129], v[182:185], v[206:209], v[126:129]
	v_mfma_f32_16x16x32_bf16 v[130:133], v[174:177], v[214:217], v[130:133]
	v_mfma_f32_16x16x32_bf16 v[134:137], v[182:185], v[214:217], v[134:137]
	s_setprio 0
	s_barrier
	ds_read_b128 v[154:157], v151
	ds_read_b128 v[158:161], v151 offset:1024
	ds_read_b128 v[162:165], v151 offset:2048
	ds_read_b128 v[166:169], v151 offset:3072
	ds_read_b128 v[170:173], v152
	ds_read_b128 v[174:177], v152 offset:1024
	ds_read_b128 v[178:181], v152 offset:2048
	ds_read_b128 v[182:185], v152 offset:3072
	s_add_u32 s98, s30, 0xb0000
	s_addc_u32 s99, s31, 0
	s_mov_b32 m0, s42
	ds_read_b128 v[186:189], v150 offset:32768
	ds_read_b128 v[190:193], v150 offset:33792
	ds_read_b128 v[194:197], v150 offset:34816
	ds_read_b128 v[198:201], v150 offset:35840
	ds_read_b128 v[202:205], v150 offset:36864
	ds_read_b128 v[206:209], v150 offset:37888
	ds_read_b128 v[210:213], v150 offset:38912
	ds_read_b128 v[214:217], v150 offset:39936
	global_load_lds_dwordx4 v114, s[98:99]
	s_mov_b32 m0, s43
	s_nop 0
	global_load_lds_dwordx4 v122, s[98:99]
	s_waitcnt vmcnt(8)
	s_waitcnt lgkmcnt(0)
	s_barrier
	s_setprio 1
	s_waitcnt lgkmcnt(0)
	v_mfma_f32_16x16x32_bf16 v[58:61], v[154:157], v[186:189], v[58:61]
	v_mfma_f32_16x16x32_bf16 v[70:73], v[162:165], v[186:189], v[70:73]
	v_mfma_f32_16x16x32_bf16 v[42:45], v[154:157], v[194:197], v[42:45]
	v_mfma_f32_16x16x32_bf16 v[50:53], v[162:165], v[194:197], v[50:53]
	v_mfma_f32_16x16x32_bf16 v[34:37], v[154:157], v[202:205], v[34:37]
	v_mfma_f32_16x16x32_bf16 v[38:41], v[162:165], v[202:205], v[38:41]
	v_mfma_f32_16x16x32_bf16 v[26:29], v[154:157], v[210:213], v[26:29]
	v_mfma_f32_16x16x32_bf16 v[30:33], v[162:165], v[210:213], v[30:33]
	v_mfma_f32_16x16x32_bf16 v[58:61], v[158:161], v[190:193], v[58:61]
	v_mfma_f32_16x16x32_bf16 v[70:73], v[166:169], v[190:193], v[70:73]
	v_mfma_f32_16x16x32_bf16 v[42:45], v[158:161], v[198:201], v[42:45]
	v_mfma_f32_16x16x32_bf16 v[50:53], v[166:169], v[198:201], v[50:53]
	v_mfma_f32_16x16x32_bf16 v[34:37], v[158:161], v[206:209], v[34:37]
	v_mfma_f32_16x16x32_bf16 v[38:41], v[166:169], v[206:209], v[38:41]
	v_mfma_f32_16x16x32_bf16 v[26:29], v[158:161], v[214:217], v[26:29]
	v_mfma_f32_16x16x32_bf16 v[30:33], v[166:169], v[214:217], v[30:33]
	s_setprio 0
	s_setprio 1
	v_mfma_f32_16x16x32_bf16 v[106:109], v[170:173], v[186:189], v[106:109]
	v_mfma_f32_16x16x32_bf16 v[110:113], v[178:181], v[186:189], v[110:113]
	v_mfma_f32_16x16x32_bf16 v[98:101], v[170:173], v[194:197], v[98:101]
	v_mfma_f32_16x16x32_bf16 v[102:105], v[178:181], v[194:197], v[102:105]
	v_mfma_f32_16x16x32_bf16 v[90:93], v[170:173], v[202:205], v[90:93]
	v_mfma_f32_16x16x32_bf16 v[94:97], v[178:181], v[202:205], v[94:97]
	v_mfma_f32_16x16x32_bf16 v[82:85], v[170:173], v[210:213], v[82:85]
	v_mfma_f32_16x16x32_bf16 v[86:89], v[178:181], v[210:213], v[86:89]
	v_mfma_f32_16x16x32_bf16 v[106:109], v[174:177], v[190:193], v[106:109]
	v_mfma_f32_16x16x32_bf16 v[110:113], v[182:185], v[190:193], v[110:113]
	v_mfma_f32_16x16x32_bf16 v[98:101], v[174:177], v[198:201], v[98:101]
	v_mfma_f32_16x16x32_bf16 v[102:105], v[182:185], v[198:201], v[102:105]
	v_mfma_f32_16x16x32_bf16 v[90:93], v[174:177], v[206:209], v[90:93]
	v_mfma_f32_16x16x32_bf16 v[94:97], v[182:185], v[206:209], v[94:97]
	v_mfma_f32_16x16x32_bf16 v[82:85], v[174:177], v[214:217], v[82:85]
	v_mfma_f32_16x16x32_bf16 v[86:89], v[182:185], v[214:217], v[86:89]
	s_setprio 0
	s_barrier
	s_add_i32 m0, s53, 0xffffff80
	ds_read_b128 v[186:189], v150 offset:49152
	ds_read_b128 v[190:193], v150 offset:50176
	ds_read_b128 v[194:197], v150 offset:51200
	ds_read_b128 v[198:201], v150 offset:52224
	ds_read_b128 v[202:205], v150 offset:53248
	ds_read_b128 v[206:209], v150 offset:54272
	ds_read_b128 v[210:213], v150 offset:55296
	ds_read_b128 v[214:217], v150 offset:56320
	global_load_lds_dwordx4 v116, s[28:29] offset:128
	s_add_i32 m0, s54, 0xffffff80
	s_nop 0
	global_load_lds_dwordx4 v124, s[28:29] offset:128
	s_add_u32 s28, s28, 0xb0080
	s_addc_u32 s29, s29, 0
	s_mov_b32 m0, s55
	s_nop 0
	global_load_lds_dwordx4 v116, s[28:29]
	s_mov_b32 m0, s56
	s_nop 0
	global_load_lds_dwordx4 v124, s[28:29]
	s_add_i32 m0, s44, 0xffffff80
	s_nop 0
	global_load_lds_dwordx4 v114, s[30:31] offset:128
	s_add_i32 m0, s45, 0xffffff80
	s_nop 0
	global_load_lds_dwordx4 v122, s[30:31] offset:128
	s_waitcnt vmcnt(8)
	s_waitcnt lgkmcnt(0)
	s_barrier
	s_setprio 1
	s_waitcnt lgkmcnt(0)
	v_mfma_f32_16x16x32_bf16 v[18:21], v[154:157], v[186:189], v[18:21]
	v_mfma_f32_16x16x32_bf16 v[22:25], v[162:165], v[186:189], v[22:25]
	v_mfma_f32_16x16x32_bf16 v[10:13], v[154:157], v[194:197], v[10:13]
	v_mfma_f32_16x16x32_bf16 v[14:17], v[162:165], v[194:197], v[14:17]
	v_mfma_f32_16x16x32_bf16 v[2:5], v[154:157], v[202:205], v[2:5]
	v_mfma_f32_16x16x32_bf16 v[6:9], v[162:165], v[202:205], v[6:9]
	v_mfma_f32_16x16x32_bf16 v[62:65], v[154:157], v[210:213], v[62:65]
	v_mfma_f32_16x16x32_bf16 v[74:77], v[162:165], v[210:213], v[74:77]
	v_mfma_f32_16x16x32_bf16 v[18:21], v[158:161], v[190:193], v[18:21]
	v_mfma_f32_16x16x32_bf16 v[22:25], v[166:169], v[190:193], v[22:25]
	v_mfma_f32_16x16x32_bf16 v[10:13], v[158:161], v[198:201], v[10:13]
	v_mfma_f32_16x16x32_bf16 v[14:17], v[166:169], v[198:201], v[14:17]
	v_mfma_f32_16x16x32_bf16 v[2:5], v[158:161], v[206:209], v[2:5]
	v_mfma_f32_16x16x32_bf16 v[6:9], v[166:169], v[206:209], v[6:9]
	v_mfma_f32_16x16x32_bf16 v[62:65], v[158:161], v[214:217], v[62:65]
	v_mfma_f32_16x16x32_bf16 v[74:77], v[166:169], v[214:217], v[74:77]
	s_setprio 0
	s_setprio 1
	v_mfma_f32_16x16x32_bf16 v[66:69], v[170:173], v[186:189], v[66:69]
	v_mfma_f32_16x16x32_bf16 v[78:81], v[178:181], v[186:189], v[78:81]
	v_mfma_f32_16x16x32_bf16 v[46:49], v[170:173], v[194:197], v[46:49]
	v_mfma_f32_16x16x32_bf16 v[54:57], v[178:181], v[194:197], v[54:57]
	v_mfma_f32_16x16x32_bf16 v[118:121], v[170:173], v[202:205], v[118:121]
	v_mfma_f32_16x16x32_bf16 v[126:129], v[178:181], v[202:205], v[126:129]
	v_mfma_f32_16x16x32_bf16 v[130:133], v[170:173], v[210:213], v[130:133]
	v_mfma_f32_16x16x32_bf16 v[134:137], v[178:181], v[210:213], v[134:137]
	v_mfma_f32_16x16x32_bf16 v[66:69], v[174:177], v[190:193], v[66:69]
	v_mfma_f32_16x16x32_bf16 v[78:81], v[182:185], v[190:193], v[78:81]
	v_mfma_f32_16x16x32_bf16 v[46:49], v[174:177], v[198:201], v[46:49]
	v_mfma_f32_16x16x32_bf16 v[54:57], v[182:185], v[198:201], v[54:57]
	v_mfma_f32_16x16x32_bf16 v[118:121], v[174:177], v[206:209], v[118:121]
	v_mfma_f32_16x16x32_bf16 v[126:129], v[182:185], v[206:209], v[126:129]
	v_mfma_f32_16x16x32_bf16 v[130:133], v[174:177], v[214:217], v[130:133]
	v_mfma_f32_16x16x32_bf16 v[134:137], v[182:185], v[214:217], v[134:137]
	s_setprio 0
	s_barrier
	s_add_i32 s46, s46, 2
	s_add_u32 s20, s20, 0x100
	s_addc_u32 s21, s21, 0
	s_cmp_lt_u32 s46, 34
	s_cbranch_scc1 .LBB0_2133
	s_waitcnt vmcnt(0)
	s_cmpk_gt_u32 s22, 0xff
	s_cbranch_scc1 .LBB0_2136
	s_barrier

.LBB0_2205:
	ds_read_b128 v[158:161], v152
	ds_read_b128 v[162:165], v152 offset:1024
	ds_read_b128 v[166:169], v152 offset:2048
	ds_read_b128 v[170:173], v152 offset:3072
	ds_read_b128 v[174:177], v153
	ds_read_b128 v[178:181], v153 offset:1024
	ds_read_b128 v[182:185], v153 offset:2048
	ds_read_b128 v[186:189], v153 offset:3072
	s_add_u32 s20, s26, s45
	s_addc_u32 s21, s27, s46
	s_add_u32 s60, s26, s47
	s_addc_u32 s61, s27, s48
	s_cmp_eq_u32 s49, 4
	s_cselect_b32 s25, s3, s21
	s_cselect_b32 s24, s2, s20
	s_cselect_b32 s21, s1, s61
	s_cselect_b32 s20, s0, s60
	s_mov_b32 m0, s50
	v_lshl_add_u64 v[222:223], s[26:27], 0, v[146:147]
	ds_read_b128 v[190:193], v154
	ds_read_b128 v[194:197], v154 offset:1024
	ds_read_b128 v[198:201], v154 offset:2048
	ds_read_b128 v[202:205], v154 offset:3072
	ds_read_b128 v[206:209], v154 offset:4096
	ds_read_b128 v[210:213], v154 offset:5120
	ds_read_b128 v[214:217], v154 offset:6144
	ds_read_b128 v[218:221], v154 offset:7168
	global_load_lds_dwordx4 v[222:223], off
	v_lshl_add_u64 v[222:223], s[26:27], 0, v[148:149]
	s_mov_b32 m0, s51
	s_nop 0
	global_load_lds_dwordx4 v[222:223], off
	s_waitcnt vmcnt(8)
	s_waitcnt lgkmcnt(0)
	s_barrier
	s_setprio 1
	s_waitcnt lgkmcnt(0)
	v_mfma_f32_16x16x32_bf16 v[126:129], v[158:161], v[190:193], v[126:129]
	v_mfma_f32_16x16x32_bf16 v[122:125], v[166:169], v[190:193], v[122:125]
	v_mfma_f32_16x16x32_bf16 v[118:121], v[158:161], v[198:201], v[118:121]
	v_mfma_f32_16x16x32_bf16 v[114:117], v[166:169], v[198:201], v[114:117]
	v_mfma_f32_16x16x32_bf16 v[110:113], v[158:161], v[206:209], v[110:113]
	v_mfma_f32_16x16x32_bf16 v[106:109], v[166:169], v[206:209], v[106:109]
	v_mfma_f32_16x16x32_bf16 v[102:105], v[158:161], v[214:217], v[102:105]
	v_mfma_f32_16x16x32_bf16 v[98:101], v[166:169], v[214:217], v[98:101]
	v_mfma_f32_16x16x32_bf16 v[126:129], v[162:165], v[194:197], v[126:129]
	v_mfma_f32_16x16x32_bf16 v[122:125], v[170:173], v[194:197], v[122:125]
	v_mfma_f32_16x16x32_bf16 v[118:121], v[162:165], v[202:205], v[118:121]
	v_mfma_f32_16x16x32_bf16 v[114:117], v[170:173], v[202:205], v[114:117]
	v_mfma_f32_16x16x32_bf16 v[110:113], v[162:165], v[210:213], v[110:113]
	v_mfma_f32_16x16x32_bf16 v[106:109], v[170:173], v[210:213], v[106:109]
	v_mfma_f32_16x16x32_bf16 v[102:105], v[162:165], v[218:221], v[102:105]
	v_mfma_f32_16x16x32_bf16 v[98:101], v[170:173], v[218:221], v[98:101]
	s_setprio 0
	s_setprio 1
	v_mfma_f32_16x16x32_bf16 v[94:97], v[174:177], v[190:193], v[94:97]
	v_mfma_f32_16x16x32_bf16 v[90:93], v[182:185], v[190:193], v[90:93]
	v_mfma_f32_16x16x32_bf16 v[86:89], v[174:177], v[198:201], v[86:89]
	v_mfma_f32_16x16x32_bf16 v[82:85], v[182:185], v[198:201], v[82:85]
	v_mfma_f32_16x16x32_bf16 v[78:81], v[174:177], v[206:209], v[78:81]
	v_mfma_f32_16x16x32_bf16 v[74:77], v[182:185], v[206:209], v[74:77]
	v_mfma_f32_16x16x32_bf16 v[70:73], v[174:177], v[214:217], v[70:73]
	v_mfma_f32_16x16x32_bf16 v[66:69], v[182:185], v[214:217], v[66:69]
	v_mfma_f32_16x16x32_bf16 v[94:97], v[178:181], v[194:197], v[94:97]
	v_mfma_f32_16x16x32_bf16 v[90:93], v[186:189], v[194:197], v[90:93]
	v_mfma_f32_16x16x32_bf16 v[86:89], v[178:181], v[202:205], v[86:89]
	v_mfma_f32_16x16x32_bf16 v[82:85], v[186:189], v[202:205], v[82:85]
	v_mfma_f32_16x16x32_bf16 v[78:81], v[178:181], v[210:213], v[78:81]
	v_mfma_f32_16x16x32_bf16 v[74:77], v[186:189], v[210:213], v[74:77]
	v_mfma_f32_16x16x32_bf16 v[70:73], v[178:181], v[218:221], v[70:73]
	v_mfma_f32_16x16x32_bf16 v[66:69], v[186:189], v[218:221], v[66:69]
	s_setprio 0
	s_barrier
	s_mov_b32 m0, s52
	s_add_u32 s60, s20, 0xb0000
	ds_read_b128 v[190:193], v154 offset:16384
	ds_read_b128 v[194:197], v154 offset:17408
	ds_read_b128 v[198:201], v154 offset:18432
	ds_read_b128 v[202:205], v154 offset:19456
	ds_read_b128 v[206:209], v154 offset:20480
	ds_read_b128 v[210:213], v154 offset:21504
	ds_read_b128 v[214:217], v154 offset:22528
	ds_read_b128 v[218:221], v154 offset:23552
	global_load_lds_dwordx4 v132, s[20:21]
	s_mov_b32 m0, s53
	s_addc_u32 s61, s21, 0
	global_load_lds_dwordx4 v136, s[20:21]
	s_mov_b32 m0, s54
	s_nop 0
	global_load_lds_dwordx4 v132, s[60:61]
	s_mov_b32 m0, s55
	s_nop 0
	global_load_lds_dwordx4 v136, s[60:61]
	s_mov_b32 m0, s31
	s_nop 0
	global_load_lds_dwordx4 v130, s[24:25]
	s_mov_b32 m0, s34
	s_nop 0
	global_load_lds_dwordx4 v134, s[24:25]
	s_waitcnt vmcnt(8)
	s_waitcnt lgkmcnt(0)
	s_barrier
	s_setprio 1
	s_waitcnt lgkmcnt(0)
	v_mfma_f32_16x16x32_bf16 v[62:65], v[158:161], v[190:193], v[62:65]
	v_mfma_f32_16x16x32_bf16 v[58:61], v[166:169], v[190:193], v[58:61]
	v_mfma_f32_16x16x32_bf16 v[54:57], v[158:161], v[198:201], v[54:57]
	v_mfma_f32_16x16x32_bf16 v[50:53], v[166:169], v[198:201], v[50:53]
	v_mfma_f32_16x16x32_bf16 v[46:49], v[158:161], v[206:209], v[46:49]
	v_mfma_f32_16x16x32_bf16 v[42:45], v[166:169], v[206:209], v[42:45]
	v_mfma_f32_16x16x32_bf16 v[38:41], v[158:161], v[214:217], v[38:41]
	v_mfma_f32_16x16x32_bf16 v[34:37], v[166:169], v[214:217], v[34:37]
	v_mfma_f32_16x16x32_bf16 v[62:65], v[162:165], v[194:197], v[62:65]
	v_mfma_f32_16x16x32_bf16 v[58:61], v[170:173], v[194:197], v[58:61]
	v_mfma_f32_16x16x32_bf16 v[54:57], v[162:165], v[202:205], v[54:57]
	v_mfma_f32_16x16x32_bf16 v[50:53], v[170:173], v[202:205], v[50:53]
	v_mfma_f32_16x16x32_bf16 v[46:49], v[162:165], v[210:213], v[46:49]
	v_mfma_f32_16x16x32_bf16 v[42:45], v[170:173], v[210:213], v[42:45]
	v_mfma_f32_16x16x32_bf16 v[38:41], v[162:165], v[218:221], v[38:41]
	v_mfma_f32_16x16x32_bf16 v[34:37], v[170:173], v[218:221], v[34:37]
	s_setprio 0
	s_setprio 1
	v_mfma_f32_16x16x32_bf16 v[30:33], v[174:177], v[190:193], v[30:33]
	v_mfma_f32_16x16x32_bf16 v[26:29], v[182:185], v[190:193], v[26:29]
	v_mfma_f32_16x16x32_bf16 v[22:25], v[174:177], v[198:201], v[22:25]
	v_mfma_f32_16x16x32_bf16 v[18:21], v[182:185], v[198:201], v[18:21]
	v_mfma_f32_16x16x32_bf16 v[14:17], v[174:177], v[206:209], v[14:17]
	v_mfma_f32_16x16x32_bf16 v[10:13], v[182:185], v[206:209], v[10:13]
	v_mfma_f32_16x16x32_bf16 v[6:9], v[174:177], v[214:217], v[6:9]
	v_mfma_f32_16x16x32_bf16 v[2:5], v[182:185], v[214:217], v[2:5]
	v_mfma_f32_16x16x32_bf16 v[30:33], v[178:181], v[194:197], v[30:33]
	v_mfma_f32_16x16x32_bf16 v[26:29], v[186:189], v[194:197], v[26:29]
	v_mfma_f32_16x16x32_bf16 v[22:25], v[178:181], v[202:205], v[22:25]
	v_mfma_f32_16x16x32_bf16 v[18:21], v[186:189], v[202:205], v[18:21]
	v_mfma_f32_16x16x32_bf16 v[14:17], v[178:181], v[210:213], v[14:17]
	v_mfma_f32_16x16x32_bf16 v[10:13], v[186:189], v[210:213], v[10:13]
	v_mfma_f32_16x16x32_bf16 v[6:9], v[178:181], v[218:221], v[6:9]
	v_mfma_f32_16x16x32_bf16 v[2:5], v[186:189], v[218:221], v[2:5]
	s_setprio 0
	s_barrier
	ds_read_b128 v[158:161], v155
	ds_read_b128 v[162:165], v155 offset:1024
	ds_read_b128 v[166:169], v155 offset:2048
	ds_read_b128 v[170:173], v155 offset:3072
	ds_read_b128 v[174:177], v156
	ds_read_b128 v[178:181], v156 offset:1024
	ds_read_b128 v[182:185], v156 offset:2048
	ds_read_b128 v[186:189], v156 offset:3072
	s_add_u32 s98, s24, 0xb0000
	s_addc_u32 s99, s25, 0
	s_mov_b32 m0, s35
	ds_read_b128 v[190:193], v154 offset:32768
	ds_read_b128 v[194:197], v154 offset:33792
	ds_read_b128 v[198:201], v154 offset:34816
	ds_read_b128 v[202:205], v154 offset:35840
	ds_read_b128 v[206:209], v154 offset:36864
	ds_read_b128 v[210:213], v154 offset:37888
	ds_read_b128 v[214:217], v154 offset:38912
	ds_read_b128 v[218:221], v154 offset:39936
	global_load_lds_dwordx4 v130, s[98:99]
	s_mov_b32 m0, s42
	s_nop 0
	global_load_lds_dwordx4 v134, s[98:99]
	s_waitcnt vmcnt(8)
	s_waitcnt lgkmcnt(0)
	s_barrier
	s_setprio 1
	s_waitcnt lgkmcnt(0)
	v_mfma_f32_16x16x32_bf16 v[126:129], v[158:161], v[190:193], v[126:129]
	v_mfma_f32_16x16x32_bf16 v[122:125], v[166:169], v[190:193], v[122:125]
	v_mfma_f32_16x16x32_bf16 v[118:121], v[158:161], v[198:201], v[118:121]
	v_mfma_f32_16x16x32_bf16 v[114:117], v[166:169], v[198:201], v[114:117]
	v_mfma_f32_16x16x32_bf16 v[110:113], v[158:161], v[206:209], v[110:113]
	v_mfma_f32_16x16x32_bf16 v[106:109], v[166:169], v[206:209], v[106:109]
	v_mfma_f32_16x16x32_bf16 v[102:105], v[158:161], v[214:217], v[102:105]
	v_mfma_f32_16x16x32_bf16 v[98:101], v[166:169], v[214:217], v[98:101]
	v_mfma_f32_16x16x32_bf16 v[126:129], v[162:165], v[194:197], v[126:129]
	v_mfma_f32_16x16x32_bf16 v[122:125], v[170:173], v[194:197], v[122:125]
	v_mfma_f32_16x16x32_bf16 v[118:121], v[162:165], v[202:205], v[118:121]
	v_mfma_f32_16x16x32_bf16 v[114:117], v[170:173], v[202:205], v[114:117]
	v_mfma_f32_16x16x32_bf16 v[110:113], v[162:165], v[210:213], v[110:113]
	v_mfma_f32_16x16x32_bf16 v[106:109], v[170:173], v[210:213], v[106:109]
	v_mfma_f32_16x16x32_bf16 v[102:105], v[162:165], v[218:221], v[102:105]
	v_mfma_f32_16x16x32_bf16 v[98:101], v[170:173], v[218:221], v[98:101]
	s_setprio 0
	s_setprio 1
	v_mfma_f32_16x16x32_bf16 v[94:97], v[174:177], v[190:193], v[94:97]
	v_mfma_f32_16x16x32_bf16 v[90:93], v[182:185], v[190:193], v[90:93]
	v_mfma_f32_16x16x32_bf16 v[86:89], v[174:177], v[198:201], v[86:89]
	v_mfma_f32_16x16x32_bf16 v[82:85], v[182:185], v[198:201], v[82:85]
	v_mfma_f32_16x16x32_bf16 v[78:81], v[174:177], v[206:209], v[78:81]
	v_mfma_f32_16x16x32_bf16 v[74:77], v[182:185], v[206:209], v[74:77]
	v_mfma_f32_16x16x32_bf16 v[70:73], v[174:177], v[214:217], v[70:73]
	v_mfma_f32_16x16x32_bf16 v[66:69], v[182:185], v[214:217], v[66:69]
	v_mfma_f32_16x16x32_bf16 v[94:97], v[178:181], v[194:197], v[94:97]
	v_mfma_f32_16x16x32_bf16 v[90:93], v[186:189], v[194:197], v[90:93]
	v_mfma_f32_16x16x32_bf16 v[86:89], v[178:181], v[202:205], v[86:89]
	v_mfma_f32_16x16x32_bf16 v[82:85], v[186:189], v[202:205], v[82:85]
	v_mfma_f32_16x16x32_bf16 v[78:81], v[178:181], v[210:213], v[78:81]
	v_mfma_f32_16x16x32_bf16 v[74:77], v[186:189], v[210:213], v[74:77]
	v_mfma_f32_16x16x32_bf16 v[70:73], v[178:181], v[218:221], v[70:73]
	v_mfma_f32_16x16x32_bf16 v[66:69], v[186:189], v[218:221], v[66:69]
	s_setprio 0
	s_barrier
	s_add_i32 m0, s56, 0xffffff80
	ds_read_b128 v[190:193], v154 offset:49152
	ds_read_b128 v[194:197], v154 offset:50176
	ds_read_b128 v[198:201], v154 offset:51200
	ds_read_b128 v[202:205], v154 offset:52224
	ds_read_b128 v[206:209], v154 offset:53248
	ds_read_b128 v[210:213], v154 offset:54272
	ds_read_b128 v[214:217], v154 offset:55296
	ds_read_b128 v[218:221], v154 offset:56320
	global_load_lds_dwordx4 v132, s[20:21] offset:128
	s_add_i32 m0, s57, 0xffffff80
	s_nop 0
	global_load_lds_dwordx4 v136, s[20:21] offset:128
	s_add_u32 s20, s20, 0xb0080
	s_addc_u32 s21, s21, 0
	s_mov_b32 m0, s58
	s_nop 0
	global_load_lds_dwordx4 v132, s[20:21]
	s_mov_b32 m0, s59
	s_nop 0
	global_load_lds_dwordx4 v136, s[20:21]
	s_add_i32 m0, s43, 0xffffff80
	s_nop 0
	global_load_lds_dwordx4 v130, s[24:25] offset:128
	s_add_i32 m0, s44, 0xffffff80
	s_nop 0
	global_load_lds_dwordx4 v134, s[24:25] offset:128
	s_waitcnt vmcnt(8)
	s_waitcnt lgkmcnt(0)
	s_barrier
	s_setprio 1
	s_waitcnt lgkmcnt(0)
	v_mfma_f32_16x16x32_bf16 v[62:65], v[158:161], v[190:193], v[62:65]
	v_mfma_f32_16x16x32_bf16 v[58:61], v[166:169], v[190:193], v[58:61]
	v_mfma_f32_16x16x32_bf16 v[54:57], v[158:161], v[198:201], v[54:57]
	v_mfma_f32_16x16x32_bf16 v[50:53], v[166:169], v[198:201], v[50:53]
	v_mfma_f32_16x16x32_bf16 v[46:49], v[158:161], v[206:209], v[46:49]
	v_mfma_f32_16x16x32_bf16 v[42:45], v[166:169], v[206:209], v[42:45]
	v_mfma_f32_16x16x32_bf16 v[38:41], v[158:161], v[214:217], v[38:41]
	v_mfma_f32_16x16x32_bf16 v[34:37], v[166:169], v[214:217], v[34:37]
	v_mfma_f32_16x16x32_bf16 v[62:65], v[162:165], v[194:197], v[62:65]
	v_mfma_f32_16x16x32_bf16 v[58:61], v[170:173], v[194:197], v[58:61]
	v_mfma_f32_16x16x32_bf16 v[54:57], v[162:165], v[202:205], v[54:57]
	v_mfma_f32_16x16x32_bf16 v[50:53], v[170:173], v[202:205], v[50:53]
	v_mfma_f32_16x16x32_bf16 v[46:49], v[162:165], v[210:213], v[46:49]
	v_mfma_f32_16x16x32_bf16 v[42:45], v[170:173], v[210:213], v[42:45]
	v_mfma_f32_16x16x32_bf16 v[38:41], v[162:165], v[218:221], v[38:41]
	v_mfma_f32_16x16x32_bf16 v[34:37], v[170:173], v[218:221], v[34:37]
	s_setprio 0
	s_setprio 1
	v_mfma_f32_16x16x32_bf16 v[30:33], v[174:177], v[190:193], v[30:33]
	v_mfma_f32_16x16x32_bf16 v[26:29], v[182:185], v[190:193], v[26:29]
	v_mfma_f32_16x16x32_bf16 v[22:25], v[174:177], v[198:201], v[22:25]
	v_mfma_f32_16x16x32_bf16 v[18:21], v[182:185], v[198:201], v[18:21]
	v_mfma_f32_16x16x32_bf16 v[14:17], v[174:177], v[206:209], v[14:17]
	v_mfma_f32_16x16x32_bf16 v[10:13], v[182:185], v[206:209], v[10:13]
	v_mfma_f32_16x16x32_bf16 v[6:9], v[174:177], v[214:217], v[6:9]
	v_mfma_f32_16x16x32_bf16 v[2:5], v[182:185], v[214:217], v[2:5]
	v_mfma_f32_16x16x32_bf16 v[30:33], v[178:181], v[194:197], v[30:33]
	v_mfma_f32_16x16x32_bf16 v[26:29], v[186:189], v[194:197], v[26:29]
	v_mfma_f32_16x16x32_bf16 v[22:25], v[178:181], v[202:205], v[22:25]
	v_mfma_f32_16x16x32_bf16 v[18:21], v[186:189], v[202:205], v[18:21]
	v_mfma_f32_16x16x32_bf16 v[14:17], v[178:181], v[210:213], v[14:17]
	v_mfma_f32_16x16x32_bf16 v[10:13], v[186:189], v[210:213], v[10:13]
	v_mfma_f32_16x16x32_bf16 v[6:9], v[178:181], v[218:221], v[6:9]
	v_mfma_f32_16x16x32_bf16 v[2:5], v[186:189], v[218:221], v[2:5]
	s_setprio 0
	s_barrier
	s_add_i32 s49, s49, 2
	s_add_u32 s45, s45, 0x100
	s_addc_u32 s46, s46, 0
	s_add_u32 s47, s47, 0x100
	s_addc_u32 s48, s48, 0
	v_lshl_add_u64 v[146:147], v[146:147], 0, s[18:19]
	s_cmp_lt_u32 s49, 6
	v_lshl_add_u64 v[148:149], v[148:149], 0, s[18:19]
	s_cbranch_scc1 .LBB0_2205
	s_waitcnt vmcnt(0)
	s_cmpk_gt_u32 s30, 0xff
	s_cbranch_scc1 .LBB0_2208
	s_barrier

.LBB0_2214:
	ds_read_b128 v[152:155], v144
	ds_read_b128 v[156:159], v144 offset:1024
	ds_read_b128 v[160:163], v144 offset:2048
	ds_read_b128 v[164:167], v144 offset:3072
	ds_read_b128 v[168:171], v145
	ds_read_b128 v[172:175], v145 offset:1024
	ds_read_b128 v[176:179], v145 offset:2048
	ds_read_b128 v[180:183], v145 offset:3072
	s_add_u32 s20, s26, s40
	s_addc_u32 s21, s27, s42
	s_add_u32 s56, s26, s43
	s_addc_u32 s57, s27, s44
	s_cmp_eq_u32 s45, 36
	s_cselect_b32 s25, s5, s21
	s_cselect_b32 s24, s4, s20
	s_cselect_b32 s21, s1, s57
	s_cselect_b32 s20, s0, s56
	s_mov_b32 m0, s46
	v_lshl_add_u64 v[216:217], s[26:27], 0, v[140:141]
	ds_read_b128 v[184:187], v146
	ds_read_b128 v[188:191], v146 offset:1024
	ds_read_b128 v[192:195], v146 offset:2048
	ds_read_b128 v[196:199], v146 offset:3072
	ds_read_b128 v[200:203], v146 offset:4096
	ds_read_b128 v[204:207], v146 offset:5120
	ds_read_b128 v[208:211], v146 offset:6144
	ds_read_b128 v[212:215], v146 offset:7168
	global_load_lds_dwordx4 v[216:217], off
	v_lshl_add_u64 v[216:217], s[26:27], 0, v[142:143]
	s_mov_b32 m0, s47
	s_nop 0
	global_load_lds_dwordx4 v[216:217], off
	s_waitcnt vmcnt(8)
	s_waitcnt lgkmcnt(0)
	s_barrier
	s_setprio 1
	s_waitcnt lgkmcnt(0)
	v_mfma_f32_16x16x32_bf16 v[126:129], v[152:155], v[184:187], v[126:129]
	v_mfma_f32_16x16x32_bf16 v[122:125], v[160:163], v[184:187], v[122:125]
	v_mfma_f32_16x16x32_bf16 v[118:121], v[152:155], v[192:195], v[118:121]
	v_mfma_f32_16x16x32_bf16 v[114:117], v[160:163], v[192:195], v[114:117]
	v_mfma_f32_16x16x32_bf16 v[94:97], v[152:155], v[200:203], v[94:97]
	v_mfma_f32_16x16x32_bf16 v[90:93], v[160:163], v[200:203], v[90:93]
	v_mfma_f32_16x16x32_bf16 v[78:81], v[152:155], v[208:211], v[78:81]
	v_mfma_f32_16x16x32_bf16 v[74:77], v[160:163], v[208:211], v[74:77]
	v_mfma_f32_16x16x32_bf16 v[126:129], v[156:159], v[188:191], v[126:129]
	v_mfma_f32_16x16x32_bf16 v[122:125], v[164:167], v[188:191], v[122:125]
	v_mfma_f32_16x16x32_bf16 v[118:121], v[156:159], v[196:199], v[118:121]
	v_mfma_f32_16x16x32_bf16 v[114:117], v[164:167], v[196:199], v[114:117]
	v_mfma_f32_16x16x32_bf16 v[94:97], v[156:159], v[204:207], v[94:97]
	v_mfma_f32_16x16x32_bf16 v[90:93], v[164:167], v[204:207], v[90:93]
	v_mfma_f32_16x16x32_bf16 v[78:81], v[156:159], v[212:215], v[78:81]
	v_mfma_f32_16x16x32_bf16 v[74:77], v[164:167], v[212:215], v[74:77]
	s_setprio 0
	s_setprio 1
	v_mfma_f32_16x16x32_bf16 v[110:113], v[168:171], v[184:187], v[110:113]
	v_mfma_f32_16x16x32_bf16 v[106:109], v[176:179], v[184:187], v[106:109]
	v_mfma_f32_16x16x32_bf16 v[102:105], v[168:171], v[192:195], v[102:105]
	v_mfma_f32_16x16x32_bf16 v[98:101], v[176:179], v[192:195], v[98:101]
	v_mfma_f32_16x16x32_bf16 v[86:89], v[168:171], v[200:203], v[86:89]
	v_mfma_f32_16x16x32_bf16 v[82:85], v[176:179], v[200:203], v[82:85]
	v_mfma_f32_16x16x32_bf16 v[70:73], v[168:171], v[208:211], v[70:73]
	v_mfma_f32_16x16x32_bf16 v[66:69], v[176:179], v[208:211], v[66:69]
	v_mfma_f32_16x16x32_bf16 v[110:113], v[172:175], v[188:191], v[110:113]
	v_mfma_f32_16x16x32_bf16 v[106:109], v[180:183], v[188:191], v[106:109]
	v_mfma_f32_16x16x32_bf16 v[102:105], v[172:175], v[196:199], v[102:105]
	v_mfma_f32_16x16x32_bf16 v[98:101], v[180:183], v[196:199], v[98:101]
	v_mfma_f32_16x16x32_bf16 v[86:89], v[172:175], v[204:207], v[86:89]
	v_mfma_f32_16x16x32_bf16 v[82:85], v[180:183], v[204:207], v[82:85]
	v_mfma_f32_16x16x32_bf16 v[70:73], v[172:175], v[212:215], v[70:73]
	v_mfma_f32_16x16x32_bf16 v[66:69], v[180:183], v[212:215], v[66:69]
	s_setprio 0
	s_barrier
	s_mov_b32 m0, s48
	s_add_u32 s56, s20, 0xb0000
	ds_read_b128 v[184:187], v146 offset:16384
	ds_read_b128 v[188:191], v146 offset:17408
	ds_read_b128 v[192:195], v146 offset:18432
	ds_read_b128 v[196:199], v146 offset:19456
	ds_read_b128 v[200:203], v146 offset:20480
	ds_read_b128 v[204:207], v146 offset:21504
	ds_read_b128 v[208:211], v146 offset:22528
	ds_read_b128 v[212:215], v146 offset:23552
	global_load_lds_dwordx4 v132, s[20:21]
	s_mov_b32 m0, s49
	s_addc_u32 s57, s21, 0
	global_load_lds_dwordx4 v136, s[20:21]
	s_mov_b32 m0, s50
	s_nop 0
	global_load_lds_dwordx4 v132, s[56:57]
	s_mov_b32 m0, s51
	s_nop 0
	global_load_lds_dwordx4 v136, s[56:57]
	s_mov_b32 m0, s31
	s_nop 0
	global_load_lds_dwordx4 v130, s[24:25]
	s_mov_b32 m0, s34
	s_nop 0
	global_load_lds_dwordx4 v134, s[24:25]
	s_waitcnt vmcnt(8)
	s_waitcnt lgkmcnt(0)
	s_barrier
	s_setprio 1
	s_waitcnt lgkmcnt(0)
	v_mfma_f32_16x16x32_bf16 v[62:65], v[152:155], v[184:187], v[62:65]
	v_mfma_f32_16x16x32_bf16 v[58:61], v[160:163], v[184:187], v[58:61]
	v_mfma_f32_16x16x32_bf16 v[46:49], v[152:155], v[192:195], v[46:49]
	v_mfma_f32_16x16x32_bf16 v[42:45], v[160:163], v[192:195], v[42:45]
	v_mfma_f32_16x16x32_bf16 v[30:33], v[152:155], v[200:203], v[30:33]
	v_mfma_f32_16x16x32_bf16 v[26:29], v[160:163], v[200:203], v[26:29]
	v_mfma_f32_16x16x32_bf16 v[14:17], v[152:155], v[208:211], v[14:17]
	v_mfma_f32_16x16x32_bf16 v[10:13], v[160:163], v[208:211], v[10:13]
	v_mfma_f32_16x16x32_bf16 v[62:65], v[156:159], v[188:191], v[62:65]
	v_mfma_f32_16x16x32_bf16 v[58:61], v[164:167], v[188:191], v[58:61]
	v_mfma_f32_16x16x32_bf16 v[46:49], v[156:159], v[196:199], v[46:49]
	v_mfma_f32_16x16x32_bf16 v[42:45], v[164:167], v[196:199], v[42:45]
	v_mfma_f32_16x16x32_bf16 v[30:33], v[156:159], v[204:207], v[30:33]
	v_mfma_f32_16x16x32_bf16 v[26:29], v[164:167], v[204:207], v[26:29]
	v_mfma_f32_16x16x32_bf16 v[14:17], v[156:159], v[212:215], v[14:17]
	v_mfma_f32_16x16x32_bf16 v[10:13], v[164:167], v[212:215], v[10:13]
	s_setprio 0
	s_setprio 1
	v_mfma_f32_16x16x32_bf16 v[54:57], v[168:171], v[184:187], v[54:57]
	v_mfma_f32_16x16x32_bf16 v[50:53], v[176:179], v[184:187], v[50:53]
	v_mfma_f32_16x16x32_bf16 v[38:41], v[168:171], v[192:195], v[38:41]
	v_mfma_f32_16x16x32_bf16 v[34:37], v[176:179], v[192:195], v[34:37]
	v_mfma_f32_16x16x32_bf16 v[22:25], v[168:171], v[200:203], v[22:25]
	v_mfma_f32_16x16x32_bf16 v[18:21], v[176:179], v[200:203], v[18:21]
	v_mfma_f32_16x16x32_bf16 v[6:9], v[168:171], v[208:211], v[6:9]
	v_mfma_f32_16x16x32_bf16 v[2:5], v[176:179], v[208:211], v[2:5]
	v_mfma_f32_16x16x32_bf16 v[54:57], v[172:175], v[188:191], v[54:57]
	v_mfma_f32_16x16x32_bf16 v[50:53], v[180:183], v[188:191], v[50:53]
	v_mfma_f32_16x16x32_bf16 v[38:41], v[172:175], v[196:199], v[38:41]
	v_mfma_f32_16x16x32_bf16 v[34:37], v[180:183], v[196:199], v[34:37]
	v_mfma_f32_16x16x32_bf16 v[22:25], v[172:175], v[204:207], v[22:25]
	v_mfma_f32_16x16x32_bf16 v[18:21], v[180:183], v[204:207], v[18:21]
	v_mfma_f32_16x16x32_bf16 v[6:9], v[172:175], v[212:215], v[6:9]
	v_mfma_f32_16x16x32_bf16 v[2:5], v[180:183], v[212:215], v[2:5]
	s_setprio 0
	s_barrier
	ds_read_b128 v[152:155], v147
	ds_read_b128 v[156:159], v147 offset:1024
	ds_read_b128 v[160:163], v147 offset:2048
	ds_read_b128 v[164:167], v147 offset:3072
	ds_read_b128 v[168:171], v148
	ds_read_b128 v[172:175], v148 offset:1024
	ds_read_b128 v[176:179], v148 offset:2048
	ds_read_b128 v[180:183], v148 offset:3072
	s_add_u32 s98, s24, 0xb0000
	s_addc_u32 s99, s25, 0
	s_mov_b32 m0, s35
	ds_read_b128 v[184:187], v146 offset:32768
	ds_read_b128 v[188:191], v146 offset:33792
	ds_read_b128 v[192:195], v146 offset:34816
	ds_read_b128 v[196:199], v146 offset:35840
	ds_read_b128 v[200:203], v146 offset:36864
	ds_read_b128 v[204:207], v146 offset:37888
	ds_read_b128 v[208:211], v146 offset:38912
	ds_read_b128 v[212:215], v146 offset:39936
	global_load_lds_dwordx4 v130, s[98:99]
	s_mov_b32 m0, s37
	s_nop 0
	global_load_lds_dwordx4 v134, s[98:99]
	s_waitcnt vmcnt(8)
	s_waitcnt lgkmcnt(0)
	s_barrier
	s_setprio 1
	s_waitcnt lgkmcnt(0)
	v_mfma_f32_16x16x32_bf16 v[126:129], v[152:155], v[184:187], v[126:129]
	v_mfma_f32_16x16x32_bf16 v[122:125], v[160:163], v[184:187], v[122:125]
	v_mfma_f32_16x16x32_bf16 v[118:121], v[152:155], v[192:195], v[118:121]
	v_mfma_f32_16x16x32_bf16 v[114:117], v[160:163], v[192:195], v[114:117]
	v_mfma_f32_16x16x32_bf16 v[94:97], v[152:155], v[200:203], v[94:97]
	v_mfma_f32_16x16x32_bf16 v[90:93], v[160:163], v[200:203], v[90:93]
	v_mfma_f32_16x16x32_bf16 v[78:81], v[152:155], v[208:211], v[78:81]
	v_mfma_f32_16x16x32_bf16 v[74:77], v[160:163], v[208:211], v[74:77]
	v_mfma_f32_16x16x32_bf16 v[126:129], v[156:159], v[188:191], v[126:129]
	v_mfma_f32_16x16x32_bf16 v[122:125], v[164:167], v[188:191], v[122:125]
	v_mfma_f32_16x16x32_bf16 v[118:121], v[156:159], v[196:199], v[118:121]
	v_mfma_f32_16x16x32_bf16 v[114:117], v[164:167], v[196:199], v[114:117]
	v_mfma_f32_16x16x32_bf16 v[94:97], v[156:159], v[204:207], v[94:97]
	v_mfma_f32_16x16x32_bf16 v[90:93], v[164:167], v[204:207], v[90:93]
	v_mfma_f32_16x16x32_bf16 v[78:81], v[156:159], v[212:215], v[78:81]
	v_mfma_f32_16x16x32_bf16 v[74:77], v[164:167], v[212:215], v[74:77]
	s_setprio 0
	s_setprio 1
	v_mfma_f32_16x16x32_bf16 v[110:113], v[168:171], v[184:187], v[110:113]
	v_mfma_f32_16x16x32_bf16 v[106:109], v[176:179], v[184:187], v[106:109]
	v_mfma_f32_16x16x32_bf16 v[102:105], v[168:171], v[192:195], v[102:105]
	v_mfma_f32_16x16x32_bf16 v[98:101], v[176:179], v[192:195], v[98:101]
	v_mfma_f32_16x16x32_bf16 v[86:89], v[168:171], v[200:203], v[86:89]
	v_mfma_f32_16x16x32_bf16 v[82:85], v[176:179], v[200:203], v[82:85]
	v_mfma_f32_16x16x32_bf16 v[70:73], v[168:171], v[208:211], v[70:73]
	v_mfma_f32_16x16x32_bf16 v[66:69], v[176:179], v[208:211], v[66:69]
	v_mfma_f32_16x16x32_bf16 v[110:113], v[172:175], v[188:191], v[110:113]
	v_mfma_f32_16x16x32_bf16 v[106:109], v[180:183], v[188:191], v[106:109]
	v_mfma_f32_16x16x32_bf16 v[102:105], v[172:175], v[196:199], v[102:105]
	v_mfma_f32_16x16x32_bf16 v[98:101], v[180:183], v[196:199], v[98:101]
	v_mfma_f32_16x16x32_bf16 v[86:89], v[172:175], v[204:207], v[86:89]
	v_mfma_f32_16x16x32_bf16 v[82:85], v[180:183], v[204:207], v[82:85]
	v_mfma_f32_16x16x32_bf16 v[70:73], v[172:175], v[212:215], v[70:73]
	v_mfma_f32_16x16x32_bf16 v[66:69], v[180:183], v[212:215], v[66:69]
	s_setprio 0
	s_barrier
	s_add_i32 m0, s52, 0xffffff80
	ds_read_b128 v[184:187], v146 offset:49152
	ds_read_b128 v[188:191], v146 offset:50176
	ds_read_b128 v[192:195], v146 offset:51200
	ds_read_b128 v[196:199], v146 offset:52224
	ds_read_b128 v[200:203], v146 offset:53248
	ds_read_b128 v[204:207], v146 offset:54272
	ds_read_b128 v[208:211], v146 offset:55296
	ds_read_b128 v[212:215], v146 offset:56320
	global_load_lds_dwordx4 v132, s[20:21] offset:128
	s_add_i32 m0, s53, 0xffffff80
	s_nop 0
	global_load_lds_dwordx4 v136, s[20:21] offset:128
	s_add_u32 s20, s20, 0xb0080
	s_addc_u32 s21, s21, 0
	s_mov_b32 m0, s54
	s_nop 0
	global_load_lds_dwordx4 v132, s[20:21]
	s_mov_b32 m0, s55
	s_nop 0
	global_load_lds_dwordx4 v136, s[20:21]
	s_add_i32 m0, s38, 0xffffff80
	s_nop 0
	global_load_lds_dwordx4 v130, s[24:25] offset:128
	s_add_i32 m0, s39, 0xffffff80
	s_nop 0
	global_load_lds_dwordx4 v134, s[24:25] offset:128
	s_waitcnt vmcnt(8)
	s_waitcnt lgkmcnt(0)
	s_barrier
	s_setprio 1
	s_waitcnt lgkmcnt(0)
	v_mfma_f32_16x16x32_bf16 v[62:65], v[152:155], v[184:187], v[62:65]
	v_mfma_f32_16x16x32_bf16 v[58:61], v[160:163], v[184:187], v[58:61]
	v_mfma_f32_16x16x32_bf16 v[46:49], v[152:155], v[192:195], v[46:49]
	v_mfma_f32_16x16x32_bf16 v[42:45], v[160:163], v[192:195], v[42:45]
	v_mfma_f32_16x16x32_bf16 v[30:33], v[152:155], v[200:203], v[30:33]
	v_mfma_f32_16x16x32_bf16 v[26:29], v[160:163], v[200:203], v[26:29]
	v_mfma_f32_16x16x32_bf16 v[14:17], v[152:155], v[208:211], v[14:17]
	v_mfma_f32_16x16x32_bf16 v[10:13], v[160:163], v[208:211], v[10:13]
	v_mfma_f32_16x16x32_bf16 v[62:65], v[156:159], v[188:191], v[62:65]
	v_mfma_f32_16x16x32_bf16 v[58:61], v[164:167], v[188:191], v[58:61]
	v_mfma_f32_16x16x32_bf16 v[46:49], v[156:159], v[196:199], v[46:49]
	v_mfma_f32_16x16x32_bf16 v[42:45], v[164:167], v[196:199], v[42:45]
	v_mfma_f32_16x16x32_bf16 v[30:33], v[156:159], v[204:207], v[30:33]
	v_mfma_f32_16x16x32_bf16 v[26:29], v[164:167], v[204:207], v[26:29]
	v_mfma_f32_16x16x32_bf16 v[14:17], v[156:159], v[212:215], v[14:17]
	v_mfma_f32_16x16x32_bf16 v[10:13], v[164:167], v[212:215], v[10:13]
	s_setprio 0
	s_setprio 1
	v_mfma_f32_16x16x32_bf16 v[54:57], v[168:171], v[184:187], v[54:57]
	v_mfma_f32_16x16x32_bf16 v[50:53], v[176:179], v[184:187], v[50:53]
	v_mfma_f32_16x16x32_bf16 v[38:41], v[168:171], v[192:195], v[38:41]
	v_mfma_f32_16x16x32_bf16 v[34:37], v[176:179], v[192:195], v[34:37]
	v_mfma_f32_16x16x32_bf16 v[22:25], v[168:171], v[200:203], v[22:25]
	v_mfma_f32_16x16x32_bf16 v[18:21], v[176:179], v[200:203], v[18:21]
	v_mfma_f32_16x16x32_bf16 v[6:9], v[168:171], v[208:211], v[6:9]
	v_mfma_f32_16x16x32_bf16 v[2:5], v[176:179], v[208:211], v[2:5]
	v_mfma_f32_16x16x32_bf16 v[54:57], v[172:175], v[188:191], v[54:57]
	v_mfma_f32_16x16x32_bf16 v[50:53], v[180:183], v[188:191], v[50:53]
	v_mfma_f32_16x16x32_bf16 v[38:41], v[172:175], v[196:199], v[38:41]
	v_mfma_f32_16x16x32_bf16 v[34:37], v[180:183], v[196:199], v[34:37]
	v_mfma_f32_16x16x32_bf16 v[22:25], v[172:175], v[204:207], v[22:25]
	v_mfma_f32_16x16x32_bf16 v[18:21], v[180:183], v[204:207], v[18:21]
	v_mfma_f32_16x16x32_bf16 v[6:9], v[172:175], v[212:215], v[6:9]
	v_mfma_f32_16x16x32_bf16 v[2:5], v[180:183], v[212:215], v[2:5]
	s_setprio 0
	s_barrier
	s_add_i32 s45, s45, 2
	s_add_u32 s40, s40, 0x100
	s_addc_u32 s42, s42, 0
	s_add_u32 s43, s43, 0x100
	s_addc_u32 s44, s44, 0
	v_lshl_add_u64 v[140:141], v[140:141], 0, s[18:19]
	s_cmp_lt_u32 s45, 38
	v_lshl_add_u64 v[142:143], v[142:143], 0, s[18:19]
	s_cbranch_scc1 .LBB0_2214
	s_waitcnt vmcnt(0)
	s_cmpk_gt_u32 s30, 0xff
	s_cbranch_scc1 .LBB0_2217
	s_barrier
